# attention: one barrier per tile (separate loops per wave group), S-phase trims (K rows staged bit2<->bit3 permuted: no lane swaps; SALU moved into M phase; 4 partial sums), tail alignment kept
# speedup vs baseline: 1.0117x; 1.0117x over previous
; __device__ __forceinline__ void unpack8(const u32x4 w, float* f) { f[0] = bf_lo(w.x); f[1] = bf_hi(w.x); f[2] = bf_lo(w.y); f[3] = bf_hi(w.y); f[4] = bf_lo(w.z); f[5] = bf_hi(w.z); f[6] = bf_lo(w.w); f[7] = bf_hi(w.w); }
; __device__ __forceinline__ void attn_unit(const bf16_t* __restrict__ Qb, const bf16_t* __restrict__ KV, const bf16_t* __restrict__ KP, bf16_t* __restrict__ Ob, ...
;   int tid_ = threadIdx.x; asm volatile("" : "+v"(tid_));
;   const int tid = tid_, wid = tid >> 6, lane = tid & 63, r32 = lane & 31, hi = lane >> 5;
;   char* V_lds = lds + OFF_V; char* KN_lds = lds + OFF_KN; char* KP_lds = lds + OFF_KP;
;   float* ws = (float*)(lds + OFF_WS) + wid * 64; float* li_l = ws; float* al_l = ws + 32;
;   float m_reg = -1e30f, l_reg = 0; f32x16 o[4] = {}; bf16x8 qr[12];
;   const bf16_t* Qw = Qb + (size_t)(qrow0 + wid * QBLK + r32) * LDQ + h * QKD + hi * 8;
; #pragma unroll
;   for (int d0 = 0; d0 < 12; ++d0) qr[d0] = ld8(Qw + d0 * 16);
;   {
;     float qf[12][8]; float ss = 0.f;
; #pragma unroll
;     for (int d0 = 0; d0 < 12; ++d0) { const u32x4 w = *reinterpret_cast<const u32x4*>(&qr[d0]); unpack8(w, qf[d0]);
; #pragma unroll
;       for (int jj = 0; jj < 8; ++jj) ss += qf[d0][jj] * qf[d0][jj]; }
;     { auto rr = __builtin_amdgcn_permlane32_swap(__float_as_uint(ss), __float_as_uint(ss), false, false); ss = __uint_as_float(rr[0]) + __uint_as_float(rr[1]); }
;     const float rinv = 1.0f / sqrtf(ss * (1.f / QKD) + EPS);
; #pragma unroll
;     for (int d0 = 0; d0 < 12; ++d0) { const f32x4 g0 = *(const f32x4*)(qn + d0 * 16 + hi * 8), g1 = *(const f32x4*)(qn + d0 * 16 + hi * 8 + 4);
.LBB0_1452:
	s_ashr_i32 s8, s2, 7
	s_lshl_b32 s6, s2, 8
	v_mov_b32_e32 v162, v188
	s_lshl_b32 s24, s8, 12
	s_and_b32 s6, s6, 0xf00
	s_or_b32 s6, s24, s6
	v_ashrrev_i32_e32 v0, 1, v162
	v_and_b32_e32 v0, 0xffffffe0, v0
	v_and_b32_e32 v184, 31, v162
	v_add_u32_e32 v178, s6, v0
	s_bfe_u32 s3, s2, 0x30004
	v_or_b32_e32 v36, v178, v184
	v_mov_b64_e32 v[0:1], s[14:15]
	v_bfe_u32 v185, v162, 5, 1
	v_mad_i64_i32 v[0:1], s[6:7], v36, s89, v[0:1]
	s_mul_i32 s68, s3, 0x180
	v_lshl_add_u64 v[0:1], v[0:1], 0, s[68:69]
	v_lshlrev_b32_e32 v172, 4, v185
	v_lshl_add_u64 v[32:33], v[0:1], 0, v[172:173]
	global_load_dwordx4 v[20:23], v[32:33], off
	global_load_dwordx4 v[24:27], v[32:33], off offset:32
	global_load_dwordx4 v[16:19], v[32:33], off offset:64
	global_load_dwordx4 v[12:15], v[32:33], off offset:96
	global_load_dwordx4 v[8:11], v[32:33], off offset:128
	global_load_dwordx4 v[4:7], v[32:33], off offset:160
	global_load_dwordx4 v[0:3], v[32:33], off offset:192
	v_and_b32_e32 v124, 32, v162
	global_load_dwordx4 v[112:115], v124, s[20:21] offset:704
	global_load_dwordx4 v[138:141], v124, s[20:21] offset:720
	global_load_dwordx4 v[28:31], v[32:33], off offset:224
	global_load_dwordx4 v[100:103], v[32:33], off offset:256
	global_load_dwordx4 v[96:99], v[32:33], off offset:288
	global_load_dwordx4 v[116:119], v[32:33], off offset:320
	global_load_dwordx4 v[120:123], v[32:33], off offset:352
	v_mov_b32_e32 v125, v173
	s_mov_b64 s[6:7], 0x1000
	s_lshl_b32 s25, s8, 8
	s_add_i32 s11, 0, 0x14000
	s_add_i32 s31, s25, 0x4000
	s_cmp_lg_u32 0, -1
	s_cselect_b32 s34, 0, 0
	s_mov_b32 s50, s48
	s_mov_b32 s51, s48
	s_mov_b32 s52, s48
	s_mov_b32 s53, s48
	s_mov_b32 s54, s48
	s_mov_b32 s55, s48
	s_mov_b32 s56, s48
	s_mov_b32 s57, s48
	s_mov_b32 s58, s48
	s_mov_b32 s59, s48
	s_mov_b32 s60, s48
	s_mov_b32 s61, s48
	s_mov_b32 s62, s48
	s_mov_b32 s63, s48
	v_mov_b64_e32 v[190:191], 0x100
	v_mov_b64_e32 v[252:253], 0xff
	s_waitcnt vmcnt(0)
	v_lshlrev_b32_e32 v229, 16, v20
	v_and_b32_e32 v230, 0xffff0000, v20
	v_lshlrev_b32_e32 v214, 16, v16
	v_and_b32_e32 v213, 0xffff0000, v16
	v_lshlrev_b32_e32 v212, 16, v17
	v_and_b32_e32 v211, 0xffff0000, v17
	v_lshlrev_b32_e32 v210, 16, v18
	v_and_b32_e32 v209, 0xffff0000, v18
	v_lshlrev_b32_e32 v208, 16, v19
	v_and_b32_e32 v207, 0xffff0000, v19
	global_load_dwordx4 v[16:19], v124, s[20:21] offset:656
	v_lshlrev_b32_e32 v227, 16, v21
	v_and_b32_e32 v228, 0xffff0000, v21
	v_lshlrev_b32_e32 v225, 16, v22
	v_and_b32_e32 v226, 0xffff0000, v22
	v_lshlrev_b32_e32 v223, 16, v23
	v_and_b32_e32 v224, 0xffff0000, v23
	global_load_dwordx4 v[20:23], v124, s[20:21] offset:640
	v_mul_f32_e32 v194, v230, v230
	v_fmac_f32_e32 v194, v229, v229
	v_fmac_f32_e32 v194, v227, v227
	v_fmac_f32_e32 v194, v228, v228
	v_fmac_f32_e32 v194, v225, v225
	v_fmac_f32_e32 v194, v226, v226
	v_fmac_f32_e32 v194, v223, v223
	v_lshlrev_b32_e32 v221, 16, v24
	v_fmac_f32_e32 v194, v224, v224
	v_and_b32_e32 v222, 0xffff0000, v24
	v_fmac_f32_e32 v194, v221, v221
	v_lshlrev_b32_e32 v219, 16, v25
	v_fmac_f32_e32 v194, v222, v222
	v_and_b32_e32 v220, 0xffff0000, v25
	v_fmac_f32_e32 v194, v219, v219
	v_lshlrev_b32_e32 v218, 16, v26
	v_fmac_f32_e32 v194, v220, v220
	v_and_b32_e32 v217, 0xffff0000, v26
	v_fmac_f32_e32 v194, v218, v218
	v_lshlrev_b32_e32 v216, 16, v27
	v_fmac_f32_e32 v194, v217, v217
	v_and_b32_e32 v215, 0xffff0000, v27
	v_fmac_f32_e32 v194, v216, v216
	v_fmac_f32_e32 v194, v215, v215
	v_fmac_f32_e32 v194, v214, v214
	v_fmac_f32_e32 v194, v213, v213
	v_fmac_f32_e32 v194, v212, v212
	v_fmac_f32_e32 v194, v211, v211
	v_fmac_f32_e32 v194, v210, v210
	v_lshlrev_b32_e32 v165, 16, v0
	v_and_b32_e32 v164, 0xffff0000, v0
	v_fmac_f32_e32 v194, v209, v209
	v_lshlrev_b32_e32 v0, 6, v36
	v_lshlrev_b32_e32 v163, 16, v1
	v_fmac_f32_e32 v194, v208, v208
	v_and_b32_e32 v239, 0xffff0000, v1
	v_lshl_add_u64 v[24:25], s[18:19], 0, v[124:125]
	v_and_b32_e32 v0, 0xfc0, v0
	v_mov_b32_e32 v1, v173
	v_lshlrev_b32_e32 v206, 16, v12
	v_lshlrev_b32_e32 v180, 16, v4
	v_and_b32_e32 v179, 0xffff0000, v4
	v_lshlrev_b32_e32 v171, 16, v5
	v_and_b32_e32 v170, 0xffff0000, v5
	v_fmac_f32_e32 v194, v207, v207
	v_lshl_add_u64 v[4:5], v[24:25], 0, v[0:1]
	v_and_b32_e32 v205, 0xffff0000, v12
	v_lshlrev_b32_e32 v198, 16, v8
	v_and_b32_e32 v197, 0xffff0000, v8
	v_lshlrev_b32_e32 v196, 16, v9
	v_and_b32_e32 v187, 0xffff0000, v9
	v_lshlrev_b32_e32 v186, 16, v10
	v_and_b32_e32 v183, 0xffff0000, v10
	v_lshlrev_b32_e32 v182, 16, v11
	v_and_b32_e32 v181, 0xffff0000, v11
	v_lshlrev_b32_e32 v169, 16, v6
	v_and_b32_e32 v168, 0xffff0000, v6
	v_lshlrev_b32_e32 v167, 16, v7
	v_and_b32_e32 v166, 0xffff0000, v7
	v_fmac_f32_e32 v194, v206, v206
	v_lshlrev_b32_e32 v237, 16, v2
	v_and_b32_e32 v235, 0xffff0000, v2
	v_lshlrev_b32_e32 v233, 16, v3
	v_and_b32_e32 v231, 0xffff0000, v3
	global_load_dwordx4 v[104:107], v124, s[20:21] offset:16
	global_load_dwordx4 v[108:111], v124, s[20:21]
	global_load_dwordx4 v[88:91], v124, s[20:21] offset:80
	global_load_dwordx4 v[92:95], v124, s[20:21] offset:64
	global_load_dwordx4 v[80:83], v124, s[20:21] offset:144
	global_load_dwordx4 v[84:87], v124, s[20:21] offset:128
	global_load_dwordx4 v[72:75], v124, s[20:21] offset:208
	global_load_dwordx4 v[76:79], v124, s[20:21] offset:192
	global_load_dwordx4 v[64:67], v124, s[20:21] offset:272
	global_load_dwordx4 v[68:71], v124, s[20:21] offset:256
	global_load_dwordx4 v[48:51], v124, s[20:21] offset:336
	global_load_dwordx4 v[56:59], v124, s[20:21] offset:320
	global_load_dwordx4 v[32:35], v124, s[20:21] offset:400
	global_load_dwordx4 v[40:43], v124, s[20:21] offset:384
	global_load_dwordx4 v[8:11], v[4:5], off
	global_load_dwordx4 v[0:3], v[4:5], off offset:16
; __device__ __forceinline__ void unpack8(const u32x4 w, float* f) { f[0] = bf_lo(w.x); f[1] = bf_hi(w.x); f[2] = bf_lo(w.y); f[3] = bf_hi(w.y); f[4] = bf_lo(w.z); f[5] = bf_hi(w.z); f[6] = bf_lo(w.w); f[7] = bf_hi(w.w); }
; __device__ __forceinline__ void attn_unit(const bf16_t* __restrict__ Qb, const bf16_t* __restrict__ KV, const bf16_t* __restrict__ KP, bf16_t* __restrict__ Ob, ...
;     ...
;   const bf16_t* Qw = Qb + (size_t)(qrow0 + wid * QBLK + r32) * LDQ + h * QKD + hi * 8;
; #pragma unroll
;   for (int d0 = 0; d0 < 12; ++d0) qr[d0] = ld8(Qw + d0 * 16);
;   {
;     float qf[12][8]; float ss = 0.f;
; #pragma unroll
;     for (int d0 = 0; d0 < 12; ++d0) { const u32x4 w = *reinterpret_cast<const u32x4*>(&qr[d0]); unpack8(w, qf[d0]);
; #pragma unroll
;       for (int jj = 0; jj < 8; ++jj) ss += qf[d0][jj] * qf[d0][jj]; }
;     { auto rr = __builtin_amdgcn_permlane32_swap(__float_as_uint(ss), __float_as_uint(ss), false, false); ss = __uint_as_float(rr[0]) + __uint_as_float(rr[1]); }
;     const float rinv = 1.0f / sqrtf(ss * (1.f / QKD) + EPS);
; #pragma unroll
;     for (int d0 = 0; d0 < 12; ++d0) { const f32x4 g0 = *(const f32x4*)(qn + d0 * 16 + hi * 8), g1 = *(const f32x4*)(qn + d0 * 16 + hi * 8 + 4);
; #pragma unroll
;       for (int jj = 0; jj < 8; ++jj) qf[d0][jj] *= rinv * (jj < 4 ? g0[jj & 3] : g1[jj & 3]); }
;     if (do_rope) { const int s = (qrow0 + wid * QBLK + r32) & (SEQ - 1), pr_ = s >> 6, pc_ = s & 63;
; #pragma unroll
;       for (int ax = 0; ax < 2; ++ax) { const float* cp = rope + (ax ? pc_ : pr_) * 16 + hi * 8; const f32x4 c0 = *(const f32x4*)cp, c1 = *(const f32x4*)(cp + 4), s0 = *(const f32x4*)(cp + 1024), s1 = *(const f32x4*)(cp + 1028);
	v_lshl_add_u64 v[6:7], v[4:5], 0, s[6:7]
	v_add_co_u32_e32 v4, vcc, s49, v4
	v_lshlrev_b32_e32 v204, 16, v13
	v_fmac_f32_e32 v194, v205, v205
	v_addc_co_u32_e32 v5, vcc, 0, v5, vcc
	v_and_b32_e32 v203, 0xffff0000, v13
	v_lshlrev_b32_e32 v202, 16, v14
	v_and_b32_e32 v201, 0xffff0000, v14
	v_lshlrev_b32_e32 v200, 16, v15
	v_and_b32_e32 v199, 0xffff0000, v15
	v_fmac_f32_e32 v194, v204, v204
	v_lshlrev_b32_e32 v241, 16, v28
	v_and_b32_e32 v244, 0xffff0000, v28
	v_lshlrev_b32_e32 v245, 16, v29
	v_and_b32_e32 v240, 0xffff0000, v29
	v_lshlrev_b32_e32 v238, 16, v30
	v_and_b32_e32 v236, 0xffff0000, v30
	v_lshlrev_b32_e32 v234, 16, v31
	v_and_b32_e32 v232, 0xffff0000, v31
	global_load_dwordx4 v[12:15], v[4:5], off
	s_nop 0
	global_load_dwordx4 v[4:7], v[6:7], off offset:16
	s_nop 0
	global_load_dwordx4 v[52:55], v124, s[20:21] offset:464
	global_load_dwordx4 v[60:63], v124, s[20:21] offset:448
	global_load_dwordx4 v[36:39], v124, s[20:21] offset:512
	global_load_dwordx4 v[28:31], v124, s[20:21] offset:528
	global_load_dwordx4 v[44:47], v124, s[20:21] offset:576
	s_nop 0
	global_load_dwordx4 v[124:127], v124, s[20:21] offset:592
	v_fmac_f32_e32 v194, v203, v203
	v_fmac_f32_e32 v194, v202, v202
	v_fmac_f32_e32 v194, v201, v201
	v_fmac_f32_e32 v194, v200, v200
	v_fmac_f32_e32 v194, v199, v199
	v_fmac_f32_e32 v194, v198, v198
	v_fmac_f32_e32 v194, v197, v197
	v_fmac_f32_e32 v194, v196, v196
	v_fmac_f32_e32 v194, v187, v187
	v_fmac_f32_e32 v194, v186, v186
	v_fmac_f32_e32 v194, v183, v183
	v_fmac_f32_e32 v194, v182, v182
	v_fmac_f32_e32 v194, v181, v181
	v_fmac_f32_e32 v194, v180, v180
	v_fmac_f32_e32 v194, v179, v179
	v_fmac_f32_e32 v194, v171, v171
	v_fmac_f32_e32 v194, v170, v170
	v_fmac_f32_e32 v194, v169, v169
	v_fmac_f32_e32 v194, v168, v168
	v_fmac_f32_e32 v194, v167, v167
	v_fmac_f32_e32 v194, v166, v166
	v_fmac_f32_e32 v194, v165, v165
	v_fmac_f32_e32 v194, v164, v164
	v_fmac_f32_e32 v194, v163, v163
	v_fmac_f32_e32 v194, v239, v239
	v_fmac_f32_e32 v194, v237, v237
	v_fmac_f32_e32 v194, v235, v235
	v_fmac_f32_e32 v194, v233, v233
	v_fmac_f32_e32 v194, v231, v231
	v_fmac_f32_e32 v194, v241, v241
	v_fmac_f32_e32 v194, v244, v244
	v_fmac_f32_e32 v194, v245, v245
	v_fmac_f32_e32 v194, v240, v240
	v_fmac_f32_e32 v194, v238, v238
	v_fmac_f32_e32 v194, v236, v236
	v_fmac_f32_e32 v194, v234, v234
	v_lshlrev_b32_e32 v159, 16, v100
	v_lshlrev_b32_e32 v158, 16, v96
	v_fmac_f32_e32 v194, v232, v232
	v_lshlrev_b32_e32 v154, 16, v97
	v_and_b32_e32 v156, 0xffff0000, v97
	v_and_b32_e32 v161, 0xffff0000, v100
	v_and_b32_e32 v160, 0xffff0000, v96
	v_pk_mul_f32 v[96:97], v[158:159], v[158:159]
	v_lshlrev_b32_e32 v146, 16, v99
	v_and_b32_e32 v148, 0xffff0000, v99
	v_lshlrev_b32_e32 v150, 16, v98
	v_and_b32_e32 v152, 0xffff0000, v98
	v_lshlrev_b32_e32 v155, 16, v101
	v_add_f32_e32 v97, v97, v194
	v_pk_mul_f32 v[98:99], v[160:161], v[160:161]
	v_pk_mul_f32 v[192:193], v[154:155], v[154:155]
	v_and_b32_e32 v157, 0xffff0000, v101
	v_add_f32_e32 v97, v99, v97
	v_lshlrev_b32_e32 v151, 16, v102
	v_pk_mul_f32 v[100:101], v[156:157], v[156:157]
	v_add_f32_e32 v97, v193, v97
	v_lshlrev_b32_e32 v128, 16, v123
	v_lshlrev_b32_e32 v129, 16, v119
	v_mov_b32_e32 v130, v140
	s_waitcnt vmcnt(25)
	v_mov_b32_e32 v131, v18
	v_and_b32_e32 v133, 0xffff0000, v119
	v_and_b32_e32 v132, 0xffff0000, v123
	v_mov_b32_e32 v18, v141
	v_lshlrev_b32_e32 v135, 16, v118
	v_lshlrev_b32_e32 v134, 16, v122
	v_and_b32_e32 v119, 0xffff0000, v118
	v_and_b32_e32 v118, 0xffff0000, v122
	v_lshlrev_b32_e32 v123, 16, v117
	v_lshlrev_b32_e32 v122, 16, v121
	v_and_b32_e32 v141, 0xffff0000, v117
	v_and_b32_e32 v140, 0xffff0000, v121
	v_lshlrev_b32_e32 v143, 16, v116
	v_lshlrev_b32_e32 v142, 16, v120
	v_and_b32_e32 v117, 0xffff0000, v116
	v_and_b32_e32 v116, 0xffff0000, v120
	v_pk_mul_f32 v[120:121], v[150:151], v[150:151]
	v_and_b32_e32 v153, 0xffff0000, v102
	v_add_f32_e32 v97, v101, v97
	v_lshlrev_b32_e32 v147, 16, v103
	v_and_b32_e32 v149, 0xffff0000, v103
	v_pk_mul_f32 v[102:103], v[152:153], v[152:153]
	v_add_f32_e32 v97, v121, v97
	v_mov_b32_e32 v144, v112
	s_waitcnt vmcnt(24)
	v_mov_b32_e32 v145, v20
	v_mov_b32_e32 v20, v113
	v_pk_mul_f32 v[112:113], v[146:147], v[146:147]
	v_add_f32_e32 v97, v103, v97
	v_mov_b32_e32 v136, v138
	v_mov_b32_e32 v137, v16
	v_mov_b32_e32 v16, v139
	v_mov_b32_e32 v138, v114
	v_mov_b32_e32 v139, v22
	v_mov_b32_e32 v22, v115
	v_pk_mul_f32 v[114:115], v[148:149], v[148:149]
	v_add_f32_e32 v97, v113, v97
	v_add_f32_e32 v97, v115, v97
	v_add_f32_e32 v96, v96, v97
	v_add_f32_e32 v101, v98, v96
	v_add_f32_e32 v101, v192, v101
	v_add_f32_e32 v100, v100, v101
	v_add_f32_e32 v100, v120, v100
	v_add_f32_e32 v100, v102, v100
	v_add_f32_e32 v102, v112, v100
	v_pk_mul_f32 v[100:101], v[142:143], v[142:143]
	v_add_f32_e32 v102, v114, v102
	v_and_b32_e32 v26, 0xfc0, v178
	v_mov_b32_e32 v27, v173
	v_pk_mul_f32 v[112:113], v[116:117], v[116:117]
	v_add_f32_e32 v101, v101, v102
	v_lshl_add_u64 v[174:175], v[24:25], 0, v[26:27]
	v_pk_mul_f32 v[120:121], v[122:123], v[122:123]
	v_add_f32_e32 v101, v113, v101
	v_lshl_add_u64 v[176:177], v[174:175], 0, s[6:7]
	v_pk_mul_f32 v[242:243], v[140:141], v[140:141]
	v_add_f32_e32 v101, v121, v101
	global_load_dwordx4 v[96:99], v[176:177], off offset:16
	v_pk_mul_f32 v[176:177], v[134:135], v[134:135]
	v_add_f32_e32 v101, v243, v101
	v_pk_mul_f32 v[192:193], v[118:119], v[118:119]
	v_add_f32_e32 v101, v177, v101
	v_add_f32_e32 v101, v193, v101
	v_fmac_f32_e32 v101, v129, v129
	v_fmac_f32_e32 v101, v133, v133
	v_add_f32_e32 v113, v100, v101
	v_add_f32_e32 v121, v112, v113
	global_load_dwordx4 v[24:27], v[174:175], off offset:16
	global_load_dwordx4 v[100:103], v[174:175], off
	v_add_co_u32_e32 v194, vcc, s49, v174
	v_add_f32_e32 v174, v120, v121
	s_nop 0
	v_addc_co_u32_e32 v195, vcc, 0, v175, vcc
	v_add_f32_e32 v177, v242, v174
	global_load_dwordx4 v[112:115], v[194:195], off
	v_mov_b32_e32 v174, v132
	v_mov_b32_e32 v175, v128
	v_add_f32_e32 v176, v176, v177
	v_pk_mul_f32 v[174:175], v[174:175], v[174:175]
	v_add_f32_e32 v176, v192, v176
	v_add_f32_e32 v175, v175, v176
	v_add_f32_e32 v174, v174, v175
	v_mov_b32_e32 v175, v174
	s_nop 1
	v_permlane32_swap_b32_e32 v174, v175
	v_add_f32_e32 v174, v174, v175
	v_fmamk_f32 v174, v174, 0x3baaaaab, v189
	v_mul_f32_e32 v175, 0x4f800000, v174
	v_cmp_gt_f32_e32 vcc, s91, v174
	s_waitcnt vmcnt(12)
; __device__ __forceinline__ void attn_unit(const bf16_t* __restrict__ Qb, const bf16_t* __restrict__ KV, const bf16_t* __restrict__ KP, bf16_t* __restrict__ Ob, ...
;     ...
;     const float rinv = 1.0f / sqrtf(ss * (1.f / QKD) + EPS);
; #pragma unroll
;     for (int d0 = 0; d0 < 12; ++d0) { const f32x4 g0 = *(const f32x4*)(qn + d0 * 16 + hi * 8), g1 = *(const f32x4*)(qn + d0 * 16 + hi * 8 + 4);
; #pragma unroll
;       for (int jj = 0; jj < 8; ++jj) qf[d0][jj] *= rinv * (jj < 4 ? g0[jj & 3] : g1[jj & 3]); }
	v_mov_b32_e32 v120, v2
	s_waitcnt vmcnt(10)
	v_mov_b32_e32 v121, v6
	v_cndmask_b32_e32 v176, v174, v175, vcc
	v_sqrt_f32_e32 v177, v176
	s_waitcnt vmcnt(4)
	v_mov_b32_e32 v174, v126
	v_mov_b32_e32 v175, v30
	v_mov_b32_e32 v30, v127
	v_add_u32_e32 v126, -1, v177
	v_fma_f32 v127, -v126, v177, v176
	v_cmp_ge_f32_e64 s[6:7], 0, v127
	v_add_u32_e32 v127, 1, v177
	s_mov_b32 s49, s48
	v_cndmask_b32_e64 v126, v177, v126, s[6:7]
	v_fma_f32 v177, -v127, v177, v176
	v_cmp_lt_f32_e64 s[6:7], 0, v177
	s_nop 1
	v_cndmask_b32_e64 v126, v126, v127, s[6:7]
	v_mul_f32_e32 v127, 0x37800000, v126
	v_cndmask_b32_e32 v126, v126, v127, vcc
	v_cmp_class_f32_e32 vcc, v176, v254
	v_mov_b32_e32 v127, v28
	v_mov_b32_e32 v28, v125
	v_cndmask_b32_e32 v176, v126, v176, vcc
	v_div_scale_f32 v177, s[6:7], v176, v176, 1.0
	v_rcp_f32_e32 v192, v177
	v_mov_b32_e32 v126, v124
	v_mov_b32_e32 v124, v0
	v_mov_b32_e32 v125, v4
	v_fma_f32 v193, -v177, v192, 1.0
	v_fmac_f32_e32 v192, v193, v192
	v_div_scale_f32 v193, vcc, 1.0, v176, 1.0
	v_mul_f32_e32 v194, v193, v192
	v_fma_f32 v195, -v177, v194, v193
	v_fmac_f32_e32 v194, v195, v192
	v_fma_f32 v177, -v177, v194, v193
	v_div_fmas_f32 v177, v177, v192, v194
	v_div_fixup_f32 v176, v177, v176, 1.0
	v_mul_f32_e32 v176, 0x3dd53b94, v176
	v_mul_f32_e32 v109, v109, v176
	v_mul_f32_e32 v230, v109, v230
	v_mov_b32_e32 v109, v38
	v_mov_b32_e32 v38, v47
	v_mov_b32_e32 v47, v36
	v_mul_f32_e32 v36, v88, v176
	v_mul_f32_e32 v218, v36, v218
	v_mul_f32_e32 v36, v89, v176
	v_mul_f32_e32 v217, v36, v217
	v_mul_f32_e32 v36, v90, v176
	v_mul_f32_e32 v90, v36, v216
	v_mul_f32_e32 v36, v91, v176
	v_mul_f32_e32 v91, v36, v215
	v_mul_f32_e32 v36, v84, v176
	v_mul_f32_e32 v84, v36, v214
	v_mul_f32_e32 v36, v85, v176
	v_mul_f32_e32 v85, v36, v213
	v_mul_f32_e32 v36, v86, v176
	v_mul_f32_e32 v86, v36, v212
	v_mul_f32_e32 v36, v87, v176
	v_mul_f32_e32 v87, v36, v211
	v_mul_f32_e32 v36, v176, v80
	v_mul_f32_e32 v80, v36, v210
	v_mul_f32_e32 v36, v176, v81
	v_mul_f32_e32 v81, v36, v209
	v_mul_f32_e32 v36, v176, v82
	v_mul_f32_e32 v82, v36, v208
	v_mul_f32_e32 v36, v176, v83
	v_mul_f32_e32 v83, v36, v207
	v_mul_f32_e32 v36, v176, v76
	v_mul_f32_e32 v76, v36, v206
	v_mul_f32_e32 v36, v176, v77
	v_mul_f32_e32 v77, v36, v205
	v_mul_f32_e32 v36, v176, v78
	v_mul_f32_e32 v78, v36, v204
	v_mul_f32_e32 v36, v176, v79
	v_mul_f32_e32 v79, v36, v203
	v_mul_f32_e32 v36, v176, v72
	v_mul_f32_e32 v72, v36, v202
	v_mul_f32_e32 v36, v176, v73
	v_mul_f32_e32 v73, v36, v201
	v_mul_f32_e32 v36, v176, v74
	v_mul_f32_e32 v74, v36, v200
	v_mul_f32_e32 v36, v176, v75
	v_mul_f32_e32 v75, v36, v199
	v_mul_f32_e32 v36, v176, v68
	v_mul_f32_e32 v68, v36, v198
	v_mul_f32_e32 v36, v176, v69
	v_mul_f32_e32 v69, v36, v197
	v_mul_f32_e32 v36, v176, v70
	v_mul_f32_e32 v70, v36, v196
	v_mul_f32_e32 v36, v176, v71
	v_mul_f32_e32 v71, v36, v187
	v_mul_f32_e32 v36, v176, v64
	v_mul_f32_e32 v64, v36, v186
	v_mul_f32_e32 v36, v176, v65
	v_mul_f32_e32 v65, v36, v183
	v_mul_f32_e32 v36, v176, v66
	v_mul_f32_e32 v66, v36, v182
	v_mul_f32_e32 v36, v176, v67
	v_mul_f32_e32 v67, v36, v181
	v_mul_f32_e32 v36, v176, v56
	v_mul_f32_e32 v56, v36, v180
	v_mul_f32_e32 v36, v176, v57
	v_mul_f32_e32 v57, v36, v179
	v_mul_f32_e32 v36, v176, v58
	v_mul_f32_e32 v32, v176, v32
	v_mul_f32_e32 v58, v36, v171
	v_mul_f32_e32 v171, v32, v237
	v_mul_f32_e32 v32, v176, v33
	v_mul_f32_e32 v179, v32, v235
	v_mul_f32_e32 v32, v176, v34
	v_mul_f32_e32 v36, v176, v59
	v_mul_f32_e32 v180, v32, v233
	v_mul_f32_e32 v32, v176, v35
	v_mul_f32_e32 v59, v36, v170
	v_mul_f32_e32 v36, v176, v48
	v_mul_f32_e32 v181, v32, v231
	v_mul_f32_e32 v32, v176, v60
	v_mul_f32_e32 v169, v36, v169
	v_mul_f32_e32 v36, v176, v49
	v_mul_f32_e32 v60, v32, v241
	v_mul_f32_e32 v32, v176, v61
	v_mul_f32_e32 v168, v36, v168
	v_mul_f32_e32 v36, v176, v50
	v_mul_f32_e32 v61, v32, v244
	v_mul_f32_e32 v32, v176, v62
	v_mul_f32_e32 v167, v36, v167
	v_mul_f32_e32 v36, v176, v51
	v_mul_f32_e32 v62, v32, v245
	v_mul_f32_e32 v32, v176, v63
	v_mul_f32_e32 v166, v36, v166
	v_mul_f32_e32 v36, v176, v40
	v_mul_f32_e32 v63, v32, v240
	v_mul_f32_e32 v32, v176, v52
	v_mul_f32_e32 v165, v36, v165
	v_mul_f32_e32 v36, v176, v41
	v_mul_f32_e32 v182, v32, v238
	v_mul_f32_e32 v32, v176, v53
	v_mul_f32_e32 v108, v108, v176
	v_mul_f32_e32 v177, v104, v176
	v_mul_f32_e32 v164, v36, v164
	v_mul_f32_e32 v36, v176, v42
	v_mul_f32_e32 v183, v32, v236
	v_mul_f32_e32 v32, v176, v54
	v_mul_f32_e32 v229, v108, v229
	v_mul_f32_e32 v177, v177, v225
	v_mov_b32_e32 v108, v46
	v_mov_b32_e32 v46, v44
	v_mul_f32_e32 v163, v36, v163
	v_mul_f32_e32 v36, v176, v43
	v_mul_f32_e32 v54, v32, v234
	v_mul_f32_e32 v32, v176, v55
	v_mul_f32_e32 v170, v36, v239
	v_mul_f32_e32 v55, v32, v232
	v_pk_mul_f32 v[32:33], v[176:177], v[46:47] op_sel_hi:[0,1]
	v_mov_b32_e32 v36, v45
	s_waitcnt vmcnt(1)
	v_mov_b32_e32 v88, v100
	s_waitcnt vmcnt(0)
; __device__ __forceinline__ u32x4 pack8(const float* f) { u32x4 w; w.x = cvt_pk_bf16(f[0], f[1]); w.y = cvt_pk_bf16(f[2], f[3]); w.z = cvt_pk_bf16(f[4], f[5]); w.w = cvt_pk_bf16(f[6], f[7]); return w; }
; __device__ __forceinline__ void attn_unit(const bf16_t* __restrict__ Qb, const bf16_t* __restrict__ KV, const bf16_t* __restrict__ KP, bf16_t* __restrict__ Ob, ...
;     ...
;     if (do_rope) { const int s = (qrow0 + wid * QBLK + r32) & (SEQ - 1), pr_ = s >> 6, pc_ = s & 63;
; #pragma unroll
;       for (int ax = 0; ax < 2; ++ax) { const float* cp = rope + (ax ? pc_ : pr_) * 16 + hi * 8; const f32x4 c0 = *(const f32x4*)cp, c1 = *(const f32x4*)(cp + 4), s0 = *(const f32x4*)(cp + 1024), s1 = *(const f32x4*)(cp + 1028);
; #pragma unroll
;         for (int jj = 0; jj < 8; ++jj) { const float c = jj < 4 ? c0[jj & 3] : c1[jj & 3], sn = jj < 4 ? s0[jj & 3] : s1[jj & 3], a = qf[8 + 2 * ax][jj], b = qf[9 + 2 * ax][jj];
;           qf[8 + 2 * ax][jj] = a * c - b * sn; qf[9 + 2 * ax][jj] = b * c + a * sn; } } }
; #pragma unroll
;     for (int d0 = 0; d0 < 12; ++d0) { const u32x4 w = pack8(qf[d0]); qr[d0] = *reinterpret_cast<const bf16x8*>(&w); }
	v_mov_b32_e32 v89, v112
	v_pk_mul_f32 v[32:33], v[32:33], v[158:159]
	v_pk_mul_f32 v[34:35], v[176:177], v[36:37] op_sel_hi:[0,1]
	v_mov_b32_e32 v52, v112
	v_mov_b32_e32 v53, v100
	v_pk_mul_f32 v[34:35], v[34:35], v[160:161]
	v_pk_mul_f32 v[52:53], v[32:33], v[52:53]
	v_pk_mul_f32 v[32:33], v[32:33], v[88:89]
	v_mov_b32_e32 v100, v113
	v_sub_f32_e32 v52, v53, v52
	v_add_f32_e32 v53, v32, v33
	v_pk_mul_f32 v[32:33], v[34:35], v[100:101]
	v_mov_b32_e32 v112, v101
	v_pk_mul_f32 v[36:37], v[176:177], v[108:109] op_sel_hi:[0,1]
	v_sub_f32_e32 v88, v33, v32
	v_pk_mul_f32 v[32:33], v[34:35], v[112:113]
	v_mul_f32_e32 v110, v110, v176
	v_mul_f32_e32 v111, v111, v176
	v_pk_mul_f32 v[36:37], v[36:37], v[154:155]
	v_add_f32_e32 v34, v32, v33
	v_mov_b32_e32 v32, v114
	v_mov_b32_e32 v33, v102
	v_mul_f32_e32 v227, v110, v227
	v_mul_f32_e32 v228, v111, v228
	v_mov_b32_e32 v110, v102
	v_mov_b32_e32 v111, v114
	v_pk_mul_f32 v[38:39], v[176:177], v[38:39] op_sel_hi:[0,1]
	v_pk_mul_f32 v[32:33], v[36:37], v[32:33]
	v_pk_mul_f32 v[38:39], v[38:39], v[156:157]
	v_sub_f32_e32 v35, v33, v32
	v_pk_mul_f32 v[32:33], v[36:37], v[110:111]
	v_mov_b32_e32 v102, v115
	v_add_f32_e32 v36, v32, v33
	v_pk_mul_f32 v[32:33], v[38:39], v[102:103]
	v_mov_b32_e32 v114, v103
	v_pk_mul_f32 v[40:41], v[176:177], v[126:127] op_sel_hi:[0,1]
	v_sub_f32_e32 v37, v33, v32
	v_pk_mul_f32 v[32:33], v[38:39], v[114:115]
	v_pk_mul_f32 v[40:41], v[40:41], v[150:151]
	v_add_f32_e32 v38, v32, v33
	v_mov_b32_e32 v32, v96
	v_mov_b32_e32 v33, v24
	v_mul_f32_e32 v193, v106, v176
	v_mul_f32_e32 v194, v107, v176
	v_mov_b32_e32 v106, v24
	v_mov_b32_e32 v107, v96
	v_pk_mul_f32 v[28:29], v[176:177], v[28:29] op_sel_hi:[0,1]
	v_pk_mul_f32 v[32:33], v[40:41], v[32:33]
	v_pk_mul_f32 v[28:29], v[28:29], v[152:153]
	v_sub_f32_e32 v39, v33, v32
	v_pk_mul_f32 v[32:33], v[40:41], v[106:107]
	v_mov_b32_e32 v24, v97
	v_mov_b32_e32 v96, v25
	v_pk_mul_f32 v[42:43], v[176:177], v[174:175] op_sel_hi:[0,1]
	v_add_f32_e32 v40, v32, v33
	v_pk_mul_f32 v[32:33], v[28:29], v[24:25]
	v_pk_mul_f32 v[24:25], v[28:29], v[96:97]
	v_pk_mul_f32 v[42:43], v[42:43], v[146:147]
	v_add_f32_e32 v28, v24, v25
	v_mov_b32_e32 v24, v98
	v_mov_b32_e32 v25, v26
	v_mul_f32_e32 v192, v105, v176
	v_mov_b32_e32 v104, v26
	v_mov_b32_e32 v105, v98
	v_pk_mul_f32 v[30:31], v[176:177], v[30:31] op_sel_hi:[0,1]
	v_pk_mul_f32 v[24:25], v[42:43], v[24:25]
	v_pk_mul_f32 v[30:31], v[30:31], v[148:149]
	v_sub_f32_e32 v29, v25, v24
	v_pk_mul_f32 v[24:25], v[42:43], v[104:105]
	v_mov_b32_e32 v26, v99
	v_sub_f32_e32 v32, v33, v32
	v_add_f32_e32 v33, v24, v25
	v_pk_mul_f32 v[24:25], v[30:31], v[26:27]
	v_mov_b32_e32 v98, v27
	v_pk_mul_f32 v[44:45], v[176:177], v[144:145] op_sel_hi:[0,1]
	v_sub_f32_e32 v26, v25, v24
	v_pk_mul_f32 v[24:25], v[30:31], v[98:99]
	v_pk_mul_f32 v[44:45], v[44:45], v[142:143]
	v_add_f32_e32 v27, v24, v25
	v_mov_b32_e32 v24, v12
	v_mov_b32_e32 v25, v8
	v_mul_f32_e32 v243, v94, v176
	v_mul_f32_e32 v246, v95, v176
	v_mov_b32_e32 v94, v8
	v_mov_b32_e32 v95, v12
	v_pk_mul_f32 v[20:21], v[176:177], v[20:21] op_sel_hi:[0,1]
	v_pk_mul_f32 v[24:25], v[44:45], v[24:25]
	v_pk_mul_f32 v[20:21], v[20:21], v[116:117]
	v_sub_f32_e32 v30, v25, v24
	v_pk_mul_f32 v[24:25], v[44:45], v[94:95]
	v_mov_b32_e32 v8, v13
	v_mov_b32_e32 v12, v9
	v_pk_mul_f32 v[46:47], v[176:177], v[138:139] op_sel_hi:[0,1]
	v_add_f32_e32 v31, v24, v25
	v_pk_mul_f32 v[24:25], v[20:21], v[8:9]
	v_pk_mul_f32 v[8:9], v[20:21], v[12:13]
	v_pk_mul_f32 v[46:47], v[46:47], v[122:123]
	v_add_f32_e32 v12, v8, v9
	v_mov_b32_e32 v8, v14
	v_mov_b32_e32 v9, v10
	v_mul_f32_e32 v195, v92, v176
	v_mul_f32_e32 v242, v93, v176
	v_mov_b32_e32 v92, v10
	v_mov_b32_e32 v93, v14
	v_pk_mul_f32 v[22:23], v[176:177], v[22:23] op_sel_hi:[0,1]
	v_pk_mul_f32 v[8:9], v[46:47], v[8:9]
	v_pk_mul_f32 v[22:23], v[22:23], v[140:141]
	v_sub_f32_e32 v13, v9, v8
	v_pk_mul_f32 v[8:9], v[46:47], v[92:93]
	v_mov_b32_e32 v10, v15
	v_add_f32_e32 v20, v8, v9
	v_pk_mul_f32 v[8:9], v[22:23], v[10:11]
	v_mov_b32_e32 v14, v11
	v_pk_mul_f32 v[48:49], v[176:177], v[136:137] op_sel_hi:[0,1]
	v_sub_f32_e32 v10, v9, v8
	v_pk_mul_f32 v[8:9], v[22:23], v[14:15]
	v_pk_mul_f32 v[48:49], v[48:49], v[134:135]
	v_add_f32_e32 v11, v8, v9
	v_mov_b32_e32 v8, v4
	v_mov_b32_e32 v9, v0
	v_pk_mul_f32 v[16:17], v[176:177], v[16:17] op_sel_hi:[0,1]
	v_pk_mul_f32 v[8:9], v[48:49], v[8:9]
	v_pk_mul_f32 v[16:17], v[16:17], v[118:119]
	v_sub_f32_e32 v14, v9, v8
	v_pk_mul_f32 v[8:9], v[48:49], v[124:125]
	v_mov_b32_e32 v0, v5
	v_mov_b32_e32 v4, v1
	v_pk_mul_f32 v[50:51], v[176:177], v[130:131] op_sel_hi:[0,1]
	v_add_f32_e32 v15, v8, v9
	v_pk_mul_f32 v[8:9], v[16:17], v[0:1]
	v_pk_mul_f32 v[0:1], v[16:17], v[4:5]
	v_pk_mul_f32 v[50:51], v[50:51], v[128:129]
	v_add_f32_e32 v4, v0, v1
	v_mov_b32_e32 v0, v6
	v_mov_b32_e32 v1, v2
	v_pk_mul_f32 v[18:19], v[176:177], v[18:19] op_sel_hi:[0,1]
	v_pk_mul_f32 v[0:1], v[50:51], v[0:1]
	v_pk_mul_f32 v[18:19], v[18:19], v[132:133]
	v_sub_f32_e32 v5, v1, v0
	v_pk_mul_f32 v[0:1], v[50:51], v[120:121]
	v_mov_b32_e32 v2, v7
	v_sub_f32_e32 v8, v9, v8
	v_add_f32_e32 v9, v0, v1
	v_pk_mul_f32 v[0:1], v[18:19], v[2:3]
	v_mov_b32_e32 v6, v3
	v_sub_f32_e32 v2, v1, v0
	v_pk_mul_f32 v[0:1], v[18:19], v[6:7]
	v_mul_f32_e32 v192, v192, v226
	v_mul_f32_e32 v193, v193, v223
	v_mul_f32_e32 v194, v194, v224
	v_mul_f32_e32 v195, v195, v221
	v_mul_f32_e32 v221, v242, v222
	v_mul_f32_e32 v219, v243, v219
	v_mul_f32_e32 v220, v246, v220
	v_add_f32_e32 v0, v0, v1
	v_cvt_pk_bf16_f32 v136, v229, v230
	v_cvt_pk_bf16_f32 v137, v227, v228
	v_cvt_pk_bf16_f32 v138, v177, v192
	v_cvt_pk_bf16_f32 v139, v193, v194
	v_cvt_pk_bf16_f32 v132, v195, v221
; __device__ __forceinline__ u32x4 pack8(const float* f) { u32x4 w; w.x = cvt_pk_bf16(f[0], f[1]); w.y = cvt_pk_bf16(f[2], f[3]); w.z = cvt_pk_bf16(f[4], f[5]); w.w = cvt_pk_bf16(f[6], f[7]); return w; }
; __device__ __forceinline__ int v_st(int k, int c) { const int kk = (k & ~0xC) | ((k & 4) << 1) | ((k & 8) >> 1); return ((kk >> 3) * 4 + (c >> 5)) * 512 + ((kk & 7) * 32 + (c & 31)) * 2; }
; __device__ __forceinline__ int v_rd_base(int lane) { return ((lane & 3) << 3) | (((lane >> 2) & 3) << 6) | (((lane >> 4) & 1) << 5) | (((lane >> 5) & 1) << 8); }
; #define SLOAD(j) do { const int r0_ = TROW(j); const bf16_t* a_ = KVh + (size_t)(r0_ + sr) * LDKV + sc; const bf16_t* b_ = KVh + (size_t)(r0_ + 32 + sr) * LDKV + sc; \
;     vs0 = ld8(a_ + 128); vs1 = ld8(b_ + 128); ks0 = ld8(a_); ks1 = ld8(b_); kp0 = ld8(KPh + (size_t)(r0_ + pr) * LDKP + pc); } while (0)
; #define SWRITE(b) do { *(bf16x8*)(V_lds + (b) * SHM_V + vst0) = vs0; *(bf16x8*)(V_lds + (b) * SHM_V + vst1) = vs1; const int kc = sc * 2; \
;     *(bf16x8*)(KN_lds + (b) * SHM_KN + KSWZ(sr, kc)) = ks0; *(bf16x8*)(KN_lds + (b) * SHM_KN + KSWZ(32 + sr, kc)) = ks1; \
;     *(bf16x8*)(KP_lds + (b) * SHM_KP + KPSWZ(pr, pc * 2)) = kp0; } while (0)
; #define SWAIT() asm volatile("s_waitcnt vmcnt(0)" ::: "memory")
; __device__ __forceinline__ void attn_unit(const bf16_t* __restrict__ Qb, const bf16_t* __restrict__ KV, const bf16_t* __restrict__ KP, bf16_t* __restrict__ Ob, ...
;     ...
;     for (int d0 = 0; d0 < 12; ++d0) { const u32x4 w = pack8(qf[d0]); qr[d0] = *reinterpret_cast<const bf16x8*>(&w); }
;   }
;   const int sr = tid >> 4, sc = (tid & 15) * 8, vst0 = v_st(sr, sc), vst1 = v_st(32 + sr, sc);
;   const int pr = tid >> 3, pc = (tid & 7) * 8;
;   const int vb0 = (int)(uintptr_t)V_lds + v_rd_base(lane);
;   bf16x8 vs0, vs1, ks0, ks1, kp0;
;   const bf16_t* KVh = KV + h * 256; const bf16_t* KPh = KP + h * QKR;
;     ...
;   f32x16 pA0, pA1, pB0, pB1; float mnA, mnB, alA, alB; bf16x8 pa0, pa1, pa2, pa3;
;   SLOAD(0); SWAIT(); SWRITE(0); __syncthreads();
	v_cvt_pk_bf16_f32 v133, v219, v220
	v_cvt_pk_bf16_f32 v134, v218, v217
	v_cvt_pk_bf16_f32 v135, v90, v91
	v_cvt_pk_bf16_f32 v128, v84, v85
	v_cvt_pk_bf16_f32 v129, v86, v87
	v_cvt_pk_bf16_f32 v130, v80, v81
	v_cvt_pk_bf16_f32 v131, v82, v83
	v_cvt_pk_bf16_f32 v124, v76, v77
	v_cvt_pk_bf16_f32 v125, v78, v79
	v_cvt_pk_bf16_f32 v126, v72, v73
	v_cvt_pk_bf16_f32 v127, v74, v75
	v_cvt_pk_bf16_f32 v120, v68, v69
	v_cvt_pk_bf16_f32 v121, v70, v71
	v_cvt_pk_bf16_f32 v122, v64, v65
	v_cvt_pk_bf16_f32 v123, v66, v67
	v_cvt_pk_bf16_f32 v140, v56, v57
	v_cvt_pk_bf16_f32 v141, v58, v59
	v_cvt_pk_bf16_f32 v142, v169, v168
	v_cvt_pk_bf16_f32 v143, v167, v166
	v_cvt_pk_bf16_f32 v116, v165, v164
	v_cvt_pk_bf16_f32 v117, v163, v170
	v_cvt_pk_bf16_f32 v118, v171, v179
	v_cvt_pk_bf16_f32 v119, v180, v181
	v_cvt_pk_bf16_f32 v112, v60, v61
	v_cvt_pk_bf16_f32 v113, v62, v63
	v_cvt_pk_bf16_f32 v114, v182, v183
	v_cvt_pk_bf16_f32 v115, v54, v55
	v_cvt_pk_bf16_f32 v108, v52, v88
	v_lshlrev_b32_e32 v52, 3, v162
	v_sub_f32_e32 v24, v25, v24
	v_cvt_pk_bf16_f32 v109, v35, v37
	v_cvt_pk_bf16_f32 v110, v39, v32
	v_cvt_pk_bf16_f32 v111, v29, v26
	v_cvt_pk_bf16_f32 v104, v53, v34
	v_cvt_pk_bf16_f32 v105, v36, v38
	v_cvt_pk_bf16_f32 v106, v40, v28
	v_cvt_pk_bf16_f32 v107, v33, v27
	v_cvt_pk_bf16_f32 v100, v30, v24
	v_cvt_pk_bf16_f32 v101, v13, v10
	v_cvt_pk_bf16_f32 v102, v14, v8
	v_cvt_pk_bf16_f32 v103, v5, v2
	v_cvt_pk_bf16_f32 v96, v31, v12
	v_cvt_pk_bf16_f32 v97, v20, v11
	v_cvt_pk_bf16_f32 v98, v15, v4
	v_cvt_pk_bf16_f32 v99, v9, v0
	v_ashrrev_i32_e32 v198, 4, v162
	v_and_b32_e32 v0, 0x78, v52
	v_lshlrev_b32_e32 v48, 1, v0
	s_lshl_b32 s6, s3, 9
	v_add_u32_e32 v0, s31, v198
	s_add_u32 s6, s27, s6
	v_ashrrev_i32_e32 v1, 31, v0
	s_addc_u32 s7, s28, 0
	v_lshlrev_b64 v[0:1], 12, v[0:1]
	v_lshl_add_u64 v[0:1], s[6:7], 0, v[0:1]
	v_mov_b32_e32 v49, v173
	v_add_u32_e32 v53, s25, v198
	v_lshl_add_u64 v[8:9], v[0:1], 0, v[48:49]
	v_add_u32_e32 v0, 0x4020, v53
	v_ashrrev_i32_e32 v1, 31, v0
	v_lshlrev_b64 v[0:1], 12, v[0:1]
	v_lshl_add_u64 v[4:5], s[6:7], 0, v[0:1]
	global_load_dwordx4 v[0:3], v[8:9], off offset:256
	v_ashrrev_i32_e32 v199, 3, v162
	s_lshl_b32 s8, s3, 7
	v_add_u32_e32 v16, s31, v199
	s_add_u32 s8, s29, s8
	v_ashrrev_i32_e32 v17, 31, v16
	v_lshlrev_b32_e32 v72, 4, v162
	s_addc_u32 s9, s30, 0
	v_lshlrev_b64 v[16:17], 10, v[16:17]
	v_lshl_add_u64 v[12:13], v[4:5], 0, v[48:49]
	v_lshl_add_u64 v[16:17], s[8:9], 0, v[16:17]
	v_and_b32_e32 v50, 0x70, v72
	v_mov_b32_e32 v51, v173
	global_load_dwordx4 v[4:7], v[12:13], off offset:256
	v_lshl_add_u64 v[16:17], v[16:17], 0, v[50:51]
	global_load_dwordx4 v[8:11], v[8:9], off
	v_and_b32_e32 v20, 0xfffff0, v198
	global_load_dwordx4 v[12:15], v[12:13], off
	v_lshlrev_b32_e32 v21, 1, v198
	global_load_dwordx4 v[16:19], v[16:17], off
	v_and_or_b32 v20, v21, 8, v20
	v_lshrrev_b32_e32 v21, 1, v198
	v_lshrrev_b32_e32 v20, 1, v20
	v_bfe_u32 v22, v52, 5, 2
	v_and_b32_e32 v23, 3, v198
	v_or_b32_e32 v20, v20, v22
	v_and_or_b32 v21, v21, 4, v23
	v_lshlrev_b32_e32 v20, 9, v20
	v_lshlrev_b32_e32 v21, 6, v21
	v_and_b32_e32 v23, 48, v48
	v_or3_b32 v20, v20, v21, v23
	v_add_u32_e32 v200, 32, v198
	v_and_b32_e32 v24, 0xfffff0, v200
	v_lshlrev_b32_e32 v25, 1, v200
	v_add_u32_e32 v201, 0, v20
	v_and_or_b32 v24, v25, 8, v24
	s_waitcnt vmcnt(0)
	v_lshrrev_b32_e32 v24, 1, v24
	v_or_b32_e32 v22, v24, v22
	v_lshlrev_b32_e32 v22, 9, v22
	v_or3_b32 v21, v22, v21, v23
	v_add_u32_e32 v202, 0, v21
	s_add_i32 s31, 0, 0x10000
	v_and_b32_e32 v74, 63, v162
	v_mov_b32_e32 v77, 0xf149f2ca
	v_lshl_add_u64 v[180:181], s[6:7], 0, v[48:49]
	v_lshl_add_u64 v[182:183], s[8:9], 0, v[50:51]
	v_mov_b32_e32 v187, 0
	s_waitcnt vmcnt(4)
	ds_write_b128 v201, v[0:3]
	v_lshlrev_b32_e32 v0, 8, v198
	v_and_b32_e32 v1, 0xf0, v162
	v_bitop3_b32 v0, v48, v0, v1 bitop3:0xde
	v_add_u32_e32 v203, 0, v0
	v_lshlrev_b32_e32 v0, 8, v200
	v_bitop3_b32 v0, v48, v0, v1 bitop3:0xde
	v_add_u32_e32 v204, 0, v0
	v_lshlrev_b32_e32 v0, 7, v199
	v_and_b32_e32 v1, 0x70, v162
	v_bitop3_b32 v73, v50, v0, v1 bitop3:0xde
	v_add_u32_e32 v0, s31, v73
	v_add_u32_e32 v222, 0, v73
	s_waitcnt vmcnt(3)
	ds_write_b128 v202, v[4:7]
	v_add_u32_e32 v223, 0x12000, v222
	s_waitcnt vmcnt(2)
	v_lshrrev_b32_e32 v206, 4, v188
	v_and_b32_e32 v207, 0x13, v206
	v_and_b32_e32 v208, 4, v206
	v_lshl_or_b32 v207, v208, 1, v207
	v_and_b32_e32 v208, 8, v206
	v_lshrrev_b32_e32 v208, 1, v208
	v_or_b32_e32 v207, v207, v208
	v_and_b32_e32 v208, 15, v207
	v_and_b32_e32 v209, 15, v188
	v_xor_b32_e32 v208, v208, v209
	v_lshlrev_b32_e32 v208, 4, v208
	v_lshl_or_b32 v203, v207, 8, v208
	v_add_u32_e32 v204, 0x2000, v203
	v_lshrrev_b32_e32 v206, 3, v188
	v_and_b32_e32 v207, 0x33, v206
	v_and_b32_e32 v208, 4, v206
	v_lshl_or_b32 v207, v208, 1, v207
	v_and_b32_e32 v208, 8, v206
	v_lshrrev_b32_e32 v208, 1, v208
	v_or_b32_e32 v207, v207, v208
	v_bfe_u32 v208, v207, 1, 3
	v_and_b32_e32 v209, 7, v188
	v_xor_b32_e32 v208, v208, v209
	v_lshlrev_b32_e32 v208, 4, v208
	v_lshl_or_b32 v222, v207, 7, v208
	v_add_u32_e32 v0, s31, v222
	ds_write_b128 v203, v[8:11] offset:32768
	v_lshlrev_b32_e32 v8, 8, v184
	v_and_b32_e32 v9, 0xf0, v72
	s_waitcnt vmcnt(1)
	ds_write_b128 v204, v[12:15] offset:32768
	s_waitcnt vmcnt(0)
	ds_write_b128 v0, v[16:19]
	v_bitop3_b32 v0, v172, v8, v9 bitop3:0xde
	v_add_u32_e32 v205, 0, v0
	s_waitcnt lgkmcnt(0)
	s_barrier
; __device__ __forceinline__ int v_st(int k, int c) { const int kk = (k & ~0xC) | ((k & 4) << 1) | ((k & 8) >> 1); return ((kk >> 3) * 4 + (c >> 5)) * 512 + ((kk & 7) * 32 + (c & 31)) * 2; }
; __device__ __forceinline__ int v_rd_base(int lane) { return ((lane & 3) << 3) | (((lane >> 2) & 3) << 6) | (((lane >> 4) & 1) << 5) | (((lane >> 5) & 1) << 8); }
; #define SLOAD(j) do { const int r0_ = TROW(j); const bf16_t* a_ = KVh + (size_t)(r0_ + sr) * LDKV + sc; const bf16_t* b_ = KVh + (size_t)(r0_ + 32 + sr) * LDKV + sc; \
;     vs0 = ld8(a_ + 128); vs1 = ld8(b_ + 128); ks0 = ld8(a_); ks1 = ld8(b_); kp0 = ld8(KPh + (size_t)(r0_ + pr) * LDKP + pc); } while (0)
; #define SWRITE(b) do { *(bf16x8*)(V_lds + (b) * SHM_V + vst0) = vs0; *(bf16x8*)(V_lds + (b) * SHM_V + vst1) = vs1; const int kc = sc * 2; \
;     *(bf16x8*)(KN_lds + (b) * SHM_KN + KSWZ(sr, kc)) = ks0; *(bf16x8*)(KN_lds + (b) * SHM_KN + KSWZ(32 + sr, kc)) = ks1; \
;     *(bf16x8*)(KP_lds + (b) * SHM_KP + KPSWZ(pr, pc * 2)) = kp0; } while (0)
; #define SWAIT() asm volatile("s_waitcnt vmcnt(0)" ::: "memory")
; __device__ __forceinline__ void attn_unit(const bf16_t* __restrict__ Qb, const bf16_t* __restrict__ KV, const bf16_t* __restrict__ KP, bf16_t* __restrict__ Ob, ...
;     ...
;   const int sr = tid >> 4, sc = (tid & 15) * 8, vst0 = v_st(sr, sc), vst1 = v_st(32 + sr, sc);
;   const int pr = tid >> 3, pc = (tid & 7) * 8;
;   const int vb0 = (int)(uintptr_t)V_lds + v_rd_base(lane);
;   bf16x8 vs0, vs1, ks0, ks1, kp0;
;   const bf16_t* KVh = KV + h * 256; const bf16_t* KPh = KP + h * QKR;
;     ...
;   f32x16 pA0, pA1, pB0, pB1; float mnA, mnB, alA, alB; bf16x8 pa0, pa1, pa2, pa3;
;   SLOAD(0); SWAIT(); SWRITE(0); __syncthreads();
;   qkt(pA0, pA1, KN_lds, KP_lds, qr, r32, hi); partialSM(pA0, pA1, m_reg, mnA, alA);
;   SLOAD(1);
;   SWAIT(); SWRITE(1); __syncthreads();
	s_movk_i32 s49, 0x1000
	s_waitcnt vmcnt(0)
	v_readfirstlane_b32 s40, v188
	s_nop 1
	s_lshr_b32 s40, s40, 6
	s_lshr_b32 s41, s40, 2
	v_and_b32_e32 v187, 0x3fffffc0, v188
	v_lshlrev_b32_e32 v179, 2, v187
	v_add_u32_e32 v179, 0x14000, v179
	v_lshl_add_u32 v186, v184, 2, v179
	v_and_b32_e32 v187, 63, v188
	v_cmp_gt_u32_e64 s[6:7], 32, v187
	s_add_i32 s31, s25, 0x4000
	s_lshl_b32 s44, s3, 9
	s_add_u32 s47, s27, s44
	s_addc_u32 s63, s28, 0
	s_lshl_b32 s44, s3, 7
	s_add_u32 s60, s29, s44
	s_addc_u32 s61, s30, 0
	v_lshrrev_b32_e32 v180, 4, v188
	v_lshlrev_b32_e32 v180, 12, v180
	v_and_b32_e32 v181, 15, v188
	v_lshl_or_b32 v180, v181, 4, v180
	v_lshrrev_b32_e32 v181, 3, v188
	v_lshlrev_b32_e32 v181, 10, v181
	v_and_b32_e32 v182, 7, v188
	v_lshl_or_b32 v181, v182, 4, v181
	v_lshlrev_b32_e32 v250, 8, v184
	v_and_b32_e32 v251, 15, v184
	v_lshlrev_b32_e32 v251, 4, v251
	v_or_b32_e32 v249, 0, v172
	v_xor_b32_e32 v249, v249, v251
	v_or_b32_e32 v249, v249, v250
	v_add_u32_e32 v160, 0x8000, v249
	v_or_b32_e32 v249, 32, v172
	v_xor_b32_e32 v249, v249, v251
	v_or_b32_e32 v249, v249, v250
	v_add_u32_e32 v161, 0x8000, v249
	v_or_b32_e32 v249, 64, v172
	v_xor_b32_e32 v249, v249, v251
	v_or_b32_e32 v249, v249, v250
	v_add_u32_e32 v162, 0x8000, v249
	v_or_b32_e32 v249, 96, v172
	v_xor_b32_e32 v249, v249, v251
	v_or_b32_e32 v249, v249, v250
	v_add_u32_e32 v163, 0x8000, v249
	v_or_b32_e32 v249, 128, v172
	v_xor_b32_e32 v249, v249, v251
	v_or_b32_e32 v249, v249, v250
	v_add_u32_e32 v164, 0x8000, v249
	v_or_b32_e32 v249, 160, v172
	v_xor_b32_e32 v249, v249, v251
	v_or_b32_e32 v249, v249, v250
	v_add_u32_e32 v165, 0x8000, v249
	v_or_b32_e32 v249, 192, v172
	v_xor_b32_e32 v249, v249, v251
	v_or_b32_e32 v249, v249, v250
	v_add_u32_e32 v166, 0x8000, v249
	v_or_b32_e32 v249, 224, v172
	v_xor_b32_e32 v249, v249, v251
	v_or_b32_e32 v249, v249, v250
	v_add_u32_e32 v167, 0x8000, v249
	v_lshlrev_b32_e32 v250, 7, v184
	v_lshrrev_b32_e32 v251, 1, v184
	v_and_b32_e32 v251, 7, v251
	v_lshlrev_b32_e32 v251, 4, v251
	v_or_b32_e32 v249, 0, v172
	v_xor_b32_e32 v249, v249, v251
	v_or_b32_e32 v249, v249, v250
	v_add_u32_e32 v168, 0x10000, v249
	v_or_b32_e32 v249, 32, v172
	v_xor_b32_e32 v249, v249, v251
	v_or_b32_e32 v249, v249, v250
	v_add_u32_e32 v169, 0x10000, v249
	v_or_b32_e32 v249, 64, v172
	v_xor_b32_e32 v249, v249, v251
	v_or_b32_e32 v249, v249, v250
	v_add_u32_e32 v170, 0x10000, v249
	v_or_b32_e32 v249, 96, v172
	v_xor_b32_e32 v249, v249, v251
	v_or_b32_e32 v249, v249, v250
	v_add_u32_e32 v171, 0x10000, v249
	v_and_b32_e32 v187, 63, v188
	v_lshlrev_b32_e32 v249, 3, v187
	v_lshlrev_b32_e32 v250, 4, v187
	v_and_b32_e32 v250, 0xc0, v250
	v_and_or_b32 v250, v249, 24, v250
	v_lshlrev_b32_e32 v251, 1, v187
	v_and_b32_e32 v251, 32, v251
	v_and_b32_e32 v249, 0x100, v249
	v_or3_b32 v174, v250, v251, v249
	v_mov_b32_e32 v244, v201
	v_add_u32_e32 v246, 0xc000, v203
	v_add_u32_e32 v248, 0x12000, v222
	v_add_u32_e32 v245, 0x4000, v201
	v_add_u32_e32 v247, 0x8000, v203
	v_add_u32_e32 v183, 0x10000, v222
	v_mov_b32_e32 v175, 0
	s_mov_b32 s62, 0
	s_mov_b32 s64, 0x42800000
	v_mov_b32_e32 v176, 0
	v_mov_b32_e32 v0, 0
	v_mov_b32_e32 v1, 0
	v_mov_b32_e32 v2, 0
	v_mov_b32_e32 v3, 0
	v_mov_b32_e32 v4, 0
	v_mov_b32_e32 v5, 0
	v_mov_b32_e32 v6, 0
	v_mov_b32_e32 v7, 0
	v_mov_b32_e32 v8, 0
	v_mov_b32_e32 v9, 0
	v_mov_b32_e32 v10, 0
	v_mov_b32_e32 v11, 0
	v_mov_b32_e32 v12, 0
	v_mov_b32_e32 v13, 0
	v_mov_b32_e32 v14, 0
	v_mov_b32_e32 v15, 0
	v_mov_b32_e32 v16, 0
	v_mov_b32_e32 v17, 0
	v_mov_b32_e32 v18, 0
	v_mov_b32_e32 v19, 0
	v_mov_b32_e32 v20, 0
	v_mov_b32_e32 v21, 0
	v_mov_b32_e32 v22, 0
	v_mov_b32_e32 v23, 0
	v_mov_b32_e32 v24, 0
	v_mov_b32_e32 v25, 0
	v_mov_b32_e32 v26, 0
	v_mov_b32_e32 v27, 0
	v_mov_b32_e32 v28, 0
	v_mov_b32_e32 v29, 0
	v_mov_b32_e32 v30, 0
	v_mov_b32_e32 v31, 0
	v_mov_b32_e32 v32, 0
	v_mov_b32_e32 v33, 0
	v_mov_b32_e32 v34, 0
	v_mov_b32_e32 v35, 0
	v_mov_b32_e32 v36, 0
	v_mov_b32_e32 v37, 0
	v_mov_b32_e32 v38, 0
	v_mov_b32_e32 v39, 0
	v_mov_b32_e32 v40, 0
	v_mov_b32_e32 v41, 0
	v_mov_b32_e32 v42, 0
	v_mov_b32_e32 v43, 0
	v_mov_b32_e32 v44, 0
	v_mov_b32_e32 v45, 0
	v_mov_b32_e32 v46, 0
	v_mov_b32_e32 v47, 0
	v_mov_b32_e32 v48, 0
	v_mov_b32_e32 v49, 0
	v_mov_b32_e32 v50, 0
	v_mov_b32_e32 v51, 0
	v_mov_b32_e32 v52, 0
	v_mov_b32_e32 v53, 0
	v_mov_b32_e32 v54, 0
	v_mov_b32_e32 v55, 0
	v_mov_b32_e32 v56, 0
	v_mov_b32_e32 v57, 0
	v_mov_b32_e32 v58, 0
	v_mov_b32_e32 v59, 0
	v_mov_b32_e32 v60, 0
	v_mov_b32_e32 v61, 0
	v_mov_b32_e32 v62, 0
	v_mov_b32_e32 v63, 0
	v_mov_b32_e32 v144, 0
	v_mov_b32_e32 v145, 0
	v_mov_b32_e32 v146, 0
	v_mov_b32_e32 v147, 0
	v_mov_b32_e32 v148, 0
	v_mov_b32_e32 v149, 0
	v_mov_b32_e32 v150, 0
	v_mov_b32_e32 v151, 0
	v_mov_b32_e32 v152, 0
	v_mov_b32_e32 v153, 0
	v_mov_b32_e32 v154, 0
	v_mov_b32_e32 v155, 0
	v_mov_b32_e32 v156, 0
	v_mov_b32_e32 v157, 0
	v_mov_b32_e32 v158, 0
	v_mov_b32_e32 v159, 0
	s_mov_b32 s35, 0
	s_mov_b32 s11, 0
	s_add_i32 s36, s31, 64
	s_mov_b32 s37, s31
	s_lshl_b32 s44, s36, 12
	s_add_u32 s50, s47, s44
	s_addc_u32 s51, s63, 0
	s_add_u32 s52, s50, 0x20000
	s_addc_u32 s53, s51, 0
	s_lshl_b32 s44, s37, 12
	s_add_u32 s54, s47, s44
	s_addc_u32 s55, s63, 0
	s_add_u32 s56, s54, 0x20000
	s_addc_u32 s57, s55, 0
	s_lshl_b32 s44, s36, 10
	s_add_u32 s58, s60, s44
	s_addc_u32 s59, s61, 0
	global_load_dwordx4 v[232:235], v180, s[50:51]
	global_load_dwordx4 v[236:239], v180, s[52:53]
	global_load_dwordx4 v[224:227], v180, s[54:55] offset:256
	global_load_dwordx4 v[228:231], v180, s[56:57] offset:256
	global_load_dwordx4 v[240:243], v181, s[58:59]
	s_cmp_eq_u32 s41, 0
	s_cbranch_scc1 .Lpp_ga
; #define SBAR() __builtin_amdgcn_sched_barrier(0)
; #define SLOAD(j) do { const int r0_ = TROW(j); const bf16_t* a_ = KVh + (size_t)(r0_ + sr) * LDKV + sc; const bf16_t* b_ = KVh + (size_t)(r0_ + 32 + sr) * LDKV + sc; \
;     vs0 = ld8(a_ + 128); vs1 = ld8(b_ + 128); ks0 = ld8(a_); ks1 = ld8(b_); kp0 = ld8(KPh + (size_t)(r0_ + pr) * LDKP + pc); } while (0)
; #define SWRITE(b) do { *(bf16x8*)(V_lds + (b) * SHM_V + vst0) = vs0; *(bf16x8*)(V_lds + (b) * SHM_V + vst1) = vs1; const int kc = sc * 2; \
;     *(bf16x8*)(KN_lds + (b) * SHM_KN + KSWZ(sr, kc)) = ks0; *(bf16x8*)(KN_lds + (b) * SHM_KN + KSWZ(32 + sr, kc)) = ks1; \
;     *(bf16x8*)(KP_lds + (b) * SHM_KP + KPSWZ(pr, pc * 2)) = kp0; } while (0)
; __device__ __forceinline__ void qkt(f32x16& p0, f32x16& p1, const char* Kn, const char* Kp, const bf16x8* qr, int r32, int hi) {
;   p0 = f32x16{}; p1 = f32x16{};
; #pragma unroll
;   for (int d0 = 0; d0 < 8; ++d0) { int cb = (d0 * 16 + hi * 8) * 2;
;     bf16x8 b0 = *reinterpret_cast<const bf16x8*>(Kn + KSWZ(r32, cb));
;     bf16x8 b1 = *reinterpret_cast<const bf16x8*>(Kn + KSWZ(32 + r32, cb));
;     p0 = __builtin_amdgcn_mfma_f32_32x32x16_bf16(b0, qr[d0], p0, 0, 0, 0);
;     p1 = __builtin_amdgcn_mfma_f32_32x32x16_bf16(b1, qr[d0], p1, 0, 0, 0); }
; #pragma unroll
;   for (int d1 = 0; d1 < 4; ++d1) { int cb = (d1 * 16 + hi * 8) * 2;
;     bf16x8 b0 = *reinterpret_cast<const bf16x8*>(Kp + KPSWZ(r32, cb));
;     bf16x8 b1 = *reinterpret_cast<const bf16x8*>(Kp + KPSWZ(32 + r32, cb));
;     p0 = __builtin_amdgcn_mfma_f32_32x32x16_bf16(b0, qr[8 + d1], p0, 0, 0, 0);
;     p1 = __builtin_amdgcn_mfma_f32_32x32x16_bf16(b1, qr[8 + d1], p1, 0, 0, 0); }
; }
; __device__ __forceinline__ void attn_unit(const bf16_t* __restrict__ Qb, const bf16_t* __restrict__ KV, const bf16_t* __restrict__ KP, bf16_t* __restrict__ Ob, ...
;     ...
;   SLOAD(0); SWAIT(); SWRITE(0); __syncthreads();
;   qkt(pA0, pA1, KN_lds, KP_lds, qr, r32, hi); partialSM(pA0, pA1, m_reg, mnA, alA);
;   SLOAD(1);
;   SWAIT(); SWRITE(1); __syncthreads();
;   for (int j = 1; j + 1 < NT; j += 2) {
;     SBAR(); qkt(pB0, pB1, KN_lds + SHM_KN, KP_lds + SHM_KP, qr, r32, hi);
;     finishSM(pA0, pA1, alA, l_reg, pa0, pa1, pa2, pa3); SBAR();
;     SLOAD(j + 1); SBAR();
;     pv_d0(o, vb0, pa0, pa1, pa2, pa3); partialSM(pB0, pB1, m_reg, mnB, alB);
;     __syncthreads(); SWAIT(); SWRITE(0);
;     RESC(alB); __syncthreads();
	s_add_i32 s36, s35, 2
	s_min_u32 s36, s36, 67
	s_lshl_b32 s44, s36, 6
	s_add_i32 s45, s31, s44
	s_add_i32 s46, s24, s44
	s_add_i32 s46, s46, 0xffffff00
	s_cmp_lt_u32 s36, 4
	s_cselect_b32 s36, s45, s46
	s_add_i32 s37, s35, 1
	s_min_u32 s37, s37, 67
	s_lshl_b32 s44, s37, 6
	s_add_i32 s45, s31, s44
	s_add_i32 s46, s24, s44
	s_add_i32 s46, s46, 0xffffff00
	s_cmp_lt_u32 s37, 4
	s_cselect_b32 s37, s45, s46
	s_add_i32 s35, s35, 1
	s_lshl_b32 s44, s36, 12
	s_add_u32 s50, s47, s44
	s_addc_u32 s51, s63, 0
	s_add_u32 s52, s50, 0x20000
	s_addc_u32 s53, s51, 0
	s_lshl_b32 s44, s37, 12
	s_add_u32 s54, s47, s44
	s_addc_u32 s55, s63, 0
	s_add_u32 s56, s54, 0x20000
	s_addc_u32 s57, s55, 0
	s_lshl_b32 s44, s36, 10
	s_add_u32 s58, s60, s44
	s_addc_u32 s59, s61, 0
	s_waitcnt vmcnt(0)
	ds_write_b128 v246, v[232:235]
	ds_write_b128 v246, v[236:239] offset:8192
	ds_write_b128 v248, v[240:243]
	ds_write_b128 v244, v[224:227]
	ds_write_b128 v244, v[228:231] offset:8192
	global_load_dwordx4 v[232:235], v180, s[50:51]
	global_load_dwordx4 v[236:239], v180, s[52:53]
	global_load_dwordx4 v[224:227], v180, s[54:55] offset:256
	global_load_dwordx4 v[228:231], v180, s[56:57] offset:256
	global_load_dwordx4 v[240:243], v181, s[58:59]
	v_swap_b32 v244, v245
	v_swap_b32 v246, v247
	v_swap_b32 v248, v183
	ds_read_b128 v[192:195], v160
	ds_read_b128 v[196:199], v160 offset:8192
	ds_read_b128 v[200:203], v161
	ds_read_b128 v[204:207], v161 offset:8192
	ds_read_b128 v[208:211], v162
	ds_read_b128 v[212:215], v162 offset:8192
	ds_read_b128 v[216:219], v163
	ds_read_b128 v[220:223], v163 offset:8192
	s_waitcnt lgkmcnt(6)
	v_mfma_f32_32x32x16_bf16 v[80:95], v[192:195], v[136:139], 0
	v_mfma_f32_32x32x16_bf16 v[64:79], v[196:199], v[136:139], 0
	s_add_i32 s36, s35, 2
	s_min_u32 s36, s36, 67
	s_lshl_b32 s44, s36, 6
	ds_read_b128 v[192:195], v164
	ds_read_b128 v[196:199], v164 offset:8192
	s_waitcnt lgkmcnt(6)
	v_mfma_f32_32x32x16_bf16 v[80:95], v[200:203], v[132:135], v[80:95]
	v_mfma_f32_32x32x16_bf16 v[64:79], v[204:207], v[132:135], v[64:79]
	s_add_i32 s45, s31, s44
	s_add_i32 s46, s24, s44
	s_add_i32 s46, s46, 0xffffff00
	ds_read_b128 v[200:203], v165
	ds_read_b128 v[204:207], v165 offset:8192
	s_waitcnt lgkmcnt(6)
	v_mfma_f32_32x32x16_bf16 v[80:95], v[208:211], v[128:131], v[80:95]
	v_mfma_f32_32x32x16_bf16 v[64:79], v[212:215], v[128:131], v[64:79]
	s_cmp_lt_u32 s36, 4
	s_cselect_b32 s36, s45, s46
	s_add_i32 s37, s35, 1
	ds_read_b128 v[208:211], v166
	ds_read_b128 v[212:215], v166 offset:8192
	s_waitcnt lgkmcnt(6)
	v_mfma_f32_32x32x16_bf16 v[80:95], v[216:219], v[124:127], v[80:95]
	v_mfma_f32_32x32x16_bf16 v[64:79], v[220:223], v[124:127], v[64:79]
	s_min_u32 s37, s37, 67
	s_lshl_b32 s44, s37, 6
	s_add_i32 s45, s31, s44
	ds_read_b128 v[216:219], v167
	ds_read_b128 v[220:223], v167 offset:8192
	s_waitcnt lgkmcnt(6)
	v_mfma_f32_32x32x16_bf16 v[80:95], v[192:195], v[120:123], v[80:95]
	v_mfma_f32_32x32x16_bf16 v[64:79], v[196:199], v[120:123], v[64:79]
	s_add_i32 s46, s24, s44
	s_add_i32 s46, s46, 0xffffff00
	s_cmp_lt_u32 s37, 4
	ds_read_b128 v[192:195], v168
	ds_read_b128 v[196:199], v168 offset:4096
	s_waitcnt lgkmcnt(6)
	v_mfma_f32_32x32x16_bf16 v[80:95], v[200:203], v[140:143], v[80:95]
	v_mfma_f32_32x32x16_bf16 v[64:79], v[204:207], v[140:143], v[64:79]
	s_cselect_b32 s37, s45, s46
	s_add_i32 s35, s35, 1
	s_lshl_b32 s44, s36, 12
	ds_read_b128 v[200:203], v169
	ds_read_b128 v[204:207], v169 offset:4096
	s_waitcnt lgkmcnt(6)
	v_mfma_f32_32x32x16_bf16 v[80:95], v[208:211], v[116:119], v[80:95]
	v_mfma_f32_32x32x16_bf16 v[64:79], v[212:215], v[116:119], v[64:79]
	s_add_u32 s50, s47, s44
	s_addc_u32 s51, s63, 0
	s_add_u32 s52, s50, 0x20000
	ds_read_b128 v[208:211], v170
	ds_read_b128 v[212:215], v170 offset:4096
	s_waitcnt lgkmcnt(6)
	v_mfma_f32_32x32x16_bf16 v[80:95], v[216:219], v[112:115], v[80:95]
	v_mfma_f32_32x32x16_bf16 v[64:79], v[220:223], v[112:115], v[64:79]
	s_addc_u32 s53, s51, 0
	s_lshl_b32 s44, s37, 12
	s_add_u32 s54, s47, s44
	ds_read_b128 v[216:219], v171
	ds_read_b128 v[220:223], v171 offset:4096
	s_waitcnt lgkmcnt(6)
	v_mfma_f32_32x32x16_bf16 v[80:95], v[192:195], v[108:111], v[80:95]
	v_mfma_f32_32x32x16_bf16 v[64:79], v[196:199], v[108:111], v[64:79]
	s_addc_u32 s55, s63, 0
	s_add_u32 s56, s54, 0x20000
	s_addc_u32 s57, s55, 0
	s_waitcnt lgkmcnt(4)
	v_mfma_f32_32x32x16_bf16 v[80:95], v[200:203], v[104:107], v[80:95]
	v_mfma_f32_32x32x16_bf16 v[64:79], v[204:207], v[104:107], v[64:79]
	s_lshl_b32 s44, s36, 10
	s_add_u32 s58, s60, s44
	s_addc_u32 s59, s61, 0
	s_waitcnt lgkmcnt(2)
	v_mfma_f32_32x32x16_bf16 v[80:95], v[208:211], v[100:103], v[80:95]
	v_mfma_f32_32x32x16_bf16 v[64:79], v[212:215], v[100:103], v[64:79]
	s_waitcnt lgkmcnt(0)
	v_mfma_f32_32x32x16_bf16 v[80:95], v[216:219], v[96:99], v[80:95]
	v_mfma_f32_32x32x16_bf16 v[64:79], v[220:223], v[96:99], v[64:79]
	s_nop 7
	s_nop 7
	s_nop 7
; #define SBAR() __builtin_amdgcn_sched_barrier(0)
; #define SLOAD(j) do { const int r0_ = TROW(j); const bf16_t* a_ = KVh + (size_t)(r0_ + sr) * LDKV + sc; const bf16_t* b_ = KVh + (size_t)(r0_ + 32 + sr) * LDKV + sc; \
;     vs0 = ld8(a_ + 128); vs1 = ld8(b_ + 128); ks0 = ld8(a_); ks1 = ld8(b_); kp0 = ld8(KPh + (size_t)(r0_ + pr) * LDKP + pc); } while (0)
; __device__ __forceinline__ void partialSM(f32x16& p0, f32x16& p1, float& m_reg, float& mn, float& alpha) {
;   constexpr float C = SCALE * 1.4426950408889634f;
;   float pmax = p0[0]; for (int r = 1; r < 16; ++r) pmax = fmaxf(pmax, p0[r]); for (int r = 0; r < 16; ++r) pmax = fmaxf(pmax, p1[r]);
;   { auto rr = __builtin_amdgcn_permlane32_swap(__float_as_uint(pmax), __float_as_uint(pmax), false, false);
;     pmax = fmaxf(__uint_as_float(rr[0]), __uint_as_float(rr[1])); }
;   if (__builtin_expect(__all(pmax - m_reg <= THR / SCALE), 1)) { mn = m_reg; alpha = 1.f; }
;   else { mn = fmaxf(m_reg, pmax); alpha = __builtin_amdgcn_exp2f((m_reg - mn) * C); m_reg = mn; }
;   float mnC = -mn * C;
;   for (int r = 0; r < 16; ++r) p0[r] = fmaf(p0[r], C, mnC); for (int r = 0; r < 16; ++r) p1[r] = fmaf(p1[r], C, mnC);
;   for (int r = 0; r < 16; ++r) p0[r] = __builtin_amdgcn_exp2f(p0[r]);
; }
; __device__ __forceinline__ void finishSM(f32x16& p0, f32x16& p1, float alpha, float& l_reg, bf16x8& pa0, bf16x8& pa1, bf16x8& pa2, bf16x8& pa3) {
;   for (int r = 0; r < 16; ++r) p1[r] = __builtin_amdgcn_exp2f(p1[r]);
;   float ps = 0; for (int r = 0; r < 16; ++r) ps += p0[r]; for (int r = 0; r < 16; ++r) ps += p1[r];
;   { auto rr = __builtin_amdgcn_permlane32_swap(__float_as_uint(ps), __float_as_uint(ps), false, false);
;     ps = __uint_as_float(rr[0]) + __uint_as_float(rr[1]); }
;   l_reg = l_reg * alpha + ps;
;     ...
;   PK4(p0, 0, pa0); PK4(p0, 8, pa1); PK4(p1, 0, pa2); PK4(p1, 8, pa3);
;     ...
; }
; __device__ __forceinline__ void attn_unit(const bf16_t* __restrict__ Qb, const bf16_t* __restrict__ KV, const bf16_t* __restrict__ KP, bf16_t* __restrict__ Ob, ...
;     ...
;   for (int j = 1; j + 1 < NT; j += 2) {
;     SBAR(); qkt(pB0, pB1, KN_lds + SHM_KN, KP_lds + SHM_KP, qr, r32, hi);
;     finishSM(pA0, pA1, alA, l_reg, pa0, pa1, pa2, pa3); SBAR();
;     SLOAD(j + 1); SBAR();
;     pv_d0(o, vb0, pa0, pa1, pa2, pa3); partialSM(pB0, pB1, m_reg, mnB, alB);
;     __syncthreads(); SWAIT(); SWRITE(0);
;     RESC(alB); __syncthreads();
.Lpp_loop:
	s_barrier
	v_max3_f32 v250, v80, v81, v82
	v_max3_f32 v250, v250, v83, v84
	v_max3_f32 v250, v250, v85, v86
	v_max3_f32 v250, v250, v87, v88
	v_max3_f32 v250, v250, v89, v90
	v_max3_f32 v250, v250, v91, v92
	v_max3_f32 v250, v250, v93, v94
	v_max3_f32 v250, v250, v95, v64
	v_max3_f32 v250, v250, v65, v66
	v_max3_f32 v250, v250, v67, v68
	v_max3_f32 v250, v250, v69, v70
	v_max3_f32 v250, v250, v71, v72
	v_max3_f32 v250, v250, v73, v74
	v_max3_f32 v250, v250, v75, v76
	v_max3_f32 v250, v250, v77, v78
	v_max3_f32 v250, v250, v79, v79
	v_cmp_lt_f32_e64 vcc, s64, |v250|
	s_waitcnt vmcnt(0)
	ds_write_b128 v246, v[232:235]
	ds_write_b128 v246, v[236:239] offset:8192
	ds_write_b128 v248, v[240:243]
	ds_write_b128 v244, v[224:227]
	ds_write_b128 v244, v[228:231] offset:8192
	global_load_dwordx4 v[232:235], v180, s[50:51]
	global_load_dwordx4 v[236:239], v180, s[52:53]
	global_load_dwordx4 v[224:227], v180, s[54:55] offset:256
	global_load_dwordx4 v[228:231], v180, s[56:57] offset:256
	global_load_dwordx4 v[240:243], v181, s[58:59]
	s_cmp_lg_u32 s62, 0
	s_cbranch_scc1 .Lpp_safe_Ba
	s_cbranch_vccnz .Lpp_sw_Ba
	v_exp_f32_e32 v80, v80
	v_exp_f32_e32 v81, v81
	v_exp_f32_e32 v82, v82
	v_exp_f32_e32 v83, v83
	v_exp_f32_e32 v84, v84
	v_exp_f32_e32 v85, v85
	v_exp_f32_e32 v86, v86
	v_exp_f32_e32 v87, v87
	v_exp_f32_e32 v88, v88
	v_exp_f32_e32 v89, v89
	v_exp_f32_e32 v90, v90
	v_exp_f32_e32 v91, v91
	v_exp_f32_e32 v92, v92
	v_exp_f32_e32 v93, v93
	v_exp_f32_e32 v94, v94
	v_exp_f32_e32 v95, v95
	v_exp_f32_e32 v64, v64
	v_exp_f32_e32 v65, v65
	v_exp_f32_e32 v66, v66
	v_exp_f32_e32 v67, v67
	v_exp_f32_e32 v68, v68
	v_exp_f32_e32 v69, v69
	v_exp_f32_e32 v70, v70
	v_exp_f32_e32 v71, v71
	v_exp_f32_e32 v72, v72
	v_exp_f32_e32 v73, v73
	v_exp_f32_e32 v74, v74
	v_exp_f32_e32 v75, v75
	v_exp_f32_e32 v76, v76
	v_exp_f32_e32 v77, v77
	v_exp_f32_e32 v78, v78
	v_exp_f32_e32 v79, v79
	v_add_f32_e32 v249, v80, v81
	v_add_f32_e32 v250, v82, v83
	v_add_f32_e32 v251, v84, v85
	v_add_f32_e32 v182, v86, v87
	v_add_f32_e32 v249, v88, v249
	v_add_f32_e32 v250, v89, v250
	v_add_f32_e32 v251, v90, v251
	v_add_f32_e32 v182, v91, v182
	v_add_f32_e32 v249, v92, v249
	v_add_f32_e32 v250, v93, v250
	v_add_f32_e32 v251, v94, v251
	v_add_f32_e32 v182, v95, v182
	v_add_f32_e32 v249, v64, v249
	v_add_f32_e32 v250, v65, v250
	v_add_f32_e32 v251, v66, v251
	v_add_f32_e32 v182, v67, v182
	v_add_f32_e32 v249, v68, v249
	v_add_f32_e32 v250, v69, v250
	v_add_f32_e32 v251, v70, v251
	v_add_f32_e32 v182, v71, v182
	v_add_f32_e32 v249, v72, v249
	v_add_f32_e32 v250, v73, v250
	v_add_f32_e32 v251, v74, v251
	v_add_f32_e32 v182, v75, v182
	v_add_f32_e32 v249, v76, v249
	v_add_f32_e32 v250, v77, v250
	v_add_f32_e32 v251, v78, v251
	v_add_f32_e32 v182, v79, v182
	v_add_f32_e32 v249, v249, v250
	v_add_f32_e32 v251, v251, v182
	v_add_f32_e32 v249, v249, v251
	v_add_f32_e32 v176, v176, v249
	v_cvt_pk_bf16_f32 v144, v80, v81
	v_cvt_pk_bf16_f32 v145, v82, v83
	v_cvt_pk_bf16_f32 v146, v84, v85
	v_cvt_pk_bf16_f32 v147, v86, v87
	v_cvt_pk_bf16_f32 v148, v88, v89
	v_cvt_pk_bf16_f32 v149, v90, v91
	v_cvt_pk_bf16_f32 v150, v92, v93
	v_cvt_pk_bf16_f32 v151, v94, v95
	v_cvt_pk_bf16_f32 v152, v64, v65
	v_cvt_pk_bf16_f32 v153, v66, v67
	v_cvt_pk_bf16_f32 v154, v68, v69
	v_cvt_pk_bf16_f32 v155, v70, v71
	v_cvt_pk_bf16_f32 v156, v72, v73
	v_cvt_pk_bf16_f32 v157, v74, v75
	v_cvt_pk_bf16_f32 v158, v76, v77
	v_cvt_pk_bf16_f32 v159, v78, v79
.Lpp_send_Ba:
	s_add_i32 s11, s11, 1
	ds_read_b128 v[192:195], v160 offset:16384
	ds_read_b128 v[196:199], v160 offset:24576
	ds_read_b128 v[200:203], v161 offset:16384
	ds_read_b128 v[204:207], v161 offset:24576
	ds_read_b128 v[208:211], v162 offset:16384
	ds_read_b128 v[212:215], v162 offset:24576
	ds_read_b128 v[216:219], v163 offset:16384
	ds_read_b128 v[220:223], v163 offset:24576
	s_waitcnt lgkmcnt(6)
	v_mfma_f32_32x32x16_bf16 v[80:95], v[192:195], v[136:139], 0
	v_mfma_f32_32x32x16_bf16 v[64:79], v[196:199], v[136:139], 0
	s_add_i32 s36, s35, 2
	s_min_u32 s36, s36, 67
	s_lshl_b32 s44, s36, 6
	ds_read_b128 v[192:195], v164 offset:16384
	ds_read_b128 v[196:199], v164 offset:24576
	s_waitcnt lgkmcnt(6)
	v_mfma_f32_32x32x16_bf16 v[80:95], v[200:203], v[132:135], v[80:95]
	v_mfma_f32_32x32x16_bf16 v[64:79], v[204:207], v[132:135], v[64:79]
	s_add_i32 s45, s31, s44
	s_add_i32 s46, s24, s44
	s_add_i32 s46, s46, 0xffffff00
	ds_read_b128 v[200:203], v165 offset:16384
	ds_read_b128 v[204:207], v165 offset:24576
	s_waitcnt lgkmcnt(6)
	v_mfma_f32_32x32x16_bf16 v[80:95], v[208:211], v[128:131], v[80:95]
	v_mfma_f32_32x32x16_bf16 v[64:79], v[212:215], v[128:131], v[64:79]
	s_cmp_lt_u32 s36, 4
	s_cselect_b32 s36, s45, s46
	s_add_i32 s37, s35, 1
	ds_read_b128 v[208:211], v166 offset:16384
	ds_read_b128 v[212:215], v166 offset:24576
	s_waitcnt lgkmcnt(6)
	v_mfma_f32_32x32x16_bf16 v[80:95], v[216:219], v[124:127], v[80:95]
	v_mfma_f32_32x32x16_bf16 v[64:79], v[220:223], v[124:127], v[64:79]
	s_min_u32 s37, s37, 67
	s_lshl_b32 s44, s37, 6
	s_add_i32 s45, s31, s44
	ds_read_b128 v[216:219], v167 offset:16384
	ds_read_b128 v[220:223], v167 offset:24576
	s_waitcnt lgkmcnt(6)
	v_mfma_f32_32x32x16_bf16 v[80:95], v[192:195], v[120:123], v[80:95]
	v_mfma_f32_32x32x16_bf16 v[64:79], v[196:199], v[120:123], v[64:79]
	s_add_i32 s46, s24, s44
	s_add_i32 s46, s46, 0xffffff00
	s_cmp_lt_u32 s37, 4
	ds_read_b128 v[192:195], v168 offset:8192
	ds_read_b128 v[196:199], v168 offset:12288
	s_waitcnt lgkmcnt(6)
	v_mfma_f32_32x32x16_bf16 v[80:95], v[200:203], v[140:143], v[80:95]
	v_mfma_f32_32x32x16_bf16 v[64:79], v[204:207], v[140:143], v[64:79]
	s_cselect_b32 s37, s45, s46
	s_add_i32 s35, s35, 1
	s_lshl_b32 s44, s36, 12
	ds_read_b128 v[200:203], v169 offset:8192
	ds_read_b128 v[204:207], v169 offset:12288
	s_waitcnt lgkmcnt(6)
; #define SBAR() __builtin_amdgcn_sched_barrier(0)
; #define SLOAD(j) do { const int r0_ = TROW(j); const bf16_t* a_ = KVh + (size_t)(r0_ + sr) * LDKV + sc; const bf16_t* b_ = KVh + (size_t)(r0_ + 32 + sr) * LDKV + sc; \
;     vs0 = ld8(a_ + 128); vs1 = ld8(b_ + 128); ks0 = ld8(a_); ks1 = ld8(b_); kp0 = ld8(KPh + (size_t)(r0_ + pr) * LDKP + pc); } while (0)
; template <int D0> __device__ __forceinline__ void pv_one(f32x16& od, int vb, bf16x8 pa0, bf16x8 pa1, bf16x8 pa2, bf16x8 pa3) {
;   const s16x4 l0 = tr_read<v_rd_off(D0, 0, 0)>(vb), h0 = tr_read<v_rd_off(D0, 0, 1)>(vb), l1 = tr_read<v_rd_off(D0, 1, 0)>(vb), h1 = tr_read<v_rd_off(D0, 1, 1)>(vb);
;   const s16x4 l2 = tr_read<v_rd_off(D0, 2, 0)>(vb), h2 = tr_read<v_rd_off(D0, 2, 1)>(vb), l3 = tr_read<v_rd_off(D0, 3, 0)>(vb), h3 = tr_read<v_rd_off(D0, 3, 1)>(vb);
;   asm volatile("s_waitcnt lgkmcnt(0)" ::: "memory"); SBAR();
;     ...
;   od = __builtin_amdgcn_mfma_f32_32x32x16_bf16(pa0, PK(l0, h0), od, 0, 0, 0);
;   od = __builtin_amdgcn_mfma_f32_32x32x16_bf16(pa1, PK(l1, h1), od, 0, 0, 0);
;   od = __builtin_amdgcn_mfma_f32_32x32x16_bf16(pa2, PK(l2, h2), od, 0, 0, 0);
;   od = __builtin_amdgcn_mfma_f32_32x32x16_bf16(pa3, PK(l3, h3), od, 0, 0, 0);
;     ...
; }
; __device__ __forceinline__ void pv_d0(f32x16* o, int vb, bf16x8 pa0, bf16x8 pa1, bf16x8 pa2, bf16x8 pa3) {
;   pv_one<0>(o[0], vb, pa0, pa1, pa2, pa3); pv_one<1>(o[1], vb, pa0, pa1, pa2, pa3); pv_one<2>(o[2], vb, pa0, pa1, pa2, pa3); pv_one<3>(o[3], vb, pa0, pa1, pa2, pa3);
; }
; __device__ __forceinline__ void attn_unit(const bf16_t* __restrict__ Qb, const bf16_t* __restrict__ KV, const bf16_t* __restrict__ KP, bf16_t* __restrict__ Ob, ...
;     ...
;   for (int j = 1; j + 1 < NT; j += 2) {
;     SBAR(); qkt(pB0, pB1, KN_lds + SHM_KN, KP_lds + SHM_KP, qr, r32, hi);
;     finishSM(pA0, pA1, alA, l_reg, pa0, pa1, pa2, pa3); SBAR();
;     SLOAD(j + 1); SBAR();
;     pv_d0(o, vb0, pa0, pa1, pa2, pa3); partialSM(pB0, pB1, m_reg, mnB, alB);
;     __syncthreads(); SWAIT(); SWRITE(0);
;     RESC(alB); __syncthreads();
;     SBAR(); qkt(pA0, pA1, KN_lds, KP_lds, qr, r32, hi);
;     finishSM(pB0, pB1, alB, l_reg, pa0, pa1, pa2, pa3); SBAR();
;     SLOAD(j + 2); SBAR();
;     pv_d0(o, vb0 + SHM_V, pa0, pa1, pa2, pa3); partialSM(pA0, pA1, m_reg, mnA, alA);
;     __syncthreads(); SWAIT(); SWRITE(1);
;     RESC(alA); __syncthreads();
	v_mfma_f32_32x32x16_bf16 v[80:95], v[208:211], v[116:119], v[80:95]
	v_mfma_f32_32x32x16_bf16 v[64:79], v[212:215], v[116:119], v[64:79]
	s_add_u32 s50, s47, s44
	s_addc_u32 s51, s63, 0
	s_add_u32 s52, s50, 0x20000
	ds_read_b128 v[208:211], v170 offset:8192
	ds_read_b128 v[212:215], v170 offset:12288
	s_waitcnt lgkmcnt(6)
	v_mfma_f32_32x32x16_bf16 v[80:95], v[216:219], v[112:115], v[80:95]
	v_mfma_f32_32x32x16_bf16 v[64:79], v[220:223], v[112:115], v[64:79]
	s_addc_u32 s53, s51, 0
	s_lshl_b32 s44, s37, 12
	s_add_u32 s54, s47, s44
	ds_read_b128 v[216:219], v171 offset:8192
	ds_read_b128 v[220:223], v171 offset:12288
	s_waitcnt lgkmcnt(6)
	v_mfma_f32_32x32x16_bf16 v[80:95], v[192:195], v[108:111], v[80:95]
	v_mfma_f32_32x32x16_bf16 v[64:79], v[196:199], v[108:111], v[64:79]
	s_addc_u32 s55, s63, 0
	s_add_u32 s56, s54, 0x20000
	s_addc_u32 s57, s55, 0
	ds_read_b64_tr_b16 v[192:193], v174 offset:0
	ds_read_b64_tr_b16 v[194:195], v174 offset:2048
	ds_read_b64_tr_b16 v[196:197], v174 offset:4096
	ds_read_b64_tr_b16 v[198:199], v174 offset:6144
	s_waitcnt lgkmcnt(8)
	v_mfma_f32_32x32x16_bf16 v[80:95], v[200:203], v[104:107], v[80:95]
	v_mfma_f32_32x32x16_bf16 v[64:79], v[204:207], v[104:107], v[64:79]
	s_lshl_b32 s44, s36, 10
	s_add_u32 s58, s60, s44
	s_addc_u32 s59, s61, 0
	ds_read_b64_tr_b16 v[200:201], v174 offset:8192
	ds_read_b64_tr_b16 v[202:203], v174 offset:10240
	ds_read_b64_tr_b16 v[204:205], v174 offset:12288
	ds_read_b64_tr_b16 v[206:207], v174 offset:14336
	s_waitcnt lgkmcnt(10)
	v_mfma_f32_32x32x16_bf16 v[80:95], v[208:211], v[100:103], v[80:95]
	v_mfma_f32_32x32x16_bf16 v[64:79], v[212:215], v[100:103], v[64:79]
	ds_read_b64_tr_b16 v[208:209], v174 offset:512
	ds_read_b64_tr_b16 v[210:211], v174 offset:2560
	ds_read_b64_tr_b16 v[212:213], v174 offset:4608
	ds_read_b64_tr_b16 v[214:215], v174 offset:6656
	s_waitcnt lgkmcnt(12)
	v_mfma_f32_32x32x16_bf16 v[80:95], v[216:219], v[96:99], v[80:95]
	v_mfma_f32_32x32x16_bf16 v[64:79], v[220:223], v[96:99], v[64:79]
	ds_read_b64_tr_b16 v[216:217], v174 offset:8704
	ds_read_b64_tr_b16 v[218:219], v174 offset:10752
	ds_read_b64_tr_b16 v[220:221], v174 offset:12800
	ds_read_b64_tr_b16 v[222:223], v174 offset:14848
	s_waitcnt lgkmcnt(12)
	v_mfma_f32_32x32x16_bf16 v[0:15], v[144:147], v[192:195], v[0:15]
	ds_read_b64_tr_b16 v[192:193], v174 offset:1024
	ds_read_b64_tr_b16 v[194:195], v174 offset:3072
	v_mfma_f32_32x32x16_bf16 v[0:15], v[148:151], v[196:199], v[0:15]
	ds_read_b64_tr_b16 v[196:197], v174 offset:5120
	ds_read_b64_tr_b16 v[198:199], v174 offset:7168
	s_waitcnt lgkmcnt(12)
	v_mfma_f32_32x32x16_bf16 v[0:15], v[152:155], v[200:203], v[0:15]
	ds_read_b64_tr_b16 v[200:201], v174 offset:9216
	ds_read_b64_tr_b16 v[202:203], v174 offset:11264
	v_mfma_f32_32x32x16_bf16 v[0:15], v[156:159], v[204:207], v[0:15]
	ds_read_b64_tr_b16 v[204:205], v174 offset:13312
	ds_read_b64_tr_b16 v[206:207], v174 offset:15360
	s_waitcnt lgkmcnt(12)
	v_mfma_f32_32x32x16_bf16 v[48:63], v[144:147], v[208:211], v[48:63]
	ds_read_b64_tr_b16 v[208:209], v174 offset:1536
	ds_read_b64_tr_b16 v[210:211], v174 offset:3584
	v_mfma_f32_32x32x16_bf16 v[48:63], v[148:151], v[212:215], v[48:63]
	ds_read_b64_tr_b16 v[212:213], v174 offset:5632
	ds_read_b64_tr_b16 v[214:215], v174 offset:7680
	s_waitcnt lgkmcnt(12)
	v_mfma_f32_32x32x16_bf16 v[48:63], v[152:155], v[216:219], v[48:63]
	ds_read_b64_tr_b16 v[216:217], v174 offset:9728
	ds_read_b64_tr_b16 v[218:219], v174 offset:11776
	v_mfma_f32_32x32x16_bf16 v[48:63], v[156:159], v[220:223], v[48:63]
	ds_read_b64_tr_b16 v[220:221], v174 offset:13824
	ds_read_b64_tr_b16 v[222:223], v174 offset:15872
	s_waitcnt lgkmcnt(12)
	v_mfma_f32_32x32x16_bf16 v[32:47], v[144:147], v[192:195], v[32:47]
	v_mfma_f32_32x32x16_bf16 v[32:47], v[148:151], v[196:199], v[32:47]
	s_waitcnt lgkmcnt(8)
	v_mfma_f32_32x32x16_bf16 v[32:47], v[152:155], v[200:203], v[32:47]
	v_mfma_f32_32x32x16_bf16 v[32:47], v[156:159], v[204:207], v[32:47]
	s_waitcnt lgkmcnt(4)
	v_mfma_f32_32x32x16_bf16 v[16:31], v[144:147], v[208:211], v[16:31]
	v_mfma_f32_32x32x16_bf16 v[16:31], v[148:151], v[212:215], v[16:31]
	s_waitcnt lgkmcnt(0)
	v_mfma_f32_32x32x16_bf16 v[16:31], v[152:155], v[216:219], v[16:31]
	v_mfma_f32_32x32x16_bf16 v[16:31], v[156:159], v[220:223], v[16:31]
	s_barrier
	v_max3_f32 v250, v80, v81, v82
	v_max3_f32 v250, v250, v83, v84
	v_max3_f32 v250, v250, v85, v86
	v_max3_f32 v250, v250, v87, v88
	v_max3_f32 v250, v250, v89, v90
	v_max3_f32 v250, v250, v91, v92
	v_max3_f32 v250, v250, v93, v94
	v_max3_f32 v250, v250, v95, v64
	v_max3_f32 v250, v250, v65, v66
	v_max3_f32 v250, v250, v67, v68
	v_max3_f32 v250, v250, v69, v70
	v_max3_f32 v250, v250, v71, v72
	v_max3_f32 v250, v250, v73, v74
	v_max3_f32 v250, v250, v75, v76
	v_max3_f32 v250, v250, v77, v78
	v_max3_f32 v250, v250, v79, v79
	v_cmp_lt_f32_e64 vcc, s64, |v250|
	s_waitcnt vmcnt(0)
	ds_write_b128 v247, v[232:235]
	ds_write_b128 v247, v[236:239] offset:8192
	ds_write_b128 v183, v[240:243]
	ds_write_b128 v245, v[224:227]
	ds_write_b128 v245, v[228:231] offset:8192
	global_load_dwordx4 v[232:235], v180, s[50:51]
	global_load_dwordx4 v[236:239], v180, s[52:53]
	global_load_dwordx4 v[224:227], v180, s[54:55] offset:256
	global_load_dwordx4 v[228:231], v180, s[56:57] offset:256
	global_load_dwordx4 v[240:243], v181, s[58:59]
	s_cmp_lg_u32 s62, 0
	s_cbranch_scc1 .Lpp_safe_Bb
	s_cbranch_vccnz .Lpp_sw_Bb
; #define SBAR() __builtin_amdgcn_sched_barrier(0)
; #define SLOAD(j) do { const int r0_ = TROW(j); const bf16_t* a_ = KVh + (size_t)(r0_ + sr) * LDKV + sc; const bf16_t* b_ = KVh + (size_t)(r0_ + 32 + sr) * LDKV + sc; \
;     vs0 = ld8(a_ + 128); vs1 = ld8(b_ + 128); ks0 = ld8(a_); ks1 = ld8(b_); kp0 = ld8(KPh + (size_t)(r0_ + pr) * LDKP + pc); } while (0)
; #define SWAIT() asm volatile("s_waitcnt vmcnt(0)" ::: "memory")
; __device__ __forceinline__ void partialSM(f32x16& p0, f32x16& p1, float& m_reg, float& mn, float& alpha) {
;   constexpr float C = SCALE * 1.4426950408889634f;
;   float pmax = p0[0]; for (int r = 1; r < 16; ++r) pmax = fmaxf(pmax, p0[r]); for (int r = 0; r < 16; ++r) pmax = fmaxf(pmax, p1[r]);
;   { auto rr = __builtin_amdgcn_permlane32_swap(__float_as_uint(pmax), __float_as_uint(pmax), false, false);
;     pmax = fmaxf(__uint_as_float(rr[0]), __uint_as_float(rr[1])); }
;   if (__builtin_expect(__all(pmax - m_reg <= THR / SCALE), 1)) { mn = m_reg; alpha = 1.f; }
;   else { mn = fmaxf(m_reg, pmax); alpha = __builtin_amdgcn_exp2f((m_reg - mn) * C); m_reg = mn; }
;   float mnC = -mn * C;
;   for (int r = 0; r < 16; ++r) p0[r] = fmaf(p0[r], C, mnC); for (int r = 0; r < 16; ++r) p1[r] = fmaf(p1[r], C, mnC);
;   for (int r = 0; r < 16; ++r) p0[r] = __builtin_amdgcn_exp2f(p0[r]);
; }
; __device__ __forceinline__ void finishSM(f32x16& p0, f32x16& p1, float alpha, float& l_reg, bf16x8& pa0, bf16x8& pa1, bf16x8& pa2, bf16x8& pa3) {
;   for (int r = 0; r < 16; ++r) p1[r] = __builtin_amdgcn_exp2f(p1[r]);
;   float ps = 0; for (int r = 0; r < 16; ++r) ps += p0[r]; for (int r = 0; r < 16; ++r) ps += p1[r];
;   { auto rr = __builtin_amdgcn_permlane32_swap(__float_as_uint(ps), __float_as_uint(ps), false, false);
;     ps = __uint_as_float(rr[0]) + __uint_as_float(rr[1]); }
;   l_reg = l_reg * alpha + ps;
;     ...
;   PK4(p0, 0, pa0); PK4(p0, 8, pa1); PK4(p1, 0, pa2); PK4(p1, 8, pa3);
;     ...
; }
; __device__ __forceinline__ void attn_unit(const bf16_t* __restrict__ Qb, const bf16_t* __restrict__ KV, const bf16_t* __restrict__ KP, bf16_t* __restrict__ Ob, ...
;     ...
;     SBAR(); qkt(pA0, pA1, KN_lds, KP_lds, qr, r32, hi);
;     finishSM(pB0, pB1, alB, l_reg, pa0, pa1, pa2, pa3); SBAR();
;     SLOAD(j + 2); SBAR();
;     pv_d0(o, vb0 + SHM_V, pa0, pa1, pa2, pa3); partialSM(pA0, pA1, m_reg, mnA, alA);
;     __syncthreads(); SWAIT(); SWRITE(1);
;     RESC(alA); __syncthreads();
	v_exp_f32_e32 v80, v80
	v_exp_f32_e32 v81, v81
	v_exp_f32_e32 v82, v82
	v_exp_f32_e32 v83, v83
	v_exp_f32_e32 v84, v84
	v_exp_f32_e32 v85, v85
	v_exp_f32_e32 v86, v86
	v_exp_f32_e32 v87, v87
	v_exp_f32_e32 v88, v88
	v_exp_f32_e32 v89, v89
	v_exp_f32_e32 v90, v90
	v_exp_f32_e32 v91, v91
	v_exp_f32_e32 v92, v92
	v_exp_f32_e32 v93, v93
	v_exp_f32_e32 v94, v94
	v_exp_f32_e32 v95, v95
	v_exp_f32_e32 v64, v64
	v_exp_f32_e32 v65, v65
	v_exp_f32_e32 v66, v66
	v_exp_f32_e32 v67, v67
	v_exp_f32_e32 v68, v68
	v_exp_f32_e32 v69, v69
	v_exp_f32_e32 v70, v70
	v_exp_f32_e32 v71, v71
	v_exp_f32_e32 v72, v72
	v_exp_f32_e32 v73, v73
	v_exp_f32_e32 v74, v74
	v_exp_f32_e32 v75, v75
	v_exp_f32_e32 v76, v76
	v_exp_f32_e32 v77, v77
	v_exp_f32_e32 v78, v78
	v_exp_f32_e32 v79, v79
	v_add_f32_e32 v249, v80, v81
	v_add_f32_e32 v250, v82, v83
	v_add_f32_e32 v251, v84, v85
	v_add_f32_e32 v182, v86, v87
	v_add_f32_e32 v249, v88, v249
	v_add_f32_e32 v250, v89, v250
	v_add_f32_e32 v251, v90, v251
	v_add_f32_e32 v182, v91, v182
	v_add_f32_e32 v249, v92, v249
	v_add_f32_e32 v250, v93, v250
	v_add_f32_e32 v251, v94, v251
	v_add_f32_e32 v182, v95, v182
	v_add_f32_e32 v249, v64, v249
	v_add_f32_e32 v250, v65, v250
	v_add_f32_e32 v251, v66, v251
	v_add_f32_e32 v182, v67, v182
	v_add_f32_e32 v249, v68, v249
	v_add_f32_e32 v250, v69, v250
	v_add_f32_e32 v251, v70, v251
	v_add_f32_e32 v182, v71, v182
	v_add_f32_e32 v249, v72, v249
	v_add_f32_e32 v250, v73, v250
	v_add_f32_e32 v251, v74, v251
	v_add_f32_e32 v182, v75, v182
	v_add_f32_e32 v249, v76, v249
	v_add_f32_e32 v250, v77, v250
	v_add_f32_e32 v251, v78, v251
	v_add_f32_e32 v182, v79, v182
	v_add_f32_e32 v249, v249, v250
	v_add_f32_e32 v251, v251, v182
	v_add_f32_e32 v249, v249, v251
	v_add_f32_e32 v176, v176, v249
	v_cvt_pk_bf16_f32 v144, v80, v81
	v_cvt_pk_bf16_f32 v145, v82, v83
	v_cvt_pk_bf16_f32 v146, v84, v85
	v_cvt_pk_bf16_f32 v147, v86, v87
	v_cvt_pk_bf16_f32 v148, v88, v89
	v_cvt_pk_bf16_f32 v149, v90, v91
	v_cvt_pk_bf16_f32 v150, v92, v93
	v_cvt_pk_bf16_f32 v151, v94, v95
	v_cvt_pk_bf16_f32 v152, v64, v65
	v_cvt_pk_bf16_f32 v153, v66, v67
	v_cvt_pk_bf16_f32 v154, v68, v69
	v_cvt_pk_bf16_f32 v155, v70, v71
	v_cvt_pk_bf16_f32 v156, v72, v73
	v_cvt_pk_bf16_f32 v157, v74, v75
	v_cvt_pk_bf16_f32 v158, v76, v77
	v_cvt_pk_bf16_f32 v159, v78, v79
.Lpp_send_Bb:
	s_add_i32 s11, s11, 1
	s_cmp_eq_u32 s11, 68
	s_cbranch_scc1 .Lpp_last
	ds_read_b128 v[192:195], v160
	ds_read_b128 v[196:199], v160 offset:8192
	ds_read_b128 v[200:203], v161
	ds_read_b128 v[204:207], v161 offset:8192
	ds_read_b128 v[208:211], v162
	ds_read_b128 v[212:215], v162 offset:8192
	ds_read_b128 v[216:219], v163
	ds_read_b128 v[220:223], v163 offset:8192
	s_waitcnt lgkmcnt(6)
	v_mfma_f32_32x32x16_bf16 v[80:95], v[192:195], v[136:139], 0
	v_mfma_f32_32x32x16_bf16 v[64:79], v[196:199], v[136:139], 0
	s_add_i32 s36, s35, 2
	s_min_u32 s36, s36, 67
	s_lshl_b32 s44, s36, 6
	ds_read_b128 v[192:195], v164
	ds_read_b128 v[196:199], v164 offset:8192
	s_waitcnt lgkmcnt(6)
	v_mfma_f32_32x32x16_bf16 v[80:95], v[200:203], v[132:135], v[80:95]
	v_mfma_f32_32x32x16_bf16 v[64:79], v[204:207], v[132:135], v[64:79]
	s_add_i32 s45, s31, s44
	s_add_i32 s46, s24, s44
	s_add_i32 s46, s46, 0xffffff00
	ds_read_b128 v[200:203], v165
	ds_read_b128 v[204:207], v165 offset:8192
	s_waitcnt lgkmcnt(6)
	v_mfma_f32_32x32x16_bf16 v[80:95], v[208:211], v[128:131], v[80:95]
	v_mfma_f32_32x32x16_bf16 v[64:79], v[212:215], v[128:131], v[64:79]
	s_cmp_lt_u32 s36, 4
	s_cselect_b32 s36, s45, s46
	s_add_i32 s37, s35, 1
	ds_read_b128 v[208:211], v166
	ds_read_b128 v[212:215], v166 offset:8192
	s_waitcnt lgkmcnt(6)
	v_mfma_f32_32x32x16_bf16 v[80:95], v[216:219], v[124:127], v[80:95]
	v_mfma_f32_32x32x16_bf16 v[64:79], v[220:223], v[124:127], v[64:79]
	s_min_u32 s37, s37, 67
	s_lshl_b32 s44, s37, 6
	s_add_i32 s45, s31, s44
	ds_read_b128 v[216:219], v167
	ds_read_b128 v[220:223], v167 offset:8192
	s_waitcnt lgkmcnt(6)
	v_mfma_f32_32x32x16_bf16 v[80:95], v[192:195], v[120:123], v[80:95]
	v_mfma_f32_32x32x16_bf16 v[64:79], v[196:199], v[120:123], v[64:79]
	s_add_i32 s46, s24, s44
	s_add_i32 s46, s46, 0xffffff00
	s_cmp_lt_u32 s37, 4
	ds_read_b128 v[192:195], v168
	ds_read_b128 v[196:199], v168 offset:4096
	s_waitcnt lgkmcnt(6)
	v_mfma_f32_32x32x16_bf16 v[80:95], v[200:203], v[140:143], v[80:95]
	v_mfma_f32_32x32x16_bf16 v[64:79], v[204:207], v[140:143], v[64:79]
	s_cselect_b32 s37, s45, s46
	s_add_i32 s35, s35, 1
	s_lshl_b32 s44, s36, 12
	ds_read_b128 v[200:203], v169
	ds_read_b128 v[204:207], v169 offset:4096
	s_waitcnt lgkmcnt(6)
	v_mfma_f32_32x32x16_bf16 v[80:95], v[208:211], v[116:119], v[80:95]
	v_mfma_f32_32x32x16_bf16 v[64:79], v[212:215], v[116:119], v[64:79]
	s_add_u32 s50, s47, s44
	s_addc_u32 s51, s63, 0
	s_add_u32 s52, s50, 0x20000
	ds_read_b128 v[208:211], v170
	ds_read_b128 v[212:215], v170 offset:4096
	s_waitcnt lgkmcnt(6)
	v_mfma_f32_32x32x16_bf16 v[80:95], v[216:219], v[112:115], v[80:95]
	v_mfma_f32_32x32x16_bf16 v[64:79], v[220:223], v[112:115], v[64:79]
	s_addc_u32 s53, s51, 0
	s_lshl_b32 s44, s37, 12
	s_add_u32 s54, s47, s44
	ds_read_b128 v[216:219], v171
	ds_read_b128 v[220:223], v171 offset:4096
	s_waitcnt lgkmcnt(6)
	v_mfma_f32_32x32x16_bf16 v[80:95], v[192:195], v[108:111], v[80:95]
	v_mfma_f32_32x32x16_bf16 v[64:79], v[196:199], v[108:111], v[64:79]
	s_addc_u32 s55, s63, 0
	s_add_u32 s56, s54, 0x20000
	s_addc_u32 s57, s55, 0
	ds_read_b64_tr_b16 v[192:193], v174 offset:16384
	ds_read_b64_tr_b16 v[194:195], v174 offset:18432
	ds_read_b64_tr_b16 v[196:197], v174 offset:20480
	ds_read_b64_tr_b16 v[198:199], v174 offset:22528
	s_waitcnt lgkmcnt(8)
; #define SBAR() __builtin_amdgcn_sched_barrier(0)
; #define RESC(a) do { if (__any((a) < 1.f)) { if (hi == 0) al_l[r32] = (a); asm volatile("s_waitcnt lgkmcnt(0)" ::: "memory"); \
;     for (int d = 0; d < 4; ++d) for (int r = 0; r < 16; ++r) o[d][r] *= al_l[crow(r, hi)]; } } while (0)
; template <int D0> __device__ __forceinline__ void pv_one(f32x16& od, int vb, bf16x8 pa0, bf16x8 pa1, bf16x8 pa2, bf16x8 pa3) {
;   const s16x4 l0 = tr_read<v_rd_off(D0, 0, 0)>(vb), h0 = tr_read<v_rd_off(D0, 0, 1)>(vb), l1 = tr_read<v_rd_off(D0, 1, 0)>(vb), h1 = tr_read<v_rd_off(D0, 1, 1)>(vb);
;   const s16x4 l2 = tr_read<v_rd_off(D0, 2, 0)>(vb), h2 = tr_read<v_rd_off(D0, 2, 1)>(vb), l3 = tr_read<v_rd_off(D0, 3, 0)>(vb), h3 = tr_read<v_rd_off(D0, 3, 1)>(vb);
;   asm volatile("s_waitcnt lgkmcnt(0)" ::: "memory"); SBAR();
;     ...
;   od = __builtin_amdgcn_mfma_f32_32x32x16_bf16(pa0, PK(l0, h0), od, 0, 0, 0);
;   od = __builtin_amdgcn_mfma_f32_32x32x16_bf16(pa1, PK(l1, h1), od, 0, 0, 0);
;   od = __builtin_amdgcn_mfma_f32_32x32x16_bf16(pa2, PK(l2, h2), od, 0, 0, 0);
;   od = __builtin_amdgcn_mfma_f32_32x32x16_bf16(pa3, PK(l3, h3), od, 0, 0, 0);
;     ...
; }
; __device__ __forceinline__ void pv_d0(f32x16* o, int vb, bf16x8 pa0, bf16x8 pa1, bf16x8 pa2, bf16x8 pa3) {
;   pv_one<0>(o[0], vb, pa0, pa1, pa2, pa3); pv_one<1>(o[1], vb, pa0, pa1, pa2, pa3); pv_one<2>(o[2], vb, pa0, pa1, pa2, pa3); pv_one<3>(o[3], vb, pa0, pa1, pa2, pa3);
; }
; __device__ __forceinline__ void attn_unit(const bf16_t* __restrict__ Qb, const bf16_t* __restrict__ KV, const bf16_t* __restrict__ KP, bf16_t* __restrict__ Ob, ...
;     ...
;   SBAR(); qkt(pB0, pB1, KN_lds + SHM_KN, KP_lds + SHM_KP, qr, r32, hi);
;   finishSM(pA0, pA1, alA, l_reg, pa0, pa1, pa2, pa3); SBAR();
;   pv_d0(o, vb0, pa0, pa1, pa2, pa3); partialSM(pB0, pB1, m_reg, mnB, alB);
;   __syncthreads(); RESC(alB);
;   finishSM(pB0, pB1, alB, l_reg, pa0, pa1, pa2, pa3); SBAR();
;   pv_d0(o, vb0 + SHM_V, pa0, pa1, pa2, pa3);
	v_mfma_f32_32x32x16_bf16 v[80:95], v[200:203], v[104:107], v[80:95]
	v_mfma_f32_32x32x16_bf16 v[64:79], v[204:207], v[104:107], v[64:79]
	s_lshl_b32 s44, s36, 10
	s_add_u32 s58, s60, s44
	s_addc_u32 s59, s61, 0
	ds_read_b64_tr_b16 v[200:201], v174 offset:24576
	ds_read_b64_tr_b16 v[202:203], v174 offset:26624
	ds_read_b64_tr_b16 v[204:205], v174 offset:28672
	ds_read_b64_tr_b16 v[206:207], v174 offset:30720
	s_waitcnt lgkmcnt(10)
	v_mfma_f32_32x32x16_bf16 v[80:95], v[208:211], v[100:103], v[80:95]
	v_mfma_f32_32x32x16_bf16 v[64:79], v[212:215], v[100:103], v[64:79]
	ds_read_b64_tr_b16 v[208:209], v174 offset:16896
	ds_read_b64_tr_b16 v[210:211], v174 offset:18944
	ds_read_b64_tr_b16 v[212:213], v174 offset:20992
	ds_read_b64_tr_b16 v[214:215], v174 offset:23040
	s_waitcnt lgkmcnt(12)
	v_mfma_f32_32x32x16_bf16 v[80:95], v[216:219], v[96:99], v[80:95]
	v_mfma_f32_32x32x16_bf16 v[64:79], v[220:223], v[96:99], v[64:79]
	ds_read_b64_tr_b16 v[216:217], v174 offset:25088
	ds_read_b64_tr_b16 v[218:219], v174 offset:27136
	ds_read_b64_tr_b16 v[220:221], v174 offset:29184
	ds_read_b64_tr_b16 v[222:223], v174 offset:31232
	s_waitcnt lgkmcnt(12)
	v_mfma_f32_32x32x16_bf16 v[0:15], v[144:147], v[192:195], v[0:15]
	ds_read_b64_tr_b16 v[192:193], v174 offset:17408
	ds_read_b64_tr_b16 v[194:195], v174 offset:19456
	v_mfma_f32_32x32x16_bf16 v[0:15], v[148:151], v[196:199], v[0:15]
	ds_read_b64_tr_b16 v[196:197], v174 offset:21504
	ds_read_b64_tr_b16 v[198:199], v174 offset:23552
	s_waitcnt lgkmcnt(12)
	v_mfma_f32_32x32x16_bf16 v[0:15], v[152:155], v[200:203], v[0:15]
	ds_read_b64_tr_b16 v[200:201], v174 offset:25600
	ds_read_b64_tr_b16 v[202:203], v174 offset:27648
	v_mfma_f32_32x32x16_bf16 v[0:15], v[156:159], v[204:207], v[0:15]
	ds_read_b64_tr_b16 v[204:205], v174 offset:29696
	ds_read_b64_tr_b16 v[206:207], v174 offset:31744
	s_waitcnt lgkmcnt(12)
	v_mfma_f32_32x32x16_bf16 v[48:63], v[144:147], v[208:211], v[48:63]
	ds_read_b64_tr_b16 v[208:209], v174 offset:17920
	ds_read_b64_tr_b16 v[210:211], v174 offset:19968
	v_mfma_f32_32x32x16_bf16 v[48:63], v[148:151], v[212:215], v[48:63]
	ds_read_b64_tr_b16 v[212:213], v174 offset:22016
	ds_read_b64_tr_b16 v[214:215], v174 offset:24064
	s_waitcnt lgkmcnt(12)
	v_mfma_f32_32x32x16_bf16 v[48:63], v[152:155], v[216:219], v[48:63]
	ds_read_b64_tr_b16 v[216:217], v174 offset:26112
	ds_read_b64_tr_b16 v[218:219], v174 offset:28160
	v_mfma_f32_32x32x16_bf16 v[48:63], v[156:159], v[220:223], v[48:63]
	ds_read_b64_tr_b16 v[220:221], v174 offset:30208
	ds_read_b64_tr_b16 v[222:223], v174 offset:32256
	s_waitcnt lgkmcnt(12)
	v_mfma_f32_32x32x16_bf16 v[32:47], v[144:147], v[192:195], v[32:47]
	v_mfma_f32_32x32x16_bf16 v[32:47], v[148:151], v[196:199], v[32:47]
	s_waitcnt lgkmcnt(8)
	v_mfma_f32_32x32x16_bf16 v[32:47], v[152:155], v[200:203], v[32:47]
	v_mfma_f32_32x32x16_bf16 v[32:47], v[156:159], v[204:207], v[32:47]
	s_waitcnt lgkmcnt(4)
	v_mfma_f32_32x32x16_bf16 v[16:31], v[144:147], v[208:211], v[16:31]
	v_mfma_f32_32x32x16_bf16 v[16:31], v[148:151], v[212:215], v[16:31]
	s_waitcnt lgkmcnt(0)
	v_mfma_f32_32x32x16_bf16 v[16:31], v[152:155], v[216:219], v[16:31]
	v_mfma_f32_32x32x16_bf16 v[16:31], v[156:159], v[220:223], v[16:31]
	s_branch .Lpp_loop
.Lpp_last:
	ds_read_b64_tr_b16 v[192:193], v174 offset:16384
	ds_read_b64_tr_b16 v[194:195], v174 offset:18432
	ds_read_b64_tr_b16 v[196:197], v174 offset:20480
	ds_read_b64_tr_b16 v[198:199], v174 offset:22528
	ds_read_b64_tr_b16 v[200:201], v174 offset:24576
	ds_read_b64_tr_b16 v[202:203], v174 offset:26624
	ds_read_b64_tr_b16 v[204:205], v174 offset:28672
	ds_read_b64_tr_b16 v[206:207], v174 offset:30720
	ds_read_b64_tr_b16 v[208:209], v174 offset:16896
	ds_read_b64_tr_b16 v[210:211], v174 offset:18944
	ds_read_b64_tr_b16 v[212:213], v174 offset:20992
	ds_read_b64_tr_b16 v[214:215], v174 offset:23040
	ds_read_b64_tr_b16 v[216:217], v174 offset:25088
	ds_read_b64_tr_b16 v[218:219], v174 offset:27136
	ds_read_b64_tr_b16 v[220:221], v174 offset:29184
	ds_read_b64_tr_b16 v[222:223], v174 offset:31232
	s_waitcnt lgkmcnt(12)
	s_nop 0
	v_mfma_f32_32x32x16_bf16 v[0:15], v[144:147], v[192:195], v[0:15]
	ds_read_b64_tr_b16 v[192:193], v174 offset:17408
	ds_read_b64_tr_b16 v[194:195], v174 offset:19456
	v_mfma_f32_32x32x16_bf16 v[0:15], v[148:151], v[196:199], v[0:15]
	ds_read_b64_tr_b16 v[196:197], v174 offset:21504
	ds_read_b64_tr_b16 v[198:199], v174 offset:23552
	s_waitcnt lgkmcnt(12)
	v_mfma_f32_32x32x16_bf16 v[0:15], v[152:155], v[200:203], v[0:15]
	ds_read_b64_tr_b16 v[200:201], v174 offset:25600
	ds_read_b64_tr_b16 v[202:203], v174 offset:27648
	v_mfma_f32_32x32x16_bf16 v[0:15], v[156:159], v[204:207], v[0:15]
	ds_read_b64_tr_b16 v[204:205], v174 offset:29696
	ds_read_b64_tr_b16 v[206:207], v174 offset:31744
	s_waitcnt lgkmcnt(12)
	v_mfma_f32_32x32x16_bf16 v[48:63], v[144:147], v[208:211], v[48:63]
	ds_read_b64_tr_b16 v[208:209], v174 offset:17920
	ds_read_b64_tr_b16 v[210:211], v174 offset:19968
	v_mfma_f32_32x32x16_bf16 v[48:63], v[148:151], v[212:215], v[48:63]
	ds_read_b64_tr_b16 v[212:213], v174 offset:22016
	ds_read_b64_tr_b16 v[214:215], v174 offset:24064
	s_waitcnt lgkmcnt(12)
	v_mfma_f32_32x32x16_bf16 v[48:63], v[152:155], v[216:219], v[48:63]
	ds_read_b64_tr_b16 v[216:217], v174 offset:26112
	ds_read_b64_tr_b16 v[218:219], v174 offset:28160
	v_mfma_f32_32x32x16_bf16 v[48:63], v[156:159], v[220:223], v[48:63]
	ds_read_b64_tr_b16 v[220:221], v174 offset:30208
	ds_read_b64_tr_b16 v[222:223], v174 offset:32256
	s_waitcnt lgkmcnt(12)
	v_mfma_f32_32x32x16_bf16 v[32:47], v[144:147], v[192:195], v[32:47]
	v_mfma_f32_32x32x16_bf16 v[32:47], v[148:151], v[196:199], v[32:47]
	s_waitcnt lgkmcnt(8)
	v_mfma_f32_32x32x16_bf16 v[32:47], v[152:155], v[200:203], v[32:47]
	v_mfma_f32_32x32x16_bf16 v[32:47], v[156:159], v[204:207], v[32:47]
	s_waitcnt lgkmcnt(4)
	v_mfma_f32_32x32x16_bf16 v[16:31], v[144:147], v[208:211], v[16:31]
	v_mfma_f32_32x32x16_bf16 v[16:31], v[148:151], v[212:215], v[16:31]
	s_waitcnt lgkmcnt(0)
	v_mfma_f32_32x32x16_bf16 v[16:31], v[152:155], v[216:219], v[16:31]
	v_mfma_f32_32x32x16_bf16 v[16:31], v[156:159], v[220:223], v[16:31]
	s_barrier
	s_branch .Lpp_fin
; __device__ __forceinline__ void partialSM(f32x16& p0, f32x16& p1, float& m_reg, float& mn, float& alpha) {
;   constexpr float C = SCALE * 1.4426950408889634f;
;   float pmax = p0[0]; for (int r = 1; r < 16; ++r) pmax = fmaxf(pmax, p0[r]); for (int r = 0; r < 16; ++r) pmax = fmaxf(pmax, p1[r]);
;   { auto rr = __builtin_amdgcn_permlane32_swap(__float_as_uint(pmax), __float_as_uint(pmax), false, false);
;     pmax = fmaxf(__uint_as_float(rr[0]), __uint_as_float(rr[1])); }
;   if (__builtin_expect(__all(pmax - m_reg <= THR / SCALE), 1)) { mn = m_reg; alpha = 1.f; }
;   else { mn = fmaxf(m_reg, pmax); alpha = __builtin_amdgcn_exp2f((m_reg - mn) * C); m_reg = mn; }
;   float mnC = -mn * C;
;   for (int r = 0; r < 16; ++r) p0[r] = fmaf(p0[r], C, mnC); for (int r = 0; r < 16; ++r) p1[r] = fmaf(p1[r], C, mnC);
;   for (int r = 0; r < 16; ++r) p0[r] = __builtin_amdgcn_exp2f(p0[r]);
; }
; __device__ __forceinline__ void qkt(f32x16& p0, f32x16& p1, const char* Kn, const char* Kp, const bf16x8* qr, int r32, int hi) {
;   p0 = f32x16{}; p1 = f32x16{};
; #pragma unroll
;   for (int d0 = 0; d0 < 8; ++d0) { int cb = (d0 * 16 + hi * 8) * 2;
;     bf16x8 b0 = *reinterpret_cast<const bf16x8*>(Kn + KSWZ(r32, cb));
;     bf16x8 b1 = *reinterpret_cast<const bf16x8*>(Kn + KSWZ(32 + r32, cb));
;     p0 = __builtin_amdgcn_mfma_f32_32x32x16_bf16(b0, qr[d0], p0, 0, 0, 0);
;     p1 = __builtin_amdgcn_mfma_f32_32x32x16_bf16(b1, qr[d0], p1, 0, 0, 0); }
; #pragma unroll
;   for (int d1 = 0; d1 < 4; ++d1) { int cb = (d1 * 16 + hi * 8) * 2;
;     bf16x8 b0 = *reinterpret_cast<const bf16x8*>(Kp + KPSWZ(r32, cb));
;     bf16x8 b1 = *reinterpret_cast<const bf16x8*>(Kp + KPSWZ(32 + r32, cb));
;     p0 = __builtin_amdgcn_mfma_f32_32x32x16_bf16(b0, qr[8 + d1], p0, 0, 0, 0);
;     p1 = __builtin_amdgcn_mfma_f32_32x32x16_bf16(b1, qr[8 + d1], p1, 0, 0, 0); }
; }
.Lpp_ga:
	ds_read_b128 v[192:195], v160
	ds_read_b128 v[196:199], v160 offset:8192
	ds_read_b128 v[200:203], v161
	ds_read_b128 v[204:207], v161 offset:8192
	ds_read_b128 v[208:211], v162
	ds_read_b128 v[212:215], v162 offset:8192
	ds_read_b128 v[216:219], v163
	ds_read_b128 v[220:223], v163 offset:8192
	s_waitcnt lgkmcnt(6)
	v_mfma_f32_32x32x16_bf16 v[80:95], v[192:195], v[136:139], 0
	v_mfma_f32_32x32x16_bf16 v[64:79], v[196:199], v[136:139], 0
	s_add_i32 s36, s35, 2
	s_min_u32 s36, s36, 67
	s_lshl_b32 s44, s36, 6
	ds_read_b128 v[192:195], v164
	ds_read_b128 v[196:199], v164 offset:8192
	s_waitcnt lgkmcnt(6)
	v_mfma_f32_32x32x16_bf16 v[80:95], v[200:203], v[132:135], v[80:95]
	v_mfma_f32_32x32x16_bf16 v[64:79], v[204:207], v[132:135], v[64:79]
	s_add_i32 s45, s31, s44
	s_add_i32 s46, s24, s44
	s_add_i32 s46, s46, 0xffffff00
	ds_read_b128 v[200:203], v165
	ds_read_b128 v[204:207], v165 offset:8192
	s_waitcnt lgkmcnt(6)
	v_mfma_f32_32x32x16_bf16 v[80:95], v[208:211], v[128:131], v[80:95]
	v_mfma_f32_32x32x16_bf16 v[64:79], v[212:215], v[128:131], v[64:79]
	s_cmp_lt_u32 s36, 4
	s_cselect_b32 s36, s45, s46
	s_add_i32 s37, s35, 1
	ds_read_b128 v[208:211], v166
	ds_read_b128 v[212:215], v166 offset:8192
	s_waitcnt lgkmcnt(6)
	v_mfma_f32_32x32x16_bf16 v[80:95], v[216:219], v[124:127], v[80:95]
	v_mfma_f32_32x32x16_bf16 v[64:79], v[220:223], v[124:127], v[64:79]
	s_min_u32 s37, s37, 67
	s_lshl_b32 s44, s37, 6
	s_add_i32 s45, s31, s44
	ds_read_b128 v[216:219], v167
	ds_read_b128 v[220:223], v167 offset:8192
	s_waitcnt lgkmcnt(6)
	v_mfma_f32_32x32x16_bf16 v[80:95], v[192:195], v[120:123], v[80:95]
	v_mfma_f32_32x32x16_bf16 v[64:79], v[196:199], v[120:123], v[64:79]
	s_add_i32 s46, s24, s44
	s_add_i32 s46, s46, 0xffffff00
	s_cmp_lt_u32 s37, 4
	ds_read_b128 v[192:195], v168
	ds_read_b128 v[196:199], v168 offset:4096
	s_waitcnt lgkmcnt(6)
	v_mfma_f32_32x32x16_bf16 v[80:95], v[200:203], v[140:143], v[80:95]
	v_mfma_f32_32x32x16_bf16 v[64:79], v[204:207], v[140:143], v[64:79]
	s_cselect_b32 s37, s45, s46
	s_add_i32 s35, s35, 1
	s_lshl_b32 s44, s36, 12
	ds_read_b128 v[200:203], v169
	ds_read_b128 v[204:207], v169 offset:4096
	s_waitcnt lgkmcnt(6)
	v_mfma_f32_32x32x16_bf16 v[80:95], v[208:211], v[116:119], v[80:95]
	v_mfma_f32_32x32x16_bf16 v[64:79], v[212:215], v[116:119], v[64:79]
	s_add_u32 s50, s47, s44
	s_addc_u32 s51, s63, 0
	s_add_u32 s52, s50, 0x20000
	ds_read_b128 v[208:211], v170
	ds_read_b128 v[212:215], v170 offset:4096
	s_waitcnt lgkmcnt(6)
	v_mfma_f32_32x32x16_bf16 v[80:95], v[216:219], v[112:115], v[80:95]
	v_mfma_f32_32x32x16_bf16 v[64:79], v[220:223], v[112:115], v[64:79]
	s_addc_u32 s53, s51, 0
	s_lshl_b32 s44, s37, 12
	s_add_u32 s54, s47, s44
	ds_read_b128 v[216:219], v171
	ds_read_b128 v[220:223], v171 offset:4096
	s_waitcnt lgkmcnt(6)
	v_mfma_f32_32x32x16_bf16 v[80:95], v[192:195], v[108:111], v[80:95]
	v_mfma_f32_32x32x16_bf16 v[64:79], v[196:199], v[108:111], v[64:79]
	s_addc_u32 s55, s63, 0
	s_add_u32 s56, s54, 0x20000
	s_addc_u32 s57, s55, 0
	s_waitcnt lgkmcnt(4)
	v_mfma_f32_32x32x16_bf16 v[80:95], v[200:203], v[104:107], v[80:95]
	v_mfma_f32_32x32x16_bf16 v[64:79], v[204:207], v[104:107], v[64:79]
	s_lshl_b32 s44, s36, 10
	s_add_u32 s58, s60, s44
	s_addc_u32 s59, s61, 0
	s_waitcnt lgkmcnt(2)
	v_mfma_f32_32x32x16_bf16 v[80:95], v[208:211], v[100:103], v[80:95]
	v_mfma_f32_32x32x16_bf16 v[64:79], v[212:215], v[100:103], v[64:79]
	s_waitcnt lgkmcnt(0)
	v_mfma_f32_32x32x16_bf16 v[80:95], v[216:219], v[96:99], v[80:95]
	v_mfma_f32_32x32x16_bf16 v[64:79], v[220:223], v[96:99], v[64:79]
	s_nop 7
	s_nop 7
	s_nop 7
.Lpp_aloop:
	v_max3_f32 v250, v80, v81, v82
	v_max3_f32 v250, v250, v83, v84
	v_max3_f32 v250, v250, v85, v86
	v_max3_f32 v250, v250, v87, v88
	v_max3_f32 v250, v250, v89, v90
	v_max3_f32 v250, v250, v91, v92
	v_max3_f32 v250, v250, v93, v94
	v_max3_f32 v250, v250, v95, v64
	v_max3_f32 v250, v250, v65, v66
	v_max3_f32 v250, v250, v67, v68
	v_max3_f32 v250, v250, v69, v70
	v_max3_f32 v250, v250, v71, v72
	v_max3_f32 v250, v250, v73, v74
	v_max3_f32 v250, v250, v75, v76
	v_max3_f32 v250, v250, v77, v78
	v_max3_f32 v250, v250, v79, v79
	v_cmp_lt_f32_e64 vcc, s64, |v250|
	s_waitcnt vmcnt(0)
	ds_write_b128 v246, v[232:235]
	ds_write_b128 v246, v[236:239] offset:8192
	ds_write_b128 v248, v[240:243]
	ds_write_b128 v244, v[224:227]
	ds_write_b128 v244, v[228:231] offset:8192
	global_load_dwordx4 v[232:235], v180, s[50:51]
	global_load_dwordx4 v[236:239], v180, s[52:53]
	global_load_dwordx4 v[224:227], v180, s[54:55] offset:256
	global_load_dwordx4 v[228:231], v180, s[56:57] offset:256
	global_load_dwordx4 v[240:243], v181, s[58:59]
	s_cmp_lg_u32 s62, 0
	s_cbranch_scc1 .Lpp_safe_Aa
	s_cbranch_vccnz .Lpp_sw_Aa
	v_exp_f32_e32 v80, v80
	v_exp_f32_e32 v81, v81
	v_exp_f32_e32 v82, v82
	v_exp_f32_e32 v83, v83
	v_exp_f32_e32 v84, v84
	v_exp_f32_e32 v85, v85
	v_exp_f32_e32 v86, v86
	v_exp_f32_e32 v87, v87
	v_exp_f32_e32 v88, v88
	v_exp_f32_e32 v89, v89
	v_exp_f32_e32 v90, v90
	v_exp_f32_e32 v91, v91
	v_exp_f32_e32 v92, v92
	v_exp_f32_e32 v93, v93
	v_exp_f32_e32 v94, v94
	v_exp_f32_e32 v95, v95
	v_exp_f32_e32 v64, v64
	v_exp_f32_e32 v65, v65
	v_exp_f32_e32 v66, v66
	v_exp_f32_e32 v67, v67
	v_exp_f32_e32 v68, v68
	v_exp_f32_e32 v69, v69
	v_exp_f32_e32 v70, v70
	v_exp_f32_e32 v71, v71
	v_exp_f32_e32 v72, v72
	v_exp_f32_e32 v73, v73
	v_exp_f32_e32 v74, v74
	v_exp_f32_e32 v75, v75
	v_exp_f32_e32 v76, v76
	v_exp_f32_e32 v77, v77
	v_exp_f32_e32 v78, v78
	v_exp_f32_e32 v79, v79
	v_add_f32_e32 v249, v80, v81
	v_add_f32_e32 v250, v82, v83
	v_add_f32_e32 v251, v84, v85
	v_add_f32_e32 v182, v86, v87
	v_add_f32_e32 v249, v88, v249
	v_add_f32_e32 v250, v89, v250
	v_add_f32_e32 v251, v90, v251
	v_add_f32_e32 v182, v91, v182
	v_add_f32_e32 v249, v92, v249
	v_add_f32_e32 v250, v93, v250
	v_add_f32_e32 v251, v94, v251
	v_add_f32_e32 v182, v95, v182
	v_add_f32_e32 v249, v64, v249
	v_add_f32_e32 v250, v65, v250
	v_add_f32_e32 v251, v66, v251
	v_add_f32_e32 v182, v67, v182
	v_add_f32_e32 v249, v68, v249
	v_add_f32_e32 v250, v69, v250
	v_add_f32_e32 v251, v70, v251
	v_add_f32_e32 v182, v71, v182
	v_add_f32_e32 v249, v72, v249
	v_add_f32_e32 v250, v73, v250
	v_add_f32_e32 v251, v74, v251
	v_add_f32_e32 v182, v75, v182
	v_add_f32_e32 v249, v76, v249
	v_add_f32_e32 v250, v77, v250
	v_add_f32_e32 v251, v78, v251
	v_add_f32_e32 v182, v79, v182
	v_add_f32_e32 v249, v249, v250
	v_add_f32_e32 v251, v251, v182
	v_add_f32_e32 v249, v249, v251
	v_add_f32_e32 v176, v176, v249
	v_cvt_pk_bf16_f32 v144, v80, v81
	v_cvt_pk_bf16_f32 v145, v82, v83
	v_cvt_pk_bf16_f32 v146, v84, v85
	v_cvt_pk_bf16_f32 v147, v86, v87
	v_cvt_pk_bf16_f32 v148, v88, v89
	v_cvt_pk_bf16_f32 v149, v90, v91
	v_cvt_pk_bf16_f32 v150, v92, v93
	v_cvt_pk_bf16_f32 v151, v94, v95
	v_cvt_pk_bf16_f32 v152, v64, v65
	v_cvt_pk_bf16_f32 v153, v66, v67
	v_cvt_pk_bf16_f32 v154, v68, v69
	v_cvt_pk_bf16_f32 v155, v70, v71
	v_cvt_pk_bf16_f32 v156, v72, v73
	v_cvt_pk_bf16_f32 v157, v74, v75
	v_cvt_pk_bf16_f32 v158, v76, v77
	v_cvt_pk_bf16_f32 v159, v78, v79
; __device__ __forceinline__ void qkt(f32x16& p0, f32x16& p1, const char* Kn, const char* Kp, const bf16x8* qr, int r32, int hi) {
;   p0 = f32x16{}; p1 = f32x16{};
; #pragma unroll
;   for (int d0 = 0; d0 < 8; ++d0) { int cb = (d0 * 16 + hi * 8) * 2;
;     bf16x8 b0 = *reinterpret_cast<const bf16x8*>(Kn + KSWZ(r32, cb));
;     bf16x8 b1 = *reinterpret_cast<const bf16x8*>(Kn + KSWZ(32 + r32, cb));
;     p0 = __builtin_amdgcn_mfma_f32_32x32x16_bf16(b0, qr[d0], p0, 0, 0, 0);
;     p1 = __builtin_amdgcn_mfma_f32_32x32x16_bf16(b1, qr[d0], p1, 0, 0, 0); }
; #pragma unroll
;   for (int d1 = 0; d1 < 4; ++d1) { int cb = (d1 * 16 + hi * 8) * 2;
;     bf16x8 b0 = *reinterpret_cast<const bf16x8*>(Kp + KPSWZ(r32, cb));
;     bf16x8 b1 = *reinterpret_cast<const bf16x8*>(Kp + KPSWZ(32 + r32, cb));
;     p0 = __builtin_amdgcn_mfma_f32_32x32x16_bf16(b0, qr[8 + d1], p0, 0, 0, 0);
;     p1 = __builtin_amdgcn_mfma_f32_32x32x16_bf16(b1, qr[8 + d1], p1, 0, 0, 0); }
; }
; __device__ __forceinline__ int v_st(int k, int c) { const int kk = (k & ~0xC) | ((k & 4) << 1) | ((k & 8) >> 1); return ((kk >> 3) * 4 + (c >> 5)) * 512 + ((kk & 7) * 32 + (c & 31)) * 2; }
; __device__ __forceinline__ int v_rd_base(int lane) { return ((lane & 3) << 3) | (((lane >> 2) & 3) << 6) | (((lane >> 4) & 1) << 5) | (((lane >> 5) & 1) << 8); }
; template <int OFF> __device__ __forceinline__ s16x4 tr_read(int vb) {
;   s16x4 r; asm volatile("ds_read_b64_tr_b16 %0, %1 offset:%2" : "=&v"(r) : "v"(vb), "i"(OFF) : "memory"); return r;
; }
; template <int D0> __device__ __forceinline__ void pv_one(f32x16& od, int vb, bf16x8 pa0, bf16x8 pa1, bf16x8 pa2, bf16x8 pa3) {
;   const s16x4 l0 = tr_read<v_rd_off(D0, 0, 0)>(vb), h0 = tr_read<v_rd_off(D0, 0, 1)>(vb), l1 = tr_read<v_rd_off(D0, 1, 0)>(vb), h1 = tr_read<v_rd_off(D0, 1, 1)>(vb);
;   const s16x4 l2 = tr_read<v_rd_off(D0, 2, 0)>(vb), h2 = tr_read<v_rd_off(D0, 2, 1)>(vb), l3 = tr_read<v_rd_off(D0, 3, 0)>(vb), h3 = tr_read<v_rd_off(D0, 3, 1)>(vb);
;   asm volatile("s_waitcnt lgkmcnt(0)" ::: "memory"); SBAR();
;     ...
;   od = __builtin_amdgcn_mfma_f32_32x32x16_bf16(pa0, PK(l0, h0), od, 0, 0, 0);
;   od = __builtin_amdgcn_mfma_f32_32x32x16_bf16(pa1, PK(l1, h1), od, 0, 0, 0);
;   od = __builtin_amdgcn_mfma_f32_32x32x16_bf16(pa2, PK(l2, h2), od, 0, 0, 0);
;   od = __builtin_amdgcn_mfma_f32_32x32x16_bf16(pa3, PK(l3, h3), od, 0, 0, 0);
;     ...
; }
.Lpp_send_Aa:
	s_waitcnt lgkmcnt(0)
	s_barrier
	s_add_i32 s11, s11, 1
	ds_read_b128 v[192:195], v160 offset:16384
	ds_read_b128 v[196:199], v160 offset:24576
	ds_read_b128 v[200:203], v161 offset:16384
	ds_read_b128 v[204:207], v161 offset:24576
	ds_read_b128 v[208:211], v162 offset:16384
	ds_read_b128 v[212:215], v162 offset:24576
	ds_read_b128 v[216:219], v163 offset:16384
	ds_read_b128 v[220:223], v163 offset:24576
	s_waitcnt lgkmcnt(6)
	v_mfma_f32_32x32x16_bf16 v[80:95], v[192:195], v[136:139], 0
	v_mfma_f32_32x32x16_bf16 v[64:79], v[196:199], v[136:139], 0
	s_add_i32 s36, s35, 2
	s_min_u32 s36, s36, 67
	s_lshl_b32 s44, s36, 6
	ds_read_b128 v[192:195], v164 offset:16384
	ds_read_b128 v[196:199], v164 offset:24576
	s_waitcnt lgkmcnt(6)
	v_mfma_f32_32x32x16_bf16 v[80:95], v[200:203], v[132:135], v[80:95]
	v_mfma_f32_32x32x16_bf16 v[64:79], v[204:207], v[132:135], v[64:79]
	s_add_i32 s45, s31, s44
	s_add_i32 s46, s24, s44
	s_add_i32 s46, s46, 0xffffff00
	ds_read_b128 v[200:203], v165 offset:16384
	ds_read_b128 v[204:207], v165 offset:24576
	s_waitcnt lgkmcnt(6)
	v_mfma_f32_32x32x16_bf16 v[80:95], v[208:211], v[128:131], v[80:95]
	v_mfma_f32_32x32x16_bf16 v[64:79], v[212:215], v[128:131], v[64:79]
	s_cmp_lt_u32 s36, 4
	s_cselect_b32 s36, s45, s46
	s_add_i32 s37, s35, 1
	ds_read_b128 v[208:211], v166 offset:16384
	ds_read_b128 v[212:215], v166 offset:24576
	s_waitcnt lgkmcnt(6)
	v_mfma_f32_32x32x16_bf16 v[80:95], v[216:219], v[124:127], v[80:95]
	v_mfma_f32_32x32x16_bf16 v[64:79], v[220:223], v[124:127], v[64:79]
	s_min_u32 s37, s37, 67
	s_lshl_b32 s44, s37, 6
	s_add_i32 s45, s31, s44
	ds_read_b128 v[216:219], v167 offset:16384
	ds_read_b128 v[220:223], v167 offset:24576
	s_waitcnt lgkmcnt(6)
	v_mfma_f32_32x32x16_bf16 v[80:95], v[192:195], v[120:123], v[80:95]
	v_mfma_f32_32x32x16_bf16 v[64:79], v[196:199], v[120:123], v[64:79]
	s_add_i32 s46, s24, s44
	s_add_i32 s46, s46, 0xffffff00
	s_cmp_lt_u32 s37, 4
	ds_read_b128 v[192:195], v168 offset:8192
	ds_read_b128 v[196:199], v168 offset:12288
	s_waitcnt lgkmcnt(6)
	v_mfma_f32_32x32x16_bf16 v[80:95], v[200:203], v[140:143], v[80:95]
	v_mfma_f32_32x32x16_bf16 v[64:79], v[204:207], v[140:143], v[64:79]
	s_cselect_b32 s37, s45, s46
	s_add_i32 s35, s35, 1
	s_lshl_b32 s44, s36, 12
	ds_read_b128 v[200:203], v169 offset:8192
	ds_read_b128 v[204:207], v169 offset:12288
	s_waitcnt lgkmcnt(6)
	v_mfma_f32_32x32x16_bf16 v[80:95], v[208:211], v[116:119], v[80:95]
	v_mfma_f32_32x32x16_bf16 v[64:79], v[212:215], v[116:119], v[64:79]
	s_add_u32 s50, s47, s44
	s_addc_u32 s51, s63, 0
	s_add_u32 s52, s50, 0x20000
	ds_read_b128 v[208:211], v170 offset:8192
	ds_read_b128 v[212:215], v170 offset:12288
	s_waitcnt lgkmcnt(6)
	v_mfma_f32_32x32x16_bf16 v[80:95], v[216:219], v[112:115], v[80:95]
	v_mfma_f32_32x32x16_bf16 v[64:79], v[220:223], v[112:115], v[64:79]
	s_addc_u32 s53, s51, 0
	s_lshl_b32 s44, s37, 12
	s_add_u32 s54, s47, s44
	ds_read_b128 v[216:219], v171 offset:8192
	ds_read_b128 v[220:223], v171 offset:12288
	s_waitcnt lgkmcnt(6)
	v_mfma_f32_32x32x16_bf16 v[80:95], v[192:195], v[108:111], v[80:95]
	v_mfma_f32_32x32x16_bf16 v[64:79], v[196:199], v[108:111], v[64:79]
	s_addc_u32 s55, s63, 0
	s_add_u32 s56, s54, 0x20000
	s_addc_u32 s57, s55, 0
	ds_read_b64_tr_b16 v[192:193], v174 offset:0
	ds_read_b64_tr_b16 v[194:195], v174 offset:2048
	ds_read_b64_tr_b16 v[196:197], v174 offset:4096
	ds_read_b64_tr_b16 v[198:199], v174 offset:6144
	s_waitcnt lgkmcnt(8)
	v_mfma_f32_32x32x16_bf16 v[80:95], v[200:203], v[104:107], v[80:95]
	v_mfma_f32_32x32x16_bf16 v[64:79], v[204:207], v[104:107], v[64:79]
	s_lshl_b32 s44, s36, 10
	s_add_u32 s58, s60, s44
	s_addc_u32 s59, s61, 0
	ds_read_b64_tr_b16 v[200:201], v174 offset:8192
	ds_read_b64_tr_b16 v[202:203], v174 offset:10240
	ds_read_b64_tr_b16 v[204:205], v174 offset:12288
	ds_read_b64_tr_b16 v[206:207], v174 offset:14336
	s_waitcnt lgkmcnt(10)
	v_mfma_f32_32x32x16_bf16 v[80:95], v[208:211], v[100:103], v[80:95]
	v_mfma_f32_32x32x16_bf16 v[64:79], v[212:215], v[100:103], v[64:79]
	ds_read_b64_tr_b16 v[208:209], v174 offset:512
	ds_read_b64_tr_b16 v[210:211], v174 offset:2560
	ds_read_b64_tr_b16 v[212:213], v174 offset:4608
	ds_read_b64_tr_b16 v[214:215], v174 offset:6656
	s_waitcnt lgkmcnt(12)
	v_mfma_f32_32x32x16_bf16 v[80:95], v[216:219], v[96:99], v[80:95]
	v_mfma_f32_32x32x16_bf16 v[64:79], v[220:223], v[96:99], v[64:79]
	ds_read_b64_tr_b16 v[216:217], v174 offset:8704
	ds_read_b64_tr_b16 v[218:219], v174 offset:10752
	ds_read_b64_tr_b16 v[220:221], v174 offset:12800
	ds_read_b64_tr_b16 v[222:223], v174 offset:14848
	s_waitcnt lgkmcnt(12)
	v_mfma_f32_32x32x16_bf16 v[0:15], v[144:147], v[192:195], v[0:15]
	ds_read_b64_tr_b16 v[192:193], v174 offset:1024
	ds_read_b64_tr_b16 v[194:195], v174 offset:3072
	v_mfma_f32_32x32x16_bf16 v[0:15], v[148:151], v[196:199], v[0:15]
	ds_read_b64_tr_b16 v[196:197], v174 offset:5120
	ds_read_b64_tr_b16 v[198:199], v174 offset:7168
	s_waitcnt lgkmcnt(12)
	v_mfma_f32_32x32x16_bf16 v[0:15], v[152:155], v[200:203], v[0:15]
	ds_read_b64_tr_b16 v[200:201], v174 offset:9216
	ds_read_b64_tr_b16 v[202:203], v174 offset:11264
	v_mfma_f32_32x32x16_bf16 v[0:15], v[156:159], v[204:207], v[0:15]
	ds_read_b64_tr_b16 v[204:205], v174 offset:13312
	ds_read_b64_tr_b16 v[206:207], v174 offset:15360
	s_waitcnt lgkmcnt(12)
	v_mfma_f32_32x32x16_bf16 v[48:63], v[144:147], v[208:211], v[48:63]
	ds_read_b64_tr_b16 v[208:209], v174 offset:1536
	ds_read_b64_tr_b16 v[210:211], v174 offset:3584
	v_mfma_f32_32x32x16_bf16 v[48:63], v[148:151], v[212:215], v[48:63]
	ds_read_b64_tr_b16 v[212:213], v174 offset:5632
	ds_read_b64_tr_b16 v[214:215], v174 offset:7680
	s_waitcnt lgkmcnt(12)
; #define SBAR() __builtin_amdgcn_sched_barrier(0)
; __device__ __forceinline__ void partialSM(f32x16& p0, f32x16& p1, float& m_reg, float& mn, float& alpha) {
;   constexpr float C = SCALE * 1.4426950408889634f;
;   float pmax = p0[0]; for (int r = 1; r < 16; ++r) pmax = fmaxf(pmax, p0[r]); for (int r = 0; r < 16; ++r) pmax = fmaxf(pmax, p1[r]);
;   { auto rr = __builtin_amdgcn_permlane32_swap(__float_as_uint(pmax), __float_as_uint(pmax), false, false);
;     pmax = fmaxf(__uint_as_float(rr[0]), __uint_as_float(rr[1])); }
;   if (__builtin_expect(__all(pmax - m_reg <= THR / SCALE), 1)) { mn = m_reg; alpha = 1.f; }
;   else { mn = fmaxf(m_reg, pmax); alpha = __builtin_amdgcn_exp2f((m_reg - mn) * C); m_reg = mn; }
;   float mnC = -mn * C;
;   for (int r = 0; r < 16; ++r) p0[r] = fmaf(p0[r], C, mnC); for (int r = 0; r < 16; ++r) p1[r] = fmaf(p1[r], C, mnC);
;   for (int r = 0; r < 16; ++r) p0[r] = __builtin_amdgcn_exp2f(p0[r]);
; }
; __device__ __forceinline__ void finishSM(f32x16& p0, f32x16& p1, float alpha, float& l_reg, bf16x8& pa0, bf16x8& pa1, bf16x8& pa2, bf16x8& pa3) {
;   for (int r = 0; r < 16; ++r) p1[r] = __builtin_amdgcn_exp2f(p1[r]);
;   float ps = 0; for (int r = 0; r < 16; ++r) ps += p0[r]; for (int r = 0; r < 16; ++r) ps += p1[r];
;   { auto rr = __builtin_amdgcn_permlane32_swap(__float_as_uint(ps), __float_as_uint(ps), false, false);
;     ps = __uint_as_float(rr[0]) + __uint_as_float(rr[1]); }
;   l_reg = l_reg * alpha + ps;
;     ...
;   PK4(p0, 0, pa0); PK4(p0, 8, pa1); PK4(p1, 0, pa2); PK4(p1, 8, pa3);
;     ...
; }
; template <int D0> __device__ __forceinline__ void pv_one(f32x16& od, int vb, bf16x8 pa0, bf16x8 pa1, bf16x8 pa2, bf16x8 pa3) {
;   const s16x4 l0 = tr_read<v_rd_off(D0, 0, 0)>(vb), h0 = tr_read<v_rd_off(D0, 0, 1)>(vb), l1 = tr_read<v_rd_off(D0, 1, 0)>(vb), h1 = tr_read<v_rd_off(D0, 1, 1)>(vb);
;   const s16x4 l2 = tr_read<v_rd_off(D0, 2, 0)>(vb), h2 = tr_read<v_rd_off(D0, 2, 1)>(vb), l3 = tr_read<v_rd_off(D0, 3, 0)>(vb), h3 = tr_read<v_rd_off(D0, 3, 1)>(vb);
;   asm volatile("s_waitcnt lgkmcnt(0)" ::: "memory"); SBAR();
;     ...
;   od = __builtin_amdgcn_mfma_f32_32x32x16_bf16(pa0, PK(l0, h0), od, 0, 0, 0);
;   od = __builtin_amdgcn_mfma_f32_32x32x16_bf16(pa1, PK(l1, h1), od, 0, 0, 0);
;   od = __builtin_amdgcn_mfma_f32_32x32x16_bf16(pa2, PK(l2, h2), od, 0, 0, 0);
;   od = __builtin_amdgcn_mfma_f32_32x32x16_bf16(pa3, PK(l3, h3), od, 0, 0, 0);
;     ...
; }
	v_mfma_f32_32x32x16_bf16 v[48:63], v[152:155], v[216:219], v[48:63]
	ds_read_b64_tr_b16 v[216:217], v174 offset:9728
	ds_read_b64_tr_b16 v[218:219], v174 offset:11776
	v_mfma_f32_32x32x16_bf16 v[48:63], v[156:159], v[220:223], v[48:63]
	ds_read_b64_tr_b16 v[220:221], v174 offset:13824
	ds_read_b64_tr_b16 v[222:223], v174 offset:15872
	s_waitcnt lgkmcnt(12)
	v_mfma_f32_32x32x16_bf16 v[32:47], v[144:147], v[192:195], v[32:47]
	v_mfma_f32_32x32x16_bf16 v[32:47], v[148:151], v[196:199], v[32:47]
	s_waitcnt lgkmcnt(8)
	v_mfma_f32_32x32x16_bf16 v[32:47], v[152:155], v[200:203], v[32:47]
	v_mfma_f32_32x32x16_bf16 v[32:47], v[156:159], v[204:207], v[32:47]
	s_waitcnt lgkmcnt(4)
	v_mfma_f32_32x32x16_bf16 v[16:31], v[144:147], v[208:211], v[16:31]
	v_mfma_f32_32x32x16_bf16 v[16:31], v[148:151], v[212:215], v[16:31]
	s_waitcnt lgkmcnt(0)
	v_mfma_f32_32x32x16_bf16 v[16:31], v[152:155], v[216:219], v[16:31]
	v_mfma_f32_32x32x16_bf16 v[16:31], v[156:159], v[220:223], v[16:31]
	v_max3_f32 v250, v80, v81, v82
	v_max3_f32 v250, v250, v83, v84
	v_max3_f32 v250, v250, v85, v86
	v_max3_f32 v250, v250, v87, v88
	v_max3_f32 v250, v250, v89, v90
	v_max3_f32 v250, v250, v91, v92
	v_max3_f32 v250, v250, v93, v94
	v_max3_f32 v250, v250, v95, v64
	v_max3_f32 v250, v250, v65, v66
	v_max3_f32 v250, v250, v67, v68
	v_max3_f32 v250, v250, v69, v70
	v_max3_f32 v250, v250, v71, v72
	v_max3_f32 v250, v250, v73, v74
	v_max3_f32 v250, v250, v75, v76
	v_max3_f32 v250, v250, v77, v78
	v_max3_f32 v250, v250, v79, v79
	v_cmp_lt_f32_e64 vcc, s64, |v250|
	s_waitcnt vmcnt(0)
	ds_write_b128 v247, v[232:235]
	ds_write_b128 v247, v[236:239] offset:8192
	ds_write_b128 v183, v[240:243]
	ds_write_b128 v245, v[224:227]
	ds_write_b128 v245, v[228:231] offset:8192
	global_load_dwordx4 v[232:235], v180, s[50:51]
	global_load_dwordx4 v[236:239], v180, s[52:53]
	global_load_dwordx4 v[224:227], v180, s[54:55] offset:256
	global_load_dwordx4 v[228:231], v180, s[56:57] offset:256
	global_load_dwordx4 v[240:243], v181, s[58:59]
	s_cmp_lg_u32 s62, 0
	s_cbranch_scc1 .Lpp_safe_Ab
	s_cbranch_vccnz .Lpp_sw_Ab
	v_exp_f32_e32 v80, v80
	v_exp_f32_e32 v81, v81
	v_exp_f32_e32 v82, v82
	v_exp_f32_e32 v83, v83
	v_exp_f32_e32 v84, v84
	v_exp_f32_e32 v85, v85
	v_exp_f32_e32 v86, v86
	v_exp_f32_e32 v87, v87
	v_exp_f32_e32 v88, v88
	v_exp_f32_e32 v89, v89
	v_exp_f32_e32 v90, v90
	v_exp_f32_e32 v91, v91
	v_exp_f32_e32 v92, v92
	v_exp_f32_e32 v93, v93
	v_exp_f32_e32 v94, v94
	v_exp_f32_e32 v95, v95
	v_exp_f32_e32 v64, v64
	v_exp_f32_e32 v65, v65
	v_exp_f32_e32 v66, v66
	v_exp_f32_e32 v67, v67
	v_exp_f32_e32 v68, v68
	v_exp_f32_e32 v69, v69
	v_exp_f32_e32 v70, v70
	v_exp_f32_e32 v71, v71
	v_exp_f32_e32 v72, v72
	v_exp_f32_e32 v73, v73
	v_exp_f32_e32 v74, v74
	v_exp_f32_e32 v75, v75
	v_exp_f32_e32 v76, v76
	v_exp_f32_e32 v77, v77
	v_exp_f32_e32 v78, v78
	v_exp_f32_e32 v79, v79
	v_add_f32_e32 v249, v80, v81
	v_add_f32_e32 v250, v82, v83
	v_add_f32_e32 v251, v84, v85
	v_add_f32_e32 v182, v86, v87
	v_add_f32_e32 v249, v88, v249
	v_add_f32_e32 v250, v89, v250
	v_add_f32_e32 v251, v90, v251
	v_add_f32_e32 v182, v91, v182
	v_add_f32_e32 v249, v92, v249
	v_add_f32_e32 v250, v93, v250
	v_add_f32_e32 v251, v94, v251
	v_add_f32_e32 v182, v95, v182
	v_add_f32_e32 v249, v64, v249
	v_add_f32_e32 v250, v65, v250
	v_add_f32_e32 v251, v66, v251
	v_add_f32_e32 v182, v67, v182
	v_add_f32_e32 v249, v68, v249
	v_add_f32_e32 v250, v69, v250
	v_add_f32_e32 v251, v70, v251
	v_add_f32_e32 v182, v71, v182
	v_add_f32_e32 v249, v72, v249
	v_add_f32_e32 v250, v73, v250
	v_add_f32_e32 v251, v74, v251
	v_add_f32_e32 v182, v75, v182
	v_add_f32_e32 v249, v76, v249
	v_add_f32_e32 v250, v77, v250
	v_add_f32_e32 v251, v78, v251
	v_add_f32_e32 v182, v79, v182
	v_add_f32_e32 v249, v249, v250
	v_add_f32_e32 v251, v251, v182
	v_add_f32_e32 v249, v249, v251
	v_add_f32_e32 v176, v176, v249
	v_cvt_pk_bf16_f32 v144, v80, v81
	v_cvt_pk_bf16_f32 v145, v82, v83
	v_cvt_pk_bf16_f32 v146, v84, v85
	v_cvt_pk_bf16_f32 v147, v86, v87
	v_cvt_pk_bf16_f32 v148, v88, v89
	v_cvt_pk_bf16_f32 v149, v90, v91
	v_cvt_pk_bf16_f32 v150, v92, v93
	v_cvt_pk_bf16_f32 v151, v94, v95
	v_cvt_pk_bf16_f32 v152, v64, v65
	v_cvt_pk_bf16_f32 v153, v66, v67
	v_cvt_pk_bf16_f32 v154, v68, v69
	v_cvt_pk_bf16_f32 v155, v70, v71
	v_cvt_pk_bf16_f32 v156, v72, v73
	v_cvt_pk_bf16_f32 v157, v74, v75
	v_cvt_pk_bf16_f32 v158, v76, v77
	v_cvt_pk_bf16_f32 v159, v78, v79
; __device__ __forceinline__ void qkt(f32x16& p0, f32x16& p1, const char* Kn, const char* Kp, const bf16x8* qr, int r32, int hi) {
;   p0 = f32x16{}; p1 = f32x16{};
; #pragma unroll
;   for (int d0 = 0; d0 < 8; ++d0) { int cb = (d0 * 16 + hi * 8) * 2;
;     bf16x8 b0 = *reinterpret_cast<const bf16x8*>(Kn + KSWZ(r32, cb));
;     bf16x8 b1 = *reinterpret_cast<const bf16x8*>(Kn + KSWZ(32 + r32, cb));
;     p0 = __builtin_amdgcn_mfma_f32_32x32x16_bf16(b0, qr[d0], p0, 0, 0, 0);
;     p1 = __builtin_amdgcn_mfma_f32_32x32x16_bf16(b1, qr[d0], p1, 0, 0, 0); }
; #pragma unroll
;   for (int d1 = 0; d1 < 4; ++d1) { int cb = (d1 * 16 + hi * 8) * 2;
;     bf16x8 b0 = *reinterpret_cast<const bf16x8*>(Kp + KPSWZ(r32, cb));
;     bf16x8 b1 = *reinterpret_cast<const bf16x8*>(Kp + KPSWZ(32 + r32, cb));
;     p0 = __builtin_amdgcn_mfma_f32_32x32x16_bf16(b0, qr[8 + d1], p0, 0, 0, 0);
;     p1 = __builtin_amdgcn_mfma_f32_32x32x16_bf16(b1, qr[8 + d1], p1, 0, 0, 0); }
; }
; __device__ __forceinline__ int v_st(int k, int c) { const int kk = (k & ~0xC) | ((k & 4) << 1) | ((k & 8) >> 1); return ((kk >> 3) * 4 + (c >> 5)) * 512 + ((kk & 7) * 32 + (c & 31)) * 2; }
; __device__ __forceinline__ int v_rd_base(int lane) { return ((lane & 3) << 3) | (((lane >> 2) & 3) << 6) | (((lane >> 4) & 1) << 5) | (((lane >> 5) & 1) << 8); }
; template <int OFF> __device__ __forceinline__ s16x4 tr_read(int vb) {
;   s16x4 r; asm volatile("ds_read_b64_tr_b16 %0, %1 offset:%2" : "=&v"(r) : "v"(vb), "i"(OFF) : "memory"); return r;
; }
; template <int D0> __device__ __forceinline__ void pv_one(f32x16& od, int vb, bf16x8 pa0, bf16x8 pa1, bf16x8 pa2, bf16x8 pa3) {
;   const s16x4 l0 = tr_read<v_rd_off(D0, 0, 0)>(vb), h0 = tr_read<v_rd_off(D0, 0, 1)>(vb), l1 = tr_read<v_rd_off(D0, 1, 0)>(vb), h1 = tr_read<v_rd_off(D0, 1, 1)>(vb);
;   const s16x4 l2 = tr_read<v_rd_off(D0, 2, 0)>(vb), h2 = tr_read<v_rd_off(D0, 2, 1)>(vb), l3 = tr_read<v_rd_off(D0, 3, 0)>(vb), h3 = tr_read<v_rd_off(D0, 3, 1)>(vb);
;   asm volatile("s_waitcnt lgkmcnt(0)" ::: "memory"); SBAR();
;     ...
;   od = __builtin_amdgcn_mfma_f32_32x32x16_bf16(pa0, PK(l0, h0), od, 0, 0, 0);
;   od = __builtin_amdgcn_mfma_f32_32x32x16_bf16(pa1, PK(l1, h1), od, 0, 0, 0);
;   od = __builtin_amdgcn_mfma_f32_32x32x16_bf16(pa2, PK(l2, h2), od, 0, 0, 0);
;   od = __builtin_amdgcn_mfma_f32_32x32x16_bf16(pa3, PK(l3, h3), od, 0, 0, 0);
;     ...
; }
.Lpp_send_Ab:
	s_waitcnt lgkmcnt(0)
	s_barrier
	s_add_i32 s11, s11, 1
	s_cmp_eq_u32 s11, 68
	s_cbranch_scc1 .Lpp_alast
	ds_read_b128 v[192:195], v160
	ds_read_b128 v[196:199], v160 offset:8192
	ds_read_b128 v[200:203], v161
	ds_read_b128 v[204:207], v161 offset:8192
	ds_read_b128 v[208:211], v162
	ds_read_b128 v[212:215], v162 offset:8192
	ds_read_b128 v[216:219], v163
	ds_read_b128 v[220:223], v163 offset:8192
	s_waitcnt lgkmcnt(6)
	v_mfma_f32_32x32x16_bf16 v[80:95], v[192:195], v[136:139], 0
	v_mfma_f32_32x32x16_bf16 v[64:79], v[196:199], v[136:139], 0
	s_add_i32 s36, s35, 2
	s_min_u32 s36, s36, 67
	s_lshl_b32 s44, s36, 6
	ds_read_b128 v[192:195], v164
	ds_read_b128 v[196:199], v164 offset:8192
	s_waitcnt lgkmcnt(6)
	v_mfma_f32_32x32x16_bf16 v[80:95], v[200:203], v[132:135], v[80:95]
	v_mfma_f32_32x32x16_bf16 v[64:79], v[204:207], v[132:135], v[64:79]
	s_add_i32 s45, s31, s44
	s_add_i32 s46, s24, s44
	s_add_i32 s46, s46, 0xffffff00
	ds_read_b128 v[200:203], v165
	ds_read_b128 v[204:207], v165 offset:8192
	s_waitcnt lgkmcnt(6)
	v_mfma_f32_32x32x16_bf16 v[80:95], v[208:211], v[128:131], v[80:95]
	v_mfma_f32_32x32x16_bf16 v[64:79], v[212:215], v[128:131], v[64:79]
	s_cmp_lt_u32 s36, 4
	s_cselect_b32 s36, s45, s46
	s_add_i32 s37, s35, 1
	ds_read_b128 v[208:211], v166
	ds_read_b128 v[212:215], v166 offset:8192
	s_waitcnt lgkmcnt(6)
	v_mfma_f32_32x32x16_bf16 v[80:95], v[216:219], v[124:127], v[80:95]
	v_mfma_f32_32x32x16_bf16 v[64:79], v[220:223], v[124:127], v[64:79]
	s_min_u32 s37, s37, 67
	s_lshl_b32 s44, s37, 6
	s_add_i32 s45, s31, s44
	ds_read_b128 v[216:219], v167
	ds_read_b128 v[220:223], v167 offset:8192
	s_waitcnt lgkmcnt(6)
	v_mfma_f32_32x32x16_bf16 v[80:95], v[192:195], v[120:123], v[80:95]
	v_mfma_f32_32x32x16_bf16 v[64:79], v[196:199], v[120:123], v[64:79]
	s_add_i32 s46, s24, s44
	s_add_i32 s46, s46, 0xffffff00
	s_cmp_lt_u32 s37, 4
	ds_read_b128 v[192:195], v168
	ds_read_b128 v[196:199], v168 offset:4096
	s_waitcnt lgkmcnt(6)
	v_mfma_f32_32x32x16_bf16 v[80:95], v[200:203], v[140:143], v[80:95]
	v_mfma_f32_32x32x16_bf16 v[64:79], v[204:207], v[140:143], v[64:79]
	s_cselect_b32 s37, s45, s46
	s_add_i32 s35, s35, 1
	s_lshl_b32 s44, s36, 12
	ds_read_b128 v[200:203], v169
	ds_read_b128 v[204:207], v169 offset:4096
	s_waitcnt lgkmcnt(6)
	v_mfma_f32_32x32x16_bf16 v[80:95], v[208:211], v[116:119], v[80:95]
	v_mfma_f32_32x32x16_bf16 v[64:79], v[212:215], v[116:119], v[64:79]
	s_add_u32 s50, s47, s44
	s_addc_u32 s51, s63, 0
	s_add_u32 s52, s50, 0x20000
	ds_read_b128 v[208:211], v170
	ds_read_b128 v[212:215], v170 offset:4096
	s_waitcnt lgkmcnt(6)
	v_mfma_f32_32x32x16_bf16 v[80:95], v[216:219], v[112:115], v[80:95]
	v_mfma_f32_32x32x16_bf16 v[64:79], v[220:223], v[112:115], v[64:79]
	s_addc_u32 s53, s51, 0
	s_lshl_b32 s44, s37, 12
	s_add_u32 s54, s47, s44
	ds_read_b128 v[216:219], v171
	ds_read_b128 v[220:223], v171 offset:4096
	s_waitcnt lgkmcnt(6)
	v_mfma_f32_32x32x16_bf16 v[80:95], v[192:195], v[108:111], v[80:95]
	v_mfma_f32_32x32x16_bf16 v[64:79], v[196:199], v[108:111], v[64:79]
	s_addc_u32 s55, s63, 0
	s_add_u32 s56, s54, 0x20000
	s_addc_u32 s57, s55, 0
	ds_read_b64_tr_b16 v[192:193], v174 offset:16384
	ds_read_b64_tr_b16 v[194:195], v174 offset:18432
	ds_read_b64_tr_b16 v[196:197], v174 offset:20480
	ds_read_b64_tr_b16 v[198:199], v174 offset:22528
	s_waitcnt lgkmcnt(8)
	v_mfma_f32_32x32x16_bf16 v[80:95], v[200:203], v[104:107], v[80:95]
	v_mfma_f32_32x32x16_bf16 v[64:79], v[204:207], v[104:107], v[64:79]
	s_lshl_b32 s44, s36, 10
	s_add_u32 s58, s60, s44
	s_addc_u32 s59, s61, 0
	ds_read_b64_tr_b16 v[200:201], v174 offset:24576
	ds_read_b64_tr_b16 v[202:203], v174 offset:26624
	ds_read_b64_tr_b16 v[204:205], v174 offset:28672
	ds_read_b64_tr_b16 v[206:207], v174 offset:30720
	s_waitcnt lgkmcnt(10)
	v_mfma_f32_32x32x16_bf16 v[80:95], v[208:211], v[100:103], v[80:95]
	v_mfma_f32_32x32x16_bf16 v[64:79], v[212:215], v[100:103], v[64:79]
	ds_read_b64_tr_b16 v[208:209], v174 offset:16896
	ds_read_b64_tr_b16 v[210:211], v174 offset:18944
	ds_read_b64_tr_b16 v[212:213], v174 offset:20992
	ds_read_b64_tr_b16 v[214:215], v174 offset:23040
	s_waitcnt lgkmcnt(12)
	v_mfma_f32_32x32x16_bf16 v[80:95], v[216:219], v[96:99], v[80:95]
	v_mfma_f32_32x32x16_bf16 v[64:79], v[220:223], v[96:99], v[64:79]
	ds_read_b64_tr_b16 v[216:217], v174 offset:25088
	ds_read_b64_tr_b16 v[218:219], v174 offset:27136
	ds_read_b64_tr_b16 v[220:221], v174 offset:29184
	ds_read_b64_tr_b16 v[222:223], v174 offset:31232
	s_waitcnt lgkmcnt(12)
	v_mfma_f32_32x32x16_bf16 v[0:15], v[144:147], v[192:195], v[0:15]
	ds_read_b64_tr_b16 v[192:193], v174 offset:17408
	ds_read_b64_tr_b16 v[194:195], v174 offset:19456
	v_mfma_f32_32x32x16_bf16 v[0:15], v[148:151], v[196:199], v[0:15]
	ds_read_b64_tr_b16 v[196:197], v174 offset:21504
	ds_read_b64_tr_b16 v[198:199], v174 offset:23552
	s_waitcnt lgkmcnt(12)
	v_mfma_f32_32x32x16_bf16 v[0:15], v[152:155], v[200:203], v[0:15]
	ds_read_b64_tr_b16 v[200:201], v174 offset:25600
	ds_read_b64_tr_b16 v[202:203], v174 offset:27648
	v_mfma_f32_32x32x16_bf16 v[0:15], v[156:159], v[204:207], v[0:15]
	ds_read_b64_tr_b16 v[204:205], v174 offset:29696
	ds_read_b64_tr_b16 v[206:207], v174 offset:31744
	s_waitcnt lgkmcnt(12)
	v_mfma_f32_32x32x16_bf16 v[48:63], v[144:147], v[208:211], v[48:63]
	ds_read_b64_tr_b16 v[208:209], v174 offset:17920
	ds_read_b64_tr_b16 v[210:211], v174 offset:19968
	v_mfma_f32_32x32x16_bf16 v[48:63], v[148:151], v[212:215], v[48:63]
	ds_read_b64_tr_b16 v[212:213], v174 offset:22016
	ds_read_b64_tr_b16 v[214:215], v174 offset:24064
	s_waitcnt lgkmcnt(12)
	v_mfma_f32_32x32x16_bf16 v[48:63], v[152:155], v[216:219], v[48:63]
	ds_read_b64_tr_b16 v[216:217], v174 offset:26112
	ds_read_b64_tr_b16 v[218:219], v174 offset:28160
	v_mfma_f32_32x32x16_bf16 v[48:63], v[156:159], v[220:223], v[48:63]
	ds_read_b64_tr_b16 v[220:221], v174 offset:30208
	ds_read_b64_tr_b16 v[222:223], v174 offset:32256
	s_waitcnt lgkmcnt(12)
	v_mfma_f32_32x32x16_bf16 v[32:47], v[144:147], v[192:195], v[32:47]
	v_mfma_f32_32x32x16_bf16 v[32:47], v[148:151], v[196:199], v[32:47]
	s_waitcnt lgkmcnt(8)
	v_mfma_f32_32x32x16_bf16 v[32:47], v[152:155], v[200:203], v[32:47]
	v_mfma_f32_32x32x16_bf16 v[32:47], v[156:159], v[204:207], v[32:47]
	s_waitcnt lgkmcnt(4)
	v_mfma_f32_32x32x16_bf16 v[16:31], v[144:147], v[208:211], v[16:31]
	v_mfma_f32_32x32x16_bf16 v[16:31], v[148:151], v[212:215], v[16:31]
	s_waitcnt lgkmcnt(0)
	v_mfma_f32_32x32x16_bf16 v[16:31], v[152:155], v[216:219], v[16:31]
	v_mfma_f32_32x32x16_bf16 v[16:31], v[156:159], v[220:223], v[16:31]
	s_branch .Lpp_aloop

; #define SBAR() __builtin_amdgcn_sched_barrier(0)
; #define RESC(a) do { if (__any((a) < 1.f)) { if (hi == 0) al_l[r32] = (a); asm volatile("s_waitcnt lgkmcnt(0)" ::: "memory"); \
;     for (int d = 0; d < 4; ++d) for (int r = 0; r < 16; ++r) o[d][r] *= al_l[crow(r, hi)]; } } while (0)
; __device__ __forceinline__ void attn_unit(const bf16_t* __restrict__ Qb, const bf16_t* __restrict__ KV, const bf16_t* __restrict__ KP, bf16_t* __restrict__ Ob, ...
;     ...
;   SBAR(); qkt(pB0, pB1, KN_lds + SHM_KN, KP_lds + SHM_KP, qr, r32, hi);
;   finishSM(pA0, pA1, alA, l_reg, pa0, pa1, pa2, pa3); SBAR();
;   pv_d0(o, vb0, pa0, pa1, pa2, pa3); partialSM(pB0, pB1, m_reg, mnB, alB);
;   __syncthreads(); RESC(alB);
;   finishSM(pB0, pB1, alB, l_reg, pa0, pa1, pa2, pa3); SBAR();
;   pv_d0(o, vb0 + SHM_V, pa0, pa1, pa2, pa3);
;   if (hi == 0) li_l[r32] = l_reg; asm volatile("s_waitcnt lgkmcnt(0)" ::: "memory");
.Lpp_fin:
	s_waitcnt vmcnt(0)
	s_cmp_lg_u32 s62, 0
	s_cbranch_scc1 .Lpp_lok
	v_mov_b32_e32 v249, v176
	s_nop 1
	v_permlane32_swap_b32_e32 v176, v249
	v_add_f32_e32 v176, v176, v249

; __device__ __forceinline__ void partialSM(f32x16& p0, f32x16& p1, float& m_reg, float& mn, float& alpha) {
;   constexpr float C = SCALE * 1.4426950408889634f;
;   float pmax = p0[0]; for (int r = 1; r < 16; ++r) pmax = fmaxf(pmax, p0[r]); for (int r = 0; r < 16; ++r) pmax = fmaxf(pmax, p1[r]);
;   { auto rr = __builtin_amdgcn_permlane32_swap(__float_as_uint(pmax), __float_as_uint(pmax), false, false);
;     pmax = fmaxf(__uint_as_float(rr[0]), __uint_as_float(rr[1])); }
;   if (__builtin_expect(__all(pmax - m_reg <= THR / SCALE), 1)) { mn = m_reg; alpha = 1.f; }
;   else { mn = fmaxf(m_reg, pmax); alpha = __builtin_amdgcn_exp2f((m_reg - mn) * C); m_reg = mn; }
;   float mnC = -mn * C;
;   for (int r = 0; r < 16; ++r) p0[r] = fmaf(p0[r], C, mnC); for (int r = 0; r < 16; ++r) p1[r] = fmaf(p1[r], C, mnC);
;   for (int r = 0; r < 16; ++r) p0[r] = __builtin_amdgcn_exp2f(p0[r]);
; }
; __device__ __forceinline__ void finishSM(f32x16& p0, f32x16& p1, float alpha, float& l_reg, bf16x8& pa0, bf16x8& pa1, bf16x8& pa2, bf16x8& pa3) {
;   for (int r = 0; r < 16; ++r) p1[r] = __builtin_amdgcn_exp2f(p1[r]);
;   float ps = 0; for (int r = 0; r < 16; ++r) ps += p0[r]; for (int r = 0; r < 16; ++r) ps += p1[r];
;   { auto rr = __builtin_amdgcn_permlane32_swap(__float_as_uint(ps), __float_as_uint(ps), false, false);
;     ps = __uint_as_float(rr[0]) + __uint_as_float(rr[1]); }
;   l_reg = l_reg * alpha + ps;
;     ...
;   PK4(p0, 0, pa0); PK4(p0, 8, pa1); PK4(p1, 0, pa2); PK4(p1, 8, pa3);
;     ...
; }
.Lpp_sw_Ba:
	v_mov_b32_e32 v249, v176
	s_nop 1
	v_permlane32_swap_b32_e32 v176, v249
	v_add_f32_e32 v176, v176, v249
	v_cmp_eq_f32_e32 vcc, 0, v176
	v_mov_b32_e32 v251, 0xf149f2ca
	s_nop 1
	v_cndmask_b32_e32 v175, v175, v251, vcc
	s_mov_b32 s62, 1
.Lpp_safe_Ba:
	v_mov_b32_e32 v251, v250
	s_nop 1
	v_permlane32_swap_b32_e32 v250, v251
	v_max_f32_e32 v250, v250, v251
	v_sub_f32_e32 v251, v250, v175
	v_cmp_ge_f32_e32 vcc, 0x4138aa3b, v251
	v_max_f32_e32 v249, v175, v250
	v_sub_f32_e32 v251, v175, v249
	v_exp_f32_e32 v251, v251
	s_nop 1
	s_cmp_eq_u64 vcc, exec
	s_cselect_b64 s[8:9], -1, 0
	v_cndmask_b32_e64 v177, v251, 1.0, s[8:9]
	v_cndmask_b32_e64 v175, v249, v175, s[8:9]
	v_cmp_gt_f32_e32 vcc, 1.0, v177
	s_nop 4
	s_cbranch_vccz .Lpp_nr_Ba
	s_and_saveexec_b64 s[42:43], s[6:7]
	ds_write_b32 v186, v177 offset:128
	s_or_b64 exec, exec, s[42:43]
	s_waitcnt lgkmcnt(0)
	v_add_u32_e32 v187, v179, v172
	ds_read_b128 v[192:195], v187 offset:128
	ds_read_b128 v[196:199], v187 offset:160
	ds_read_b128 v[200:203], v187 offset:192
	ds_read_b128 v[204:207], v187 offset:224
	s_waitcnt lgkmcnt(0)
	v_pk_mul_f32 v[0:1], v[0:1], v[192:193]
	v_pk_mul_f32 v[2:3], v[2:3], v[194:195]
	v_pk_mul_f32 v[4:5], v[4:5], v[196:197]
	v_pk_mul_f32 v[6:7], v[6:7], v[198:199]
	v_pk_mul_f32 v[8:9], v[8:9], v[200:201]
	v_pk_mul_f32 v[10:11], v[10:11], v[202:203]
	v_pk_mul_f32 v[12:13], v[12:13], v[204:205]
	v_pk_mul_f32 v[14:15], v[14:15], v[206:207]
	v_pk_mul_f32 v[48:49], v[48:49], v[192:193]
	v_pk_mul_f32 v[50:51], v[50:51], v[194:195]
	v_pk_mul_f32 v[52:53], v[52:53], v[196:197]
	v_pk_mul_f32 v[54:55], v[54:55], v[198:199]
	v_pk_mul_f32 v[56:57], v[56:57], v[200:201]
	v_pk_mul_f32 v[58:59], v[58:59], v[202:203]
	v_pk_mul_f32 v[60:61], v[60:61], v[204:205]
	v_pk_mul_f32 v[62:63], v[62:63], v[206:207]
	v_pk_mul_f32 v[32:33], v[32:33], v[192:193]
	v_pk_mul_f32 v[34:35], v[34:35], v[194:195]
	v_pk_mul_f32 v[36:37], v[36:37], v[196:197]
	v_pk_mul_f32 v[38:39], v[38:39], v[198:199]
	v_pk_mul_f32 v[40:41], v[40:41], v[200:201]
	v_pk_mul_f32 v[42:43], v[42:43], v[202:203]
	v_pk_mul_f32 v[44:45], v[44:45], v[204:205]
	v_pk_mul_f32 v[46:47], v[46:47], v[206:207]
	v_pk_mul_f32 v[16:17], v[16:17], v[192:193]
	v_pk_mul_f32 v[18:19], v[18:19], v[194:195]
	v_pk_mul_f32 v[20:21], v[20:21], v[196:197]
	v_pk_mul_f32 v[22:23], v[22:23], v[198:199]
	v_pk_mul_f32 v[24:25], v[24:25], v[200:201]
	v_pk_mul_f32 v[26:27], v[26:27], v[202:203]
	v_pk_mul_f32 v[28:29], v[28:29], v[204:205]
	v_pk_mul_f32 v[30:31], v[30:31], v[206:207]
.Lpp_nr_Ba:
	v_sub_f32_e32 v80, v80, v175
	v_sub_f32_e32 v81, v81, v175
	v_sub_f32_e32 v82, v82, v175
	v_sub_f32_e32 v83, v83, v175
	v_sub_f32_e32 v84, v84, v175
	v_sub_f32_e32 v85, v85, v175
	v_sub_f32_e32 v86, v86, v175
	v_sub_f32_e32 v87, v87, v175
	v_sub_f32_e32 v88, v88, v175
	v_sub_f32_e32 v89, v89, v175
	v_sub_f32_e32 v90, v90, v175
	v_sub_f32_e32 v91, v91, v175
	v_sub_f32_e32 v92, v92, v175
	v_sub_f32_e32 v93, v93, v175
	v_sub_f32_e32 v94, v94, v175
	v_sub_f32_e32 v95, v95, v175
	v_sub_f32_e32 v64, v64, v175
	v_sub_f32_e32 v65, v65, v175
	v_sub_f32_e32 v66, v66, v175
	v_sub_f32_e32 v67, v67, v175
	v_sub_f32_e32 v68, v68, v175
	v_sub_f32_e32 v69, v69, v175
	v_sub_f32_e32 v70, v70, v175
	v_sub_f32_e32 v71, v71, v175
	v_sub_f32_e32 v72, v72, v175
	v_sub_f32_e32 v73, v73, v175
	v_sub_f32_e32 v74, v74, v175
	v_sub_f32_e32 v75, v75, v175
	v_sub_f32_e32 v76, v76, v175
	v_sub_f32_e32 v77, v77, v175
	v_sub_f32_e32 v78, v78, v175
	v_sub_f32_e32 v79, v79, v175
	v_exp_f32_e32 v80, v80
	v_exp_f32_e32 v81, v81
	v_exp_f32_e32 v82, v82
	v_exp_f32_e32 v83, v83
	v_exp_f32_e32 v84, v84
	v_exp_f32_e32 v85, v85
	v_exp_f32_e32 v86, v86
	v_exp_f32_e32 v87, v87
	v_exp_f32_e32 v88, v88
	v_exp_f32_e32 v89, v89
	v_exp_f32_e32 v90, v90
	v_exp_f32_e32 v91, v91
	v_exp_f32_e32 v92, v92
	v_exp_f32_e32 v93, v93
	v_exp_f32_e32 v94, v94
	v_exp_f32_e32 v95, v95
	v_exp_f32_e32 v64, v64
	v_exp_f32_e32 v65, v65
	v_exp_f32_e32 v66, v66
	v_exp_f32_e32 v67, v67
	v_exp_f32_e32 v68, v68
	v_exp_f32_e32 v69, v69
	v_exp_f32_e32 v70, v70
	v_exp_f32_e32 v71, v71
	v_exp_f32_e32 v72, v72
	v_exp_f32_e32 v73, v73
	v_exp_f32_e32 v74, v74
	v_exp_f32_e32 v75, v75
	v_exp_f32_e32 v76, v76
	v_exp_f32_e32 v77, v77
	v_exp_f32_e32 v78, v78
	v_exp_f32_e32 v79, v79
	s_nop 0
	v_add_f32_e32 v249, v80, v81
	v_add_f32_e32 v249, v82, v249
	v_add_f32_e32 v249, v83, v249
	v_add_f32_e32 v249, v84, v249
	v_add_f32_e32 v249, v85, v249
	v_add_f32_e32 v249, v86, v249
	v_add_f32_e32 v249, v87, v249
	v_add_f32_e32 v249, v88, v249
	v_add_f32_e32 v249, v89, v249
	v_add_f32_e32 v249, v90, v249
	v_add_f32_e32 v249, v91, v249
	v_add_f32_e32 v249, v92, v249
	v_add_f32_e32 v249, v93, v249
	v_add_f32_e32 v249, v94, v249
	v_add_f32_e32 v249, v95, v249
	v_add_f32_e32 v249, v64, v249
	v_add_f32_e32 v249, v65, v249
	v_add_f32_e32 v249, v66, v249
	v_add_f32_e32 v249, v67, v249
	v_add_f32_e32 v249, v68, v249
	v_add_f32_e32 v249, v69, v249
	v_add_f32_e32 v249, v70, v249
	v_add_f32_e32 v249, v71, v249
	v_add_f32_e32 v249, v72, v249
	v_add_f32_e32 v249, v73, v249
	v_add_f32_e32 v249, v74, v249
	v_add_f32_e32 v249, v75, v249
	v_add_f32_e32 v249, v76, v249
	v_add_f32_e32 v249, v77, v249
	v_add_f32_e32 v249, v78, v249
	v_add_f32_e32 v249, v79, v249
	v_mov_b32_e32 v250, v249
	s_nop 1
	v_permlane32_swap_b32_e32 v249, v250
	v_add_f32_e32 v249, v249, v250
	v_fma_f32 v176, v176, v177, v249
	v_cvt_pk_bf16_f32 v144, v80, v81
	v_cvt_pk_bf16_f32 v145, v82, v83
	v_cvt_pk_bf16_f32 v146, v84, v85
	v_cvt_pk_bf16_f32 v147, v86, v87
	v_cvt_pk_bf16_f32 v148, v88, v89
	v_cvt_pk_bf16_f32 v149, v90, v91
	v_cvt_pk_bf16_f32 v150, v92, v93
	v_cvt_pk_bf16_f32 v151, v94, v95
	v_cvt_pk_bf16_f32 v152, v64, v65
	v_cvt_pk_bf16_f32 v153, v66, v67
	v_cvt_pk_bf16_f32 v154, v68, v69
	v_cvt_pk_bf16_f32 v155, v70, v71
	v_cvt_pk_bf16_f32 v156, v72, v73
	v_cvt_pk_bf16_f32 v157, v74, v75
	v_cvt_pk_bf16_f32 v158, v76, v77
	v_cvt_pk_bf16_f32 v159, v78, v79
	s_branch .Lpp_send_Ba

; __device__ __forceinline__ void partialSM(f32x16& p0, f32x16& p1, float& m_reg, float& mn, float& alpha) {
;   constexpr float C = SCALE * 1.4426950408889634f;
;   float pmax = p0[0]; for (int r = 1; r < 16; ++r) pmax = fmaxf(pmax, p0[r]); for (int r = 0; r < 16; ++r) pmax = fmaxf(pmax, p1[r]);
;   { auto rr = __builtin_amdgcn_permlane32_swap(__float_as_uint(pmax), __float_as_uint(pmax), false, false);
;     pmax = fmaxf(__uint_as_float(rr[0]), __uint_as_float(rr[1])); }
;   if (__builtin_expect(__all(pmax - m_reg <= THR / SCALE), 1)) { mn = m_reg; alpha = 1.f; }
;   else { mn = fmaxf(m_reg, pmax); alpha = __builtin_amdgcn_exp2f((m_reg - mn) * C); m_reg = mn; }
;   float mnC = -mn * C;
;   for (int r = 0; r < 16; ++r) p0[r] = fmaf(p0[r], C, mnC); for (int r = 0; r < 16; ++r) p1[r] = fmaf(p1[r], C, mnC);
;   for (int r = 0; r < 16; ++r) p0[r] = __builtin_amdgcn_exp2f(p0[r]);
; }
; __device__ __forceinline__ void finishSM(f32x16& p0, f32x16& p1, float alpha, float& l_reg, bf16x8& pa0, bf16x8& pa1, bf16x8& pa2, bf16x8& pa3) {
;   for (int r = 0; r < 16; ++r) p1[r] = __builtin_amdgcn_exp2f(p1[r]);
;   float ps = 0; for (int r = 0; r < 16; ++r) ps += p0[r]; for (int r = 0; r < 16; ++r) ps += p1[r];
;   { auto rr = __builtin_amdgcn_permlane32_swap(__float_as_uint(ps), __float_as_uint(ps), false, false);
;     ps = __uint_as_float(rr[0]) + __uint_as_float(rr[1]); }
;   l_reg = l_reg * alpha + ps;
;     ...
;   PK4(p0, 0, pa0); PK4(p0, 8, pa1); PK4(p1, 0, pa2); PK4(p1, 8, pa3);
;     ...
; }
.Lpp_nr_Ab:
	v_sub_f32_e32 v80, v80, v175
	v_sub_f32_e32 v81, v81, v175
	v_sub_f32_e32 v82, v82, v175
	v_sub_f32_e32 v83, v83, v175
	v_sub_f32_e32 v84, v84, v175
	v_sub_f32_e32 v85, v85, v175
	v_sub_f32_e32 v86, v86, v175
	v_sub_f32_e32 v87, v87, v175
	v_sub_f32_e32 v88, v88, v175
	v_sub_f32_e32 v89, v89, v175
	v_sub_f32_e32 v90, v90, v175
	v_sub_f32_e32 v91, v91, v175
	v_sub_f32_e32 v92, v92, v175
	v_sub_f32_e32 v93, v93, v175
	v_sub_f32_e32 v94, v94, v175
	v_sub_f32_e32 v95, v95, v175
	v_sub_f32_e32 v64, v64, v175
	v_sub_f32_e32 v65, v65, v175
	v_sub_f32_e32 v66, v66, v175
	v_sub_f32_e32 v67, v67, v175
	v_sub_f32_e32 v68, v68, v175
	v_sub_f32_e32 v69, v69, v175
	v_sub_f32_e32 v70, v70, v175
	v_sub_f32_e32 v71, v71, v175
	v_sub_f32_e32 v72, v72, v175
	v_sub_f32_e32 v73, v73, v175
	v_sub_f32_e32 v74, v74, v175
	v_sub_f32_e32 v75, v75, v175
	v_sub_f32_e32 v76, v76, v175
	v_sub_f32_e32 v77, v77, v175
	v_sub_f32_e32 v78, v78, v175
	v_sub_f32_e32 v79, v79, v175
	v_exp_f32_e32 v80, v80
	v_exp_f32_e32 v81, v81
	v_exp_f32_e32 v82, v82
	v_exp_f32_e32 v83, v83
	v_exp_f32_e32 v84, v84
	v_exp_f32_e32 v85, v85
	v_exp_f32_e32 v86, v86
	v_exp_f32_e32 v87, v87
	v_exp_f32_e32 v88, v88
	v_exp_f32_e32 v89, v89
	v_exp_f32_e32 v90, v90
	v_exp_f32_e32 v91, v91
	v_exp_f32_e32 v92, v92
	v_exp_f32_e32 v93, v93
	v_exp_f32_e32 v94, v94
	v_exp_f32_e32 v95, v95
	v_exp_f32_e32 v64, v64
	v_exp_f32_e32 v65, v65
	v_exp_f32_e32 v66, v66
	v_exp_f32_e32 v67, v67
	v_exp_f32_e32 v68, v68
	v_exp_f32_e32 v69, v69
	v_exp_f32_e32 v70, v70
	v_exp_f32_e32 v71, v71
	v_exp_f32_e32 v72, v72
	v_exp_f32_e32 v73, v73
	v_exp_f32_e32 v74, v74
	v_exp_f32_e32 v75, v75
	v_exp_f32_e32 v76, v76
	v_exp_f32_e32 v77, v77
	v_exp_f32_e32 v78, v78
	v_exp_f32_e32 v79, v79
	s_nop 0
	v_add_f32_e32 v249, v80, v81
	v_add_f32_e32 v249, v82, v249
	v_add_f32_e32 v249, v83, v249
	v_add_f32_e32 v249, v84, v249
	v_add_f32_e32 v249, v85, v249
	v_add_f32_e32 v249, v86, v249
	v_add_f32_e32 v249, v87, v249
	v_add_f32_e32 v249, v88, v249
	v_add_f32_e32 v249, v89, v249
	v_add_f32_e32 v249, v90, v249
	v_add_f32_e32 v249, v91, v249
	v_add_f32_e32 v249, v92, v249
	v_add_f32_e32 v249, v93, v249
	v_add_f32_e32 v249, v94, v249
	v_add_f32_e32 v249, v95, v249
	v_add_f32_e32 v249, v64, v249
	v_add_f32_e32 v249, v65, v249
	v_add_f32_e32 v249, v66, v249
	v_add_f32_e32 v249, v67, v249
	v_add_f32_e32 v249, v68, v249
	v_add_f32_e32 v249, v69, v249
	v_add_f32_e32 v249, v70, v249
	v_add_f32_e32 v249, v71, v249
	v_add_f32_e32 v249, v72, v249
	v_add_f32_e32 v249, v73, v249
	v_add_f32_e32 v249, v74, v249
	v_add_f32_e32 v249, v75, v249
	v_add_f32_e32 v249, v76, v249
	v_add_f32_e32 v249, v77, v249
	v_add_f32_e32 v249, v78, v249
	v_add_f32_e32 v249, v79, v249
	v_mov_b32_e32 v250, v249
	s_nop 1
	v_permlane32_swap_b32_e32 v249, v250
	v_add_f32_e32 v249, v249, v250
	v_fma_f32 v176, v176, v177, v249
	v_cvt_pk_bf16_f32 v144, v80, v81
	v_cvt_pk_bf16_f32 v145, v82, v83
	v_cvt_pk_bf16_f32 v146, v84, v85
	v_cvt_pk_bf16_f32 v147, v86, v87
	v_cvt_pk_bf16_f32 v148, v88, v89
	v_cvt_pk_bf16_f32 v149, v90, v91
	v_cvt_pk_bf16_f32 v150, v92, v93
	v_cvt_pk_bf16_f32 v151, v94, v95
	v_cvt_pk_bf16_f32 v152, v64, v65
	v_cvt_pk_bf16_f32 v153, v66, v67
	v_cvt_pk_bf16_f32 v154, v68, v69
	v_cvt_pk_bf16_f32 v155, v70, v71
	v_cvt_pk_bf16_f32 v156, v72, v73
	v_cvt_pk_bf16_f32 v157, v74, v75
	v_cvt_pk_bf16_f32 v158, v76, v77
	v_cvt_pk_bf16_f32 v159, v78, v79
	s_branch .Lpp_send_Ab
	s_nop 0
	s_nop 0
	s_nop 0
	s_nop 0
	s_nop 0
	s_nop 0
	s_nop 0
	s_nop 0
	s_nop 0
	s_nop 0
	s_nop 0
	s_nop 0
	s_nop 0
	s_nop 0
	s_nop 0
